# 88 flat_load/flat_store to global memory rewritten as global_load/global_store (no lgkmcnt coupling), on top of v77
# baseline (speedup 1.0000x reference)
.LBB0_65:
	s_or_b64 exec, exec, s[8:9]
	s_bitcmp1_b32 s14, 3
	v_readlane_b32 s2, v255, 29
	s_cselect_b32 s44, s66, s2
	v_and_b32_e32 v3, 0xff, v0
	v_readlane_b32 s2, v255, 13
	v_readlane_b32 s3, v255, 30
	s_cselect_b32 s45, s67, s3
	v_lshl_add_u32 v1, v3, 2, s2
	v_cmp_lt_i32_e32 vcc, -1, v4
	v_lshl_add_u32 v1, v2, 10, v1
	s_and_saveexec_b64 s[6:7], vcc
	s_cbranch_execz .LBB0_67
	v_lshl_or_b32 v140, v4, 8, v3
	v_lshlrev_b64 v[4:5], 6, v[140:141]
	v_lshl_add_u64 v[16:17], s[44:45], 0, v[4:5]
	global_load_dwordx4 v[4:7], v[16:17], off
	global_load_dwordx4 v[8:11], v[16:17], off offset:32
	global_load_dwordx4 v[12:15], v[16:17], off offset:16
	s_nop 0
	global_load_dwordx4 v[16:19], v[16:17], off offset:48
	s_waitcnt vmcnt(0) lgkmcnt(0)
	v_mov_b32_e32 v20, v4
	v_mov_b32_e32 v21, v8
	v_mov_b32_e32 v8, v5
	v_mov_b32_e32 v4, v6
	v_mov_b32_e32 v5, v10
	v_mov_b32_e32 v10, v7
	v_mov_b32_e32 v6, v12
	v_mov_b32_e32 v7, v16
	v_mov_b32_e32 v16, v13
	v_mov_b32_e32 v12, v14
	v_mov_b32_e32 v13, v18
	v_mov_b32_e32 v18, v15
	v_pk_add_f32 v[8:9], v[20:21], v[8:9]
	v_pk_add_f32 v[4:5], v[4:5], v[10:11]
	v_pk_add_f32 v[6:7], v[6:7], v[16:17]
	v_pk_add_f32 v[10:11], v[12:13], v[18:19]
	v_pk_add_f32 v[4:5], v[8:9], v[4:5]
	v_pk_add_f32 v[6:7], v[6:7], v[10:11]
	s_nop 0
	v_pk_add_f32 v[4:5], v[4:5], v[6:7]
	s_nop 0
	v_add_f32_e32 v4, v4, v5
	v_fmamk_f32 v4, v4, 0x3a800000, v250
	v_rsq_f32_e32 v4, v4
	ds_write_b32 v1, v4

.LBB0_78:
	v_lshl_or_b32 v140, v4, 8, v3
	v_lshlrev_b64 v[2:3], 6, v[140:141]
	v_lshl_add_u64 v[14:15], s[44:45], 0, v[2:3]
	global_load_dwordx4 v[2:5], v[14:15], off
	global_load_dwordx4 v[6:9], v[14:15], off offset:32
	global_load_dwordx4 v[10:13], v[14:15], off offset:16
	s_nop 0
	global_load_dwordx4 v[14:17], v[14:15], off offset:48
	s_waitcnt vmcnt(0) lgkmcnt(0)
	v_mov_b32_e32 v18, v2
	v_mov_b32_e32 v19, v6
	v_mov_b32_e32 v6, v3
	v_mov_b32_e32 v2, v4
	v_mov_b32_e32 v3, v8
	v_mov_b32_e32 v8, v5
	v_mov_b32_e32 v4, v10
	v_mov_b32_e32 v5, v14
	v_mov_b32_e32 v14, v11
	v_mov_b32_e32 v10, v12
	v_mov_b32_e32 v11, v16
	v_mov_b32_e32 v16, v13
	v_pk_add_f32 v[6:7], v[18:19], v[6:7]
	v_pk_add_f32 v[2:3], v[2:3], v[8:9]
	v_pk_add_f32 v[4:5], v[4:5], v[14:15]
	v_pk_add_f32 v[8:9], v[10:11], v[16:17]
	v_pk_add_f32 v[2:3], v[6:7], v[2:3]
	v_pk_add_f32 v[4:5], v[4:5], v[8:9]
	s_nop 0
	v_pk_add_f32 v[2:3], v[2:3], v[4:5]
	s_nop 0
	v_add_f32_e32 v0, v2, v3
	v_fmamk_f32 v0, v0, 0x3a800000, v250
	v_rsq_f32_e32 v0, v0
	ds_write_b32 v1, v0 offset:2048

.LBB0_95:
	s_mov_b32 s5, -1
	s_getreg_b32 s6, hwreg(HW_REG_HW_ID, 0, 6)
	s_and_b32 s6, s6, 63
	s_lshl_b32 s6, s6, 2
	s_add_i32 s6, s6, 0
	s_add_i32 s6, s6, 0x20200
	v_mov_b32_e32 v140, s6
	ds_read_b32 v140, v140
	v_mbcnt_lo_u32_b32 v142, s5, 0
	v_mbcnt_hi_u32_b32 v142, s5, v142
	v_bfrev_b32_e32 v144, 0.5
	s_mov_b64 s[8:9], -1
	s_waitcnt lgkmcnt(0)
	v_readfirstlane_b32 s5, v140
	s_nop 1
	v_lshl_add_u32 v142, s5, 6, v142
	v_and_b32_e32 v184, 63, v142
	v_and_b32_e32 v185, 3, v184
	v_lshrrev_b32_e32 v186, 2, v184
	v_and_b32_e32 v187, 60, v184
	v_lshl_or_b32 v169, v185, 6, v187
	v_and_b32_e32 v187, 15, v184
	v_lshrrev_b32_e32 v184, 4, v184
	v_sub_u32_e32 v186, v186, v187
	v_sub_u32_e32 v185, v185, v184
	v_lshlrev_b32_e32 v186, 7, v186
	v_lshl_add_u32 v170, v185, 4, v186
	v_ashrrev_i32_e32 v171, 31, v170
	s_lshl_b32 s5, s46, 8
	v_readfirstlane_b32 s10, v142
	s_ashr_i32 s6, s10, 2
	s_andn2_b32 s6, s6, 63
	v_bfe_u32 v140, v142, 4, 2
	s_cmp_gt_u32 s94, 3
	v_and_or_b32 v158, v142, 15, s6
	v_lshlrev_b32_e32 v143, 2, v140
	v_lshlrev_b32_e32 v142, 2, v142
	s_cselect_b64 s[6:7], -1, 0
	v_add_u32_e32 v162, s5, v158
	v_bitop3_b32 v168, v142, 64, v144 bitop3:0x6c
	v_bitop3_b32 v167, v142, s84, v144 bitop3:0x6c
	s_and_b64 vcc, exec, s[6:7]
	v_lshlrev_b32_e32 v160, 2, v143
	s_cbranch_vccz .LBB0_97
	v_ashrrev_i32_e32 v163, 31, v162
	v_lshlrev_b64 v[142:143], 6, v[162:163]
	v_lshl_add_u64 v[142:143], s[44:45], 0, v[142:143]
	v_mov_b32_e32 v161, v141
	v_lshl_add_u64 v[142:143], v[142:143], 0, v[160:161]
	global_load_dwordx4 v[142:145], v[142:143], off
	s_mov_b64 s[8:9], 0
	s_waitcnt vmcnt(0) lgkmcnt(0)
	v_mov_b32_e32 v146, v143
	v_mov_b32_e32 v147, v144
	v_mov_b32_e32 v143, v145
	v_pk_add_f32 v[142:143], v[146:147], v[142:143]
	s_nop 0
	v_add_f32_e32 v142, v142, v143
	v_mov_b32_e32 v143, v142
	s_nop 1
	v_permlane16_swap_b32_e32 v143, v142
	s_waitcnt lgkmcnt(0)
	v_add_f32_e32 v142, v142, v143
	ds_bpermute_b32 v143, v167, v142
	s_waitcnt lgkmcnt(0)
	v_add_f32_e32 v142, v142, v143
	v_fmamk_f32 v142, v142, 0x3a800000, v250
	v_rsq_f32_e32 v164, v142

.LBB0_99:
	s_lshr_b32 s8, s10, 1
	s_lshl_b32 s4, s4, 8
	s_and_b32 s9, s8, 64
	v_lshlrev_b32_e32 v140, 3, v140
	s_or_b32 s4, s9, s4
	v_and_or_b32 v140, s8, 32, v140
	s_lshl_b32 s8, s46, 6
	s_ashr_i32 s4, s4, 6
	s_waitcnt lgkmcnt(0)
	v_pk_mul_f32 v[122:123], v[122:123], v[164:165] op_sel_hi:[1,0]
	v_pk_mul_f32 v[120:121], v[120:121], v[164:165] op_sel_hi:[1,0]
	s_add_i32 s8, s4, s8
	v_pk_mul_f32 v[126:127], v[126:127], v[164:165] op_sel_hi:[1,0]
	v_pk_mul_f32 v[124:125], v[124:125], v[164:165] op_sel_hi:[1,0]
	v_max_f32_e32 v120, 0, v120
	v_max_f32_e32 v121, 0, v121
	v_max_f32_e32 v122, 0, v122
	s_ashr_i32 s9, s8, 31
	v_max_f32_e32 v124, 0, v124
	v_mul_f32_e32 v142, v120, v120
	v_max_f32_e32 v120, 0, v125
	v_mul_f32_e32 v125, v121, v121
	v_max_f32_e32 v121, 0, v126
	v_mul_f32_e32 v126, v122, v122
	v_max_f32_e32 v122, 0, v127
	s_lshl_b64 s[10:11], s[8:9], 15
	v_mul_f32_e32 v124, v124, v124
	v_mul_f32_e32 v120, v120, v120
	v_mul_f32_e32 v121, v121, v121
	v_max_f32_e32 v123, 0, v123
	v_mul_f32_e32 v122, v122, v122
	v_ashrrev_i32_e32 v159, 31, v158
	s_add_u32 s58, s86, s10
	v_mul_f32_e32 v123, v123, v123
	v_cvt_pk_bf16_f32 v120, v124, v120
	v_cvt_pk_bf16_f32 v121, v121, v122
	v_cvt_pk_bf16_f32 v122, v142, v125
	s_addc_u32 s59, s87, s11
	v_lshlrev_b64 v[124:125], 7, v[158:159]
	s_or_b32 s8, s8, 2
	v_cvt_pk_bf16_f32 v123, v126, v123
	v_lshl_add_u64 v[126:127], s[58:59], 0, v[124:125]
	v_lshlrev_b32_e32 v140, 1, v140
	v_pk_mul_f32 v[114:115], v[114:115], v[164:165] op_sel_hi:[1,0]
	v_pk_mul_f32 v[112:113], v[112:113], v[164:165] op_sel_hi:[1,0]
	s_ashr_i32 s9, s8, 31
	v_lshl_add_u64 v[126:127], v[126:127], 0, v[140:141]
	v_pk_mul_f32 v[118:119], v[118:119], v[164:165] op_sel_hi:[1,0]
	v_pk_mul_f32 v[116:117], v[116:117], v[164:165] op_sel_hi:[1,0]
	v_max_f32_e32 v112, 0, v112
	v_max_f32_e32 v113, 0, v113
	v_max_f32_e32 v114, 0, v114
	s_lshl_b64 s[8:9], s[8:9], 15
	ds_bpermute_b32 v172, v169, v120
	ds_bpermute_b32 v173, v169, v121
	ds_bpermute_b32 v174, v169, v122
	ds_bpermute_b32 v175, v169, v123
	v_lshl_add_u64 v[176:177], v[126:127], 0, v[170:171]
	v_max_f32_e32 v116, 0, v116
	s_add_u32 s74, s86, s8
	v_mul_f32_e32 v120, v112, v112
	v_max_f32_e32 v112, 0, v117
	v_mul_f32_e32 v117, v113, v113
	v_max_f32_e32 v113, 0, v118
	v_mul_f32_e32 v118, v114, v114
	v_max_f32_e32 v114, 0, v119
	v_mul_f32_e32 v116, v116, v116
	v_mul_f32_e32 v112, v112, v112
	v_mul_f32_e32 v113, v113, v113
	v_mul_f32_e32 v114, v114, v114
	s_addc_u32 s75, s87, s9
	v_max_f32_e32 v115, 0, v115
	v_cvt_pk_bf16_f32 v112, v116, v112
	v_cvt_pk_bf16_f32 v113, v113, v114
	v_cvt_pk_bf16_f32 v114, v120, v117
	v_lshl_add_u64 v[116:117], s[74:75], 0, v[124:125]
	v_mul_f32_e32 v115, v115, v115
	v_lshl_add_u64 v[116:117], v[116:117], 0, v[140:141]
	v_cvt_pk_bf16_f32 v115, v118, v115
	s_waitcnt lgkmcnt(0)
	global_store_dwordx4 v[176:177], v[172:175], off nt
	ds_bpermute_b32 v178, v169, v112
	ds_bpermute_b32 v179, v169, v113
	ds_bpermute_b32 v180, v169, v114
	ds_bpermute_b32 v181, v169, v115
	v_lshl_add_u64 v[182:183], v[116:117], 0, v[170:171]
	v_or_b32_e32 v116, 16, v162
	s_mov_b64 s[8:9], -1
	s_and_b64 vcc, exec, s[6:7]
	v_subrev_u32_e32 v113, s5, v116
	v_mov_b32_e32 v198, v220
	v_mov_b32_e32 v199, v221
	v_mov_b32_e32 v205, v223
	v_mov_b32_e32 v196, v224
	s_cbranch_vccz .LBB0_101
	v_ashrrev_i32_e32 v117, 31, v116
	v_lshlrev_b64 v[114:115], 6, v[116:117]
	v_lshl_add_u64 v[114:115], s[44:45], 0, v[114:115]
	v_mov_b32_e32 v161, v141
	v_lshl_add_u64 v[114:115], v[114:115], 0, v[160:161]
	global_load_dwordx4 v[118:121], v[114:115], off
	s_mov_b64 s[8:9], 0
	s_waitcnt vmcnt(0) lgkmcnt(0)
	v_mov_b32_e32 v114, v119
	v_mov_b32_e32 v115, v120
	v_mov_b32_e32 v119, v121
	v_pk_add_f32 v[114:115], v[114:115], v[118:119]
	s_nop 0
	v_add_f32_e32 v112, v114, v115
	v_mov_b32_e32 v114, v112
	s_nop 1
	v_permlane16_swap_b32_e32 v114, v112
	s_waitcnt lgkmcnt(0)
	v_add_f32_e32 v112, v112, v114
	v_mov_b32_e32 v114, v112
	s_nop 1
	v_permlane32_swap_b32_e32 v114, v112
	s_waitcnt lgkmcnt(0)
	v_add_f32_e32 v112, v112, v114
	v_fmamk_f32 v112, v112, 0x3a800000, v250
	v_rsq_f32_e32 v112, v112
	v_subrev_u32_e32 v114, s5, v116

.LBB0_103:
	s_waitcnt lgkmcnt(0)
	v_pk_mul_f32 v[106:107], v[106:107], v[112:113] op_sel_hi:[1,0]
	v_pk_mul_f32 v[104:105], v[104:105], v[112:113] op_sel_hi:[1,0]
	v_pk_mul_f32 v[110:111], v[110:111], v[112:113] op_sel_hi:[1,0]
	v_pk_mul_f32 v[108:109], v[108:109], v[112:113] op_sel_hi:[1,0]
	v_max_f32_e32 v104, 0, v104
	v_max_f32_e32 v105, 0, v105
	v_max_f32_e32 v106, 0, v106
	v_max_f32_e32 v108, 0, v108
	v_mul_f32_e32 v113, v104, v104
	v_max_f32_e32 v104, 0, v109
	v_mul_f32_e32 v109, v105, v105
	v_max_f32_e32 v105, 0, v110
	v_mul_f32_e32 v110, v106, v106
	v_max_f32_e32 v106, 0, v111
	v_mul_f32_e32 v108, v108, v108
	v_mul_f32_e32 v104, v104, v104
	v_mul_f32_e32 v105, v105, v105
	v_max_f32_e32 v107, 0, v107
	v_mul_f32_e32 v106, v106, v106
	v_ashrrev_i32_e32 v115, 31, v114
	v_mul_f32_e32 v107, v107, v107
	v_cvt_pk_bf16_f32 v104, v108, v104
	v_cvt_pk_bf16_f32 v105, v105, v106
	v_cvt_pk_bf16_f32 v106, v113, v109
	v_lshlrev_b64 v[108:109], 7, v[114:115]
	v_cvt_pk_bf16_f32 v107, v110, v107
	v_lshl_add_u64 v[110:111], s[58:59], 0, v[108:109]
	v_pk_mul_f32 v[98:99], v[98:99], v[112:113] op_sel_hi:[1,0]
	v_pk_mul_f32 v[96:97], v[96:97], v[112:113] op_sel_hi:[1,0]
	v_lshl_add_u64 v[110:111], v[110:111], 0, v[140:141]
	v_pk_mul_f32 v[102:103], v[102:103], v[112:113] op_sel_hi:[1,0]
	v_pk_mul_f32 v[100:101], v[100:101], v[112:113] op_sel_hi:[1,0]
	v_max_f32_e32 v96, 0, v96
	v_max_f32_e32 v97, 0, v97
	v_max_f32_e32 v98, 0, v98
	s_waitcnt lgkmcnt(0)
	global_store_dwordx4 v[182:183], v[178:181], off nt
	ds_bpermute_b32 v172, v169, v104
	ds_bpermute_b32 v173, v169, v105
	ds_bpermute_b32 v174, v169, v106
	ds_bpermute_b32 v175, v169, v107
	v_lshl_add_u64 v[176:177], v[110:111], 0, v[170:171]
	v_max_f32_e32 v100, 0, v100
	v_mul_f32_e32 v100, v100, v100
	v_mul_f32_e32 v104, v96, v96
	v_max_f32_e32 v96, 0, v101
	v_mul_f32_e32 v101, v97, v97
	v_max_f32_e32 v97, 0, v102
	v_mul_f32_e32 v102, v98, v98
	v_max_f32_e32 v98, 0, v103
	v_mul_f32_e32 v96, v96, v96
	v_mul_f32_e32 v97, v97, v97
	v_mul_f32_e32 v98, v98, v98
	v_max_f32_e32 v99, 0, v99
	v_cvt_pk_bf16_f32 v96, v100, v96
	v_cvt_pk_bf16_f32 v97, v97, v98
	v_cvt_pk_bf16_f32 v98, v104, v101
	v_lshl_add_u64 v[100:101], s[74:75], 0, v[108:109]
	v_mul_f32_e32 v99, v99, v99
	v_lshl_add_u64 v[100:101], v[100:101], 0, v[140:141]
	v_cvt_pk_bf16_f32 v99, v102, v99
	s_waitcnt lgkmcnt(0)
	global_store_dwordx4 v[176:177], v[172:175], off nt
	ds_bpermute_b32 v178, v169, v96
	ds_bpermute_b32 v179, v169, v97
	ds_bpermute_b32 v180, v169, v98
	ds_bpermute_b32 v181, v169, v99
	v_lshl_add_u64 v[182:183], v[100:101], 0, v[170:171]
	v_or_b32_e32 v100, 32, v162
	s_mov_b64 s[8:9], -1
	s_and_b64 vcc, exec, s[6:7]
	v_subrev_u32_e32 v97, s5, v100
	s_cbranch_vccz .LBB0_105
	v_ashrrev_i32_e32 v101, 31, v100
	v_lshlrev_b64 v[98:99], 6, v[100:101]
	v_lshl_add_u64 v[98:99], s[44:45], 0, v[98:99]
	v_mov_b32_e32 v161, v141
	v_lshl_add_u64 v[98:99], v[98:99], 0, v[160:161]
	global_load_dwordx4 v[102:105], v[98:99], off
	s_mov_b64 s[8:9], 0
	s_waitcnt vmcnt(0) lgkmcnt(0)
	v_mov_b32_e32 v98, v103
	v_mov_b32_e32 v99, v104
	v_mov_b32_e32 v103, v105
	v_pk_add_f32 v[98:99], v[98:99], v[102:103]
	s_nop 0
	v_add_f32_e32 v96, v98, v99
	v_mov_b32_e32 v98, v96
	s_nop 1
	v_permlane16_swap_b32_e32 v98, v96
	s_waitcnt lgkmcnt(0)
	v_add_f32_e32 v96, v96, v98
	v_mov_b32_e32 v98, v96
	s_nop 1
	v_permlane32_swap_b32_e32 v98, v96
	s_waitcnt lgkmcnt(0)
	v_add_f32_e32 v96, v96, v98
	v_fmamk_f32 v96, v96, 0x3a800000, v250
	v_rsq_f32_e32 v96, v96
	v_subrev_u32_e32 v98, s5, v100

.LBB0_107:
	s_waitcnt lgkmcnt(0)
	v_pk_mul_f32 v[90:91], v[90:91], v[96:97] op_sel_hi:[1,0]
	v_pk_mul_f32 v[88:89], v[88:89], v[96:97] op_sel_hi:[1,0]
	v_pk_mul_f32 v[94:95], v[94:95], v[96:97] op_sel_hi:[1,0]
	v_pk_mul_f32 v[92:93], v[92:93], v[96:97] op_sel_hi:[1,0]
	v_max_f32_e32 v88, 0, v88
	v_max_f32_e32 v89, 0, v89
	v_max_f32_e32 v90, 0, v90
	v_max_f32_e32 v92, 0, v92
	v_mul_f32_e32 v97, v88, v88
	v_max_f32_e32 v88, 0, v93
	v_mul_f32_e32 v93, v89, v89
	v_max_f32_e32 v89, 0, v94
	v_mul_f32_e32 v94, v90, v90
	v_max_f32_e32 v90, 0, v95
	v_mul_f32_e32 v92, v92, v92
	v_mul_f32_e32 v88, v88, v88
	v_mul_f32_e32 v89, v89, v89
	v_max_f32_e32 v91, 0, v91
	v_mul_f32_e32 v90, v90, v90
	v_ashrrev_i32_e32 v99, 31, v98
	v_mul_f32_e32 v91, v91, v91
	v_cvt_pk_bf16_f32 v88, v92, v88
	v_cvt_pk_bf16_f32 v89, v89, v90
	v_cvt_pk_bf16_f32 v90, v97, v93
	v_lshlrev_b64 v[92:93], 7, v[98:99]
	v_cvt_pk_bf16_f32 v91, v94, v91
	v_lshl_add_u64 v[94:95], s[58:59], 0, v[92:93]
	v_pk_mul_f32 v[82:83], v[82:83], v[96:97] op_sel_hi:[1,0]
	v_pk_mul_f32 v[80:81], v[80:81], v[96:97] op_sel_hi:[1,0]
	v_lshl_add_u64 v[94:95], v[94:95], 0, v[140:141]
	v_pk_mul_f32 v[86:87], v[86:87], v[96:97] op_sel_hi:[1,0]
	v_pk_mul_f32 v[84:85], v[84:85], v[96:97] op_sel_hi:[1,0]
	v_max_f32_e32 v80, 0, v80
	v_max_f32_e32 v81, 0, v81
	v_max_f32_e32 v82, 0, v82
	s_waitcnt lgkmcnt(0)
	global_store_dwordx4 v[182:183], v[178:181], off nt
	ds_bpermute_b32 v172, v169, v88
	ds_bpermute_b32 v173, v169, v89
	ds_bpermute_b32 v174, v169, v90
	ds_bpermute_b32 v175, v169, v91
	v_lshl_add_u64 v[176:177], v[94:95], 0, v[170:171]
	v_max_f32_e32 v84, 0, v84
	v_mul_f32_e32 v84, v84, v84
	v_mul_f32_e32 v88, v80, v80
	v_max_f32_e32 v80, 0, v85
	v_mul_f32_e32 v85, v81, v81
	v_max_f32_e32 v81, 0, v86
	v_mul_f32_e32 v86, v82, v82
	v_max_f32_e32 v82, 0, v87
	v_mul_f32_e32 v80, v80, v80
	v_mul_f32_e32 v81, v81, v81
	v_mul_f32_e32 v82, v82, v82
	v_max_f32_e32 v83, 0, v83
	v_cvt_pk_bf16_f32 v80, v84, v80
	v_cvt_pk_bf16_f32 v81, v81, v82
	v_cvt_pk_bf16_f32 v82, v88, v85
	v_lshl_add_u64 v[84:85], s[74:75], 0, v[92:93]
	v_mul_f32_e32 v83, v83, v83
	v_lshl_add_u64 v[84:85], v[84:85], 0, v[140:141]
	v_cvt_pk_bf16_f32 v83, v86, v83
	s_waitcnt lgkmcnt(0)
	global_store_dwordx4 v[176:177], v[172:175], off nt
	ds_bpermute_b32 v178, v169, v80
	ds_bpermute_b32 v179, v169, v81
	ds_bpermute_b32 v180, v169, v82
	ds_bpermute_b32 v181, v169, v83
	v_lshl_add_u64 v[182:183], v[84:85], 0, v[170:171]
	v_or_b32_e32 v84, 48, v162
	s_mov_b64 s[8:9], -1
	s_and_b64 vcc, exec, s[6:7]
	v_subrev_u32_e32 v81, s5, v84
	s_cbranch_vccz .LBB0_109
	v_ashrrev_i32_e32 v85, 31, v84
	v_lshlrev_b64 v[82:83], 6, v[84:85]
	v_lshl_add_u64 v[82:83], s[44:45], 0, v[82:83]
	v_mov_b32_e32 v161, v141
	v_lshl_add_u64 v[82:83], v[82:83], 0, v[160:161]
	global_load_dwordx4 v[86:89], v[82:83], off
	s_mov_b64 s[8:9], 0
	s_waitcnt vmcnt(0) lgkmcnt(0)
	v_mov_b32_e32 v82, v87
	v_mov_b32_e32 v83, v88
	v_mov_b32_e32 v87, v89
	v_pk_add_f32 v[82:83], v[82:83], v[86:87]
	s_nop 0
	v_add_f32_e32 v80, v82, v83
	v_mov_b32_e32 v82, v80
	s_nop 1
	v_permlane16_swap_b32_e32 v82, v80
	s_waitcnt lgkmcnt(0)
	v_add_f32_e32 v80, v80, v82
	v_mov_b32_e32 v82, v80
	s_nop 1
	v_permlane32_swap_b32_e32 v82, v80
	s_waitcnt lgkmcnt(0)
	v_add_f32_e32 v80, v80, v82
	v_fmamk_f32 v80, v80, 0x3a800000, v250
	v_rsq_f32_e32 v80, v80
	v_subrev_u32_e32 v82, s5, v84

.LBB0_111:
	s_waitcnt lgkmcnt(0)
	v_pk_mul_f32 v[74:75], v[74:75], v[80:81] op_sel_hi:[1,0]
	v_pk_mul_f32 v[72:73], v[72:73], v[80:81] op_sel_hi:[1,0]
	v_pk_mul_f32 v[78:79], v[78:79], v[80:81] op_sel_hi:[1,0]
	v_pk_mul_f32 v[76:77], v[76:77], v[80:81] op_sel_hi:[1,0]
	v_max_f32_e32 v72, 0, v72
	v_max_f32_e32 v73, 0, v73
	v_max_f32_e32 v74, 0, v74
	v_max_f32_e32 v76, 0, v76
	v_mul_f32_e32 v81, v72, v72
	v_max_f32_e32 v72, 0, v77
	v_mul_f32_e32 v77, v73, v73
	v_max_f32_e32 v73, 0, v78
	v_mul_f32_e32 v78, v74, v74
	v_max_f32_e32 v74, 0, v79
	v_mul_f32_e32 v76, v76, v76
	v_mul_f32_e32 v72, v72, v72
	v_mul_f32_e32 v73, v73, v73
	v_max_f32_e32 v75, 0, v75
	v_mul_f32_e32 v74, v74, v74
	v_ashrrev_i32_e32 v83, 31, v82
	v_mul_f32_e32 v75, v75, v75
	v_cvt_pk_bf16_f32 v72, v76, v72
	v_cvt_pk_bf16_f32 v73, v73, v74
	v_cvt_pk_bf16_f32 v74, v81, v77
	v_lshlrev_b64 v[76:77], 7, v[82:83]
	v_cvt_pk_bf16_f32 v75, v78, v75
	v_lshl_add_u64 v[78:79], s[58:59], 0, v[76:77]
	v_pk_mul_f32 v[66:67], v[66:67], v[80:81] op_sel_hi:[1,0]
	v_pk_mul_f32 v[64:65], v[64:65], v[80:81] op_sel_hi:[1,0]
	v_lshl_add_u64 v[78:79], v[78:79], 0, v[140:141]
	v_pk_mul_f32 v[70:71], v[70:71], v[80:81] op_sel_hi:[1,0]
	v_pk_mul_f32 v[68:69], v[68:69], v[80:81] op_sel_hi:[1,0]
	v_max_f32_e32 v64, 0, v64
	v_max_f32_e32 v65, 0, v65
	v_max_f32_e32 v66, 0, v66
	s_waitcnt lgkmcnt(0)
	global_store_dwordx4 v[182:183], v[178:181], off nt
	ds_bpermute_b32 v172, v169, v72
	ds_bpermute_b32 v173, v169, v73
	ds_bpermute_b32 v174, v169, v74
	ds_bpermute_b32 v175, v169, v75
	v_lshl_add_u64 v[176:177], v[78:79], 0, v[170:171]
	v_max_f32_e32 v68, 0, v68
	v_mul_f32_e32 v68, v68, v68
	v_mul_f32_e32 v72, v64, v64
	v_max_f32_e32 v64, 0, v69
	v_mul_f32_e32 v69, v65, v65
	v_max_f32_e32 v65, 0, v70
	v_mul_f32_e32 v70, v66, v66
	v_max_f32_e32 v66, 0, v71
	v_mul_f32_e32 v64, v64, v64
	v_mul_f32_e32 v65, v65, v65
	v_mul_f32_e32 v66, v66, v66
	v_max_f32_e32 v67, 0, v67
	v_cvt_pk_bf16_f32 v64, v68, v64
	v_cvt_pk_bf16_f32 v65, v65, v66
	v_cvt_pk_bf16_f32 v66, v72, v69
	v_lshl_add_u64 v[68:69], s[74:75], 0, v[76:77]
	v_mul_f32_e32 v67, v67, v67
	v_lshl_add_u64 v[68:69], v[68:69], 0, v[140:141]
	v_cvt_pk_bf16_f32 v67, v70, v67
	s_waitcnt lgkmcnt(0)
	global_store_dwordx4 v[176:177], v[172:175], off nt
	ds_bpermute_b32 v178, v169, v64
	ds_bpermute_b32 v179, v169, v65
	ds_bpermute_b32 v180, v169, v66
	ds_bpermute_b32 v181, v169, v67
	v_lshl_add_u64 v[182:183], v[68:69], 0, v[170:171]
	v_add_u32_e32 v68, 0x80, v162
	s_mov_b64 s[8:9], -1
	s_and_b64 vcc, exec, s[6:7]
	v_subrev_u32_e32 v65, s5, v68
	s_cbranch_vccz .LBB0_113
	v_ashrrev_i32_e32 v69, 31, v68
	v_lshlrev_b64 v[66:67], 6, v[68:69]
	v_lshl_add_u64 v[66:67], s[44:45], 0, v[66:67]
	v_mov_b32_e32 v161, v141
	v_lshl_add_u64 v[66:67], v[66:67], 0, v[160:161]
	global_load_dwordx4 v[70:73], v[66:67], off
	s_mov_b64 s[8:9], 0
	s_waitcnt vmcnt(0) lgkmcnt(0)
	v_mov_b32_e32 v66, v71
	v_mov_b32_e32 v67, v72
	v_mov_b32_e32 v71, v73
	v_pk_add_f32 v[66:67], v[66:67], v[70:71]
	s_nop 0
	v_add_f32_e32 v64, v66, v67
	v_mov_b32_e32 v66, v64
	s_nop 1
	v_permlane16_swap_b32_e32 v66, v64
	s_waitcnt lgkmcnt(0)
	v_add_f32_e32 v64, v64, v66
	v_mov_b32_e32 v66, v64
	s_nop 1
	v_permlane32_swap_b32_e32 v66, v64
	s_waitcnt lgkmcnt(0)
	v_add_f32_e32 v64, v64, v66
	v_fmamk_f32 v64, v64, 0x3a800000, v250
	v_rsq_f32_e32 v64, v64
	v_subrev_u32_e32 v66, s5, v68

.LBB0_115:
	s_waitcnt lgkmcnt(0)
	v_pk_mul_f32 v[58:59], v[58:59], v[64:65] op_sel_hi:[1,0]
	v_pk_mul_f32 v[56:57], v[56:57], v[64:65] op_sel_hi:[1,0]
	v_pk_mul_f32 v[62:63], v[62:63], v[64:65] op_sel_hi:[1,0]
	v_pk_mul_f32 v[60:61], v[60:61], v[64:65] op_sel_hi:[1,0]
	v_max_f32_e32 v56, 0, v56
	v_max_f32_e32 v57, 0, v57
	v_max_f32_e32 v58, 0, v58
	v_max_f32_e32 v60, 0, v60
	v_mul_f32_e32 v65, v56, v56
	v_max_f32_e32 v56, 0, v61
	v_mul_f32_e32 v61, v57, v57
	v_max_f32_e32 v57, 0, v62
	v_mul_f32_e32 v62, v58, v58
	v_max_f32_e32 v58, 0, v63
	v_mul_f32_e32 v60, v60, v60
	v_mul_f32_e32 v56, v56, v56
	v_mul_f32_e32 v57, v57, v57
	v_max_f32_e32 v59, 0, v59
	v_mul_f32_e32 v58, v58, v58
	v_ashrrev_i32_e32 v67, 31, v66
	v_mul_f32_e32 v59, v59, v59
	v_cvt_pk_bf16_f32 v56, v60, v56
	v_cvt_pk_bf16_f32 v57, v57, v58
	v_cvt_pk_bf16_f32 v58, v65, v61
	v_lshlrev_b64 v[60:61], 7, v[66:67]
	v_cvt_pk_bf16_f32 v59, v62, v59
	v_lshl_add_u64 v[62:63], s[58:59], 0, v[60:61]
	v_pk_mul_f32 v[50:51], v[50:51], v[64:65] op_sel_hi:[1,0]
	v_pk_mul_f32 v[48:49], v[48:49], v[64:65] op_sel_hi:[1,0]
	v_lshl_add_u64 v[62:63], v[62:63], 0, v[140:141]
	v_pk_mul_f32 v[54:55], v[54:55], v[64:65] op_sel_hi:[1,0]
	v_pk_mul_f32 v[52:53], v[52:53], v[64:65] op_sel_hi:[1,0]
	v_max_f32_e32 v48, 0, v48
	v_max_f32_e32 v49, 0, v49
	v_max_f32_e32 v50, 0, v50
	s_waitcnt lgkmcnt(0)
	global_store_dwordx4 v[182:183], v[178:181], off nt
	ds_bpermute_b32 v172, v169, v56
	ds_bpermute_b32 v173, v169, v57
	ds_bpermute_b32 v174, v169, v58
	ds_bpermute_b32 v175, v169, v59
	v_lshl_add_u64 v[176:177], v[62:63], 0, v[170:171]
	v_max_f32_e32 v52, 0, v52
	v_mul_f32_e32 v52, v52, v52
	v_mul_f32_e32 v56, v48, v48
	v_max_f32_e32 v48, 0, v53
	v_mul_f32_e32 v53, v49, v49
	v_max_f32_e32 v49, 0, v54
	v_mul_f32_e32 v54, v50, v50
	v_max_f32_e32 v50, 0, v55
	v_mul_f32_e32 v48, v48, v48
	v_mul_f32_e32 v49, v49, v49
	v_mul_f32_e32 v50, v50, v50
	v_max_f32_e32 v51, 0, v51
	v_cvt_pk_bf16_f32 v48, v52, v48
	v_cvt_pk_bf16_f32 v49, v49, v50
	v_cvt_pk_bf16_f32 v50, v56, v53
	v_lshl_add_u64 v[52:53], s[74:75], 0, v[60:61]
	v_mul_f32_e32 v51, v51, v51
	v_lshl_add_u64 v[52:53], v[52:53], 0, v[140:141]
	v_cvt_pk_bf16_f32 v51, v54, v51
	s_waitcnt lgkmcnt(0)
	global_store_dwordx4 v[176:177], v[172:175], off nt
	ds_bpermute_b32 v178, v169, v48
	ds_bpermute_b32 v179, v169, v49
	ds_bpermute_b32 v180, v169, v50
	ds_bpermute_b32 v181, v169, v51
	v_lshl_add_u64 v[182:183], v[52:53], 0, v[170:171]
	v_add_u32_e32 v52, 0x90, v162
	s_mov_b64 s[8:9], -1
	s_and_b64 vcc, exec, s[6:7]
	v_subrev_u32_e32 v49, s5, v52
	s_cbranch_vccz .LBB0_117
	v_ashrrev_i32_e32 v53, 31, v52
	v_lshlrev_b64 v[50:51], 6, v[52:53]
	v_lshl_add_u64 v[50:51], s[44:45], 0, v[50:51]
	v_mov_b32_e32 v161, v141
	v_lshl_add_u64 v[50:51], v[50:51], 0, v[160:161]
	global_load_dwordx4 v[54:57], v[50:51], off
	s_mov_b64 s[8:9], 0
	s_waitcnt vmcnt(0) lgkmcnt(0)
	v_mov_b32_e32 v50, v55
	v_mov_b32_e32 v51, v56
	v_mov_b32_e32 v55, v57
	v_pk_add_f32 v[50:51], v[50:51], v[54:55]
	s_nop 0
	v_add_f32_e32 v48, v50, v51
	v_mov_b32_e32 v50, v48
	s_nop 1
	v_permlane16_swap_b32_e32 v50, v48
	s_waitcnt lgkmcnt(0)
	v_add_f32_e32 v48, v48, v50
	v_mov_b32_e32 v50, v48
	s_nop 1
	v_permlane32_swap_b32_e32 v50, v48
	s_waitcnt lgkmcnt(0)
	v_add_f32_e32 v48, v48, v50
	v_fmamk_f32 v48, v48, 0x3a800000, v250
	v_rsq_f32_e32 v48, v48
	v_subrev_u32_e32 v50, s5, v52

.LBB0_119:
	s_waitcnt lgkmcnt(0)
	v_pk_mul_f32 v[42:43], v[42:43], v[48:49] op_sel_hi:[1,0]
	v_pk_mul_f32 v[40:41], v[40:41], v[48:49] op_sel_hi:[1,0]
	v_pk_mul_f32 v[46:47], v[46:47], v[48:49] op_sel_hi:[1,0]
	v_pk_mul_f32 v[44:45], v[44:45], v[48:49] op_sel_hi:[1,0]
	v_max_f32_e32 v40, 0, v40
	v_max_f32_e32 v41, 0, v41
	v_max_f32_e32 v42, 0, v42
	v_max_f32_e32 v44, 0, v44
	v_mul_f32_e32 v49, v40, v40
	v_max_f32_e32 v40, 0, v45
	v_mul_f32_e32 v45, v41, v41
	v_max_f32_e32 v41, 0, v46
	v_mul_f32_e32 v46, v42, v42
	v_max_f32_e32 v42, 0, v47
	v_mul_f32_e32 v44, v44, v44
	v_mul_f32_e32 v40, v40, v40
	v_mul_f32_e32 v41, v41, v41
	v_max_f32_e32 v43, 0, v43
	v_mul_f32_e32 v42, v42, v42
	v_ashrrev_i32_e32 v51, 31, v50
	v_mul_f32_e32 v43, v43, v43
	v_cvt_pk_bf16_f32 v40, v44, v40
	v_cvt_pk_bf16_f32 v41, v41, v42
	v_cvt_pk_bf16_f32 v42, v49, v45
	v_lshlrev_b64 v[44:45], 7, v[50:51]
	v_cvt_pk_bf16_f32 v43, v46, v43
	v_lshl_add_u64 v[46:47], s[58:59], 0, v[44:45]
	v_pk_mul_f32 v[34:35], v[34:35], v[48:49] op_sel_hi:[1,0]
	v_pk_mul_f32 v[32:33], v[32:33], v[48:49] op_sel_hi:[1,0]
	v_lshl_add_u64 v[46:47], v[46:47], 0, v[140:141]
	v_pk_mul_f32 v[38:39], v[38:39], v[48:49] op_sel_hi:[1,0]
	v_pk_mul_f32 v[36:37], v[36:37], v[48:49] op_sel_hi:[1,0]
	v_max_f32_e32 v32, 0, v32
	v_max_f32_e32 v33, 0, v33
	v_max_f32_e32 v34, 0, v34
	s_waitcnt lgkmcnt(0)
	global_store_dwordx4 v[182:183], v[178:181], off nt
	ds_bpermute_b32 v172, v169, v40
	ds_bpermute_b32 v173, v169, v41
	ds_bpermute_b32 v174, v169, v42
	ds_bpermute_b32 v175, v169, v43
	v_lshl_add_u64 v[176:177], v[46:47], 0, v[170:171]
	v_max_f32_e32 v36, 0, v36
	v_mul_f32_e32 v36, v36, v36
	v_mul_f32_e32 v40, v32, v32
	v_max_f32_e32 v32, 0, v37
	v_mul_f32_e32 v37, v33, v33
	v_max_f32_e32 v33, 0, v38
	v_mul_f32_e32 v38, v34, v34
	v_max_f32_e32 v34, 0, v39
	v_mul_f32_e32 v32, v32, v32
	v_mul_f32_e32 v33, v33, v33
	v_mul_f32_e32 v34, v34, v34
	v_max_f32_e32 v35, 0, v35
	v_cvt_pk_bf16_f32 v32, v36, v32
	v_cvt_pk_bf16_f32 v33, v33, v34
	v_cvt_pk_bf16_f32 v34, v40, v37
	v_lshl_add_u64 v[36:37], s[74:75], 0, v[44:45]
	v_mul_f32_e32 v35, v35, v35
	v_lshl_add_u64 v[36:37], v[36:37], 0, v[140:141]
	v_cvt_pk_bf16_f32 v35, v38, v35
	s_waitcnt lgkmcnt(0)
	global_store_dwordx4 v[176:177], v[172:175], off nt
	ds_bpermute_b32 v178, v169, v32
	ds_bpermute_b32 v179, v169, v33
	ds_bpermute_b32 v180, v169, v34
	ds_bpermute_b32 v181, v169, v35
	v_lshl_add_u64 v[182:183], v[36:37], 0, v[170:171]
	v_add_u32_e32 v36, 0xa0, v162
	s_mov_b64 s[8:9], -1
	s_and_b64 vcc, exec, s[6:7]
	v_subrev_u32_e32 v33, s5, v36
	s_cbranch_vccz .LBB0_121
	v_ashrrev_i32_e32 v37, 31, v36
	v_lshlrev_b64 v[34:35], 6, v[36:37]
	v_lshl_add_u64 v[34:35], s[44:45], 0, v[34:35]
	v_mov_b32_e32 v161, v141
	v_lshl_add_u64 v[34:35], v[34:35], 0, v[160:161]
	global_load_dwordx4 v[38:41], v[34:35], off
	s_mov_b64 s[8:9], 0
	s_waitcnt vmcnt(0) lgkmcnt(0)
	v_mov_b32_e32 v34, v39
	v_mov_b32_e32 v35, v40
	v_mov_b32_e32 v39, v41
	v_pk_add_f32 v[34:35], v[34:35], v[38:39]
	s_nop 0
	v_add_f32_e32 v32, v34, v35
	v_mov_b32_e32 v34, v32
	s_nop 1
	v_permlane16_swap_b32_e32 v34, v32
	s_waitcnt lgkmcnt(0)
	v_add_f32_e32 v32, v32, v34
	v_mov_b32_e32 v34, v32
	s_nop 1
	v_permlane32_swap_b32_e32 v34, v32
	s_waitcnt lgkmcnt(0)
	v_add_f32_e32 v32, v32, v34
	v_fmamk_f32 v32, v32, 0x3a800000, v250
	v_rsq_f32_e32 v32, v32
	v_subrev_u32_e32 v34, s5, v36

.LBB0_123:
	s_waitcnt lgkmcnt(0)
	v_pk_mul_f32 v[26:27], v[26:27], v[32:33] op_sel_hi:[1,0]
	v_pk_mul_f32 v[24:25], v[24:25], v[32:33] op_sel_hi:[1,0]
	v_pk_mul_f32 v[30:31], v[30:31], v[32:33] op_sel_hi:[1,0]
	v_pk_mul_f32 v[28:29], v[28:29], v[32:33] op_sel_hi:[1,0]
	v_max_f32_e32 v24, 0, v24
	v_max_f32_e32 v25, 0, v25
	v_max_f32_e32 v26, 0, v26
	v_max_f32_e32 v28, 0, v28
	v_mul_f32_e32 v33, v24, v24
	v_max_f32_e32 v24, 0, v29
	v_mul_f32_e32 v29, v25, v25
	v_max_f32_e32 v25, 0, v30
	v_mul_f32_e32 v30, v26, v26
	v_max_f32_e32 v26, 0, v31
	v_mul_f32_e32 v28, v28, v28
	v_mul_f32_e32 v24, v24, v24
	v_mul_f32_e32 v25, v25, v25
	v_max_f32_e32 v27, 0, v27
	v_mul_f32_e32 v26, v26, v26
	v_ashrrev_i32_e32 v35, 31, v34
	v_mul_f32_e32 v27, v27, v27
	v_cvt_pk_bf16_f32 v24, v28, v24
	v_cvt_pk_bf16_f32 v25, v25, v26
	v_cvt_pk_bf16_f32 v26, v33, v29
	v_lshlrev_b64 v[28:29], 7, v[34:35]
	v_cvt_pk_bf16_f32 v27, v30, v27
	v_lshl_add_u64 v[30:31], s[58:59], 0, v[28:29]
	v_pk_mul_f32 v[18:19], v[18:19], v[32:33] op_sel_hi:[1,0]
	v_pk_mul_f32 v[16:17], v[16:17], v[32:33] op_sel_hi:[1,0]
	v_lshl_add_u64 v[30:31], v[30:31], 0, v[140:141]
	v_pk_mul_f32 v[22:23], v[22:23], v[32:33] op_sel_hi:[1,0]
	v_pk_mul_f32 v[20:21], v[20:21], v[32:33] op_sel_hi:[1,0]
	v_max_f32_e32 v16, 0, v16
	v_max_f32_e32 v17, 0, v17
	v_max_f32_e32 v18, 0, v18
	s_waitcnt lgkmcnt(0)
	global_store_dwordx4 v[182:183], v[178:181], off nt
	ds_bpermute_b32 v172, v169, v24
	ds_bpermute_b32 v173, v169, v25
	ds_bpermute_b32 v174, v169, v26
	ds_bpermute_b32 v175, v169, v27
	v_lshl_add_u64 v[176:177], v[30:31], 0, v[170:171]
	v_max_f32_e32 v20, 0, v20
	v_mul_f32_e32 v20, v20, v20
	v_mul_f32_e32 v24, v16, v16
	v_max_f32_e32 v16, 0, v21
	v_mul_f32_e32 v21, v17, v17
	v_max_f32_e32 v17, 0, v22
	v_mul_f32_e32 v22, v18, v18
	v_max_f32_e32 v18, 0, v23
	v_mul_f32_e32 v16, v16, v16
	v_mul_f32_e32 v17, v17, v17
	v_mul_f32_e32 v18, v18, v18
	v_max_f32_e32 v19, 0, v19
	v_cvt_pk_bf16_f32 v16, v20, v16
	v_cvt_pk_bf16_f32 v17, v17, v18
	v_cvt_pk_bf16_f32 v18, v24, v21
	v_lshl_add_u64 v[20:21], s[74:75], 0, v[28:29]
	v_mul_f32_e32 v19, v19, v19
	v_lshl_add_u64 v[20:21], v[20:21], 0, v[140:141]
	v_cvt_pk_bf16_f32 v19, v22, v19
	s_waitcnt lgkmcnt(0)
	global_store_dwordx4 v[176:177], v[172:175], off nt
	ds_bpermute_b32 v178, v169, v16
	ds_bpermute_b32 v179, v169, v17
	ds_bpermute_b32 v180, v169, v18
	ds_bpermute_b32 v181, v169, v19
	v_lshl_add_u64 v[182:183], v[20:21], 0, v[170:171]
	v_add_u32_e32 v20, 0xb0, v162
	s_mov_b64 s[8:9], -1
	s_and_b64 vcc, exec, s[6:7]
	v_subrev_u32_e32 v17, s5, v20
	s_cbranch_vccz .LBB0_125
	v_ashrrev_i32_e32 v21, 31, v20
	v_lshlrev_b64 v[18:19], 6, v[20:21]
	v_lshl_add_u64 v[18:19], s[44:45], 0, v[18:19]
	v_mov_b32_e32 v161, v141
	v_lshl_add_u64 v[18:19], v[18:19], 0, v[160:161]
	global_load_dwordx4 v[22:25], v[18:19], off
	s_mov_b64 s[8:9], 0
	s_waitcnt vmcnt(0) lgkmcnt(0)
	v_mov_b32_e32 v18, v23
	v_mov_b32_e32 v19, v24
	v_mov_b32_e32 v23, v25
	v_pk_add_f32 v[18:19], v[18:19], v[22:23]
	s_nop 0
	v_add_f32_e32 v16, v18, v19
	v_mov_b32_e32 v18, v16
	s_nop 1
	v_permlane16_swap_b32_e32 v18, v16
	s_waitcnt lgkmcnt(0)
	v_add_f32_e32 v16, v16, v18
	v_mov_b32_e32 v18, v16
	s_nop 1
	v_permlane32_swap_b32_e32 v18, v16
	s_waitcnt lgkmcnt(0)
	v_add_f32_e32 v16, v16, v18
	v_fmamk_f32 v16, v16, 0x3a800000, v250
	v_rsq_f32_e32 v16, v16
	v_subrev_u32_e32 v18, s5, v20

.LBB0_150:
	s_mov_b32 s6, -1
	s_lshl_b32 s5, s5, 8
	v_mbcnt_lo_u32_b32 v128, s6, 0
	v_mbcnt_hi_u32_b32 v128, s6, v128
	s_getreg_b32 s6, hwreg(HW_REG_HW_ID, 0, 6)
	s_and_b32 s6, s6, 63
	s_lshl_b32 s6, s6, 2
	s_add_i32 s6, s6, 0
	s_add_i32 s6, s6, 0x20200
	v_mov_b32_e32 v129, s6
	ds_read_b32 v129, v129
	v_bfrev_b32_e32 v130, 0.5
	s_movk_i32 s84, 0x80
	s_lshl_b32 s74, s4, 2
	s_ashr_i32 s75, s74, 31
	s_waitcnt lgkmcnt(0)
	v_readfirstlane_b32 s6, v129
	s_nop 1
	v_lshl_add_u32 v128, s6, 6, v128
	s_nop 0
	v_readfirstlane_b32 s6, v128
	s_bfe_u32 s8, s6, 0x20006
	s_ashr_i32 s6, s6, 2
	s_andn2_b32 s6, s6, 63
	s_add_i32 s6, s6, s5
	v_and_or_b32 v170, v128, 15, s6
	s_lshl_b32 s5, s4, 8
	s_lshl_b32 s6, s8, 5
	v_bfe_u32 v129, v128, 4, 2
	s_or_b32 s5, s6, s5
	v_lshl_or_b32 v168, v129, 3, s5
	v_ashrrev_i32_e32 v169, 31, v168
	v_lshlrev_b64 v[146:147], 1, v[168:169]
	v_ashrrev_i32_e32 v171, 31, v170
	v_lshlrev_b32_e32 v128, 2, v128
	v_lshl_add_u64 v[172:173], s[68:69], 0, v[146:147]
	v_lshlrev_b64 v[148:149], 11, v[170:171]
	v_bitop3_b32 v180, v128, 64, v130 bitop3:0x6c
	v_bitop3_b32 v181, v128, s84, v130 bitop3:0x6c
	v_cmp_eq_u32_e32 vcc, 0, v129
	v_lshl_add_u64 v[128:129], v[172:173], 0, v[148:149]
	global_load_dwordx4 v[142:145], v[128:129], off
	global_load_dwordx4 v[136:139], v[128:129], off offset:256
	v_or_b32_e32 v174, 16, v170
	v_ashrrev_i32_e32 v175, 31, v174
	v_lshlrev_b64 v[176:177], 11, v[174:175]
	v_lshl_add_u64 v[128:129], v[172:173], 0, v[176:177]
	global_load_dwordx4 v[132:135], v[128:129], off
	s_nop 0
	global_load_dwordx4 v[128:131], v[128:129], off offset:256
	s_waitcnt vmcnt(0)
	v_lshlrev_b32_e32 v150, 16, v142
	v_and_b32_e32 v151, 0xffff0000, v142
	v_lshlrev_b32_e32 v142, 16, v143
	v_and_b32_e32 v143, 0xffff0000, v143
	v_lshlrev_b32_e32 v152, 16, v144
	v_and_b32_e32 v153, 0xffff0000, v144
	v_lshlrev_b32_e32 v144, 16, v145
	v_and_b32_e32 v145, 0xffff0000, v145
	v_pk_add_f32 v[124:125], v[124:125], v[150:151]
	v_pk_add_f32 v[126:127], v[126:127], v[142:143]
	v_pk_add_f32 v[142:143], v[122:123], v[144:145]
	v_pk_add_f32 v[122:123], v[120:121], v[152:153]
	v_cvt_pk_bf16_f32 v120, v124, v125
	v_lshl_add_u64 v[124:125], s[68:69], 0, v[148:149]
	v_lshl_add_u64 v[124:125], v[124:125], 0, v[146:147]
	v_cvt_pk_bf16_f32 v121, v126, v127
	v_cvt_pk_bf16_f32 v122, v122, v123
	v_cvt_pk_bf16_f32 v123, v142, v143
	global_store_dwordx4 v[124:125], v[120:123], off nt
	v_lshlrev_b32_e32 v126, 16, v120
	v_and_b32_e32 v127, 0xffff0000, v138
	v_and_b32_e32 v120, 0xffff0000, v120
	v_mul_f32_e32 v120, v120, v120
	v_fmac_f32_e32 v120, v126, v126
	v_lshlrev_b32_e32 v126, 16, v121
	v_and_b32_e32 v121, 0xffff0000, v121
	v_mul_f32_e32 v121, v121, v121
	v_fmac_f32_e32 v121, v126, v126
	v_add_f32_e32 v120, v120, v121
	v_lshlrev_b32_e32 v121, 16, v122
	v_and_b32_e32 v122, 0xffff0000, v122
	v_mul_f32_e32 v122, v122, v122
	v_fmac_f32_e32 v122, v121, v121
	v_add_f32_e32 v120, v120, v122
	v_and_b32_e32 v122, 0xffff0000, v123
	v_lshlrev_b32_e32 v121, 16, v123
	v_mul_f32_e32 v122, v122, v122
	v_fmac_f32_e32 v122, v121, v121
	v_add_f32_e32 v142, v120, v122
	v_lshlrev_b32_e32 v120, 16, v136
	v_and_b32_e32 v121, 0xffff0000, v136
	v_lshlrev_b32_e32 v122, 16, v137
	v_and_b32_e32 v123, 0xffff0000, v137
	v_lshlrev_b32_e32 v126, 16, v138
	v_lshlrev_b32_e32 v136, 16, v139
	v_and_b32_e32 v137, 0xffff0000, v139
	v_pk_add_f32 v[116:117], v[116:117], v[120:121]
	v_pk_add_f32 v[120:121], v[114:115], v[136:137]
	v_pk_add_f32 v[114:115], v[112:113], v[126:127]
	v_cvt_pk_bf16_f32 v112, v116, v117
	v_pk_add_f32 v[118:119], v[118:119], v[122:123]
	v_lshlrev_b32_e32 v116, 16, v112
	v_cvt_pk_bf16_f32 v113, v118, v119
	v_cvt_pk_bf16_f32 v114, v114, v115
	v_cvt_pk_bf16_f32 v115, v120, v121
	global_store_dwordx4 v[124:125], v[112:115], off offset:256 nt
	s_nop 1
	v_and_b32_e32 v112, 0xffff0000, v112
	v_mul_f32_e32 v112, v112, v112
	v_fmac_f32_e32 v112, v116, v116
	v_lshlrev_b32_e32 v116, 16, v113
	v_and_b32_e32 v113, 0xffff0000, v113
	v_mul_f32_e32 v113, v113, v113
	v_add_f32_e32 v112, v142, v112
	v_fmac_f32_e32 v113, v116, v116
	v_add_f32_e32 v112, v112, v113
	v_lshlrev_b32_e32 v113, 16, v114
	v_and_b32_e32 v114, 0xffff0000, v114
	v_mul_f32_e32 v114, v114, v114
	v_fmac_f32_e32 v114, v113, v113
	v_add_f32_e32 v112, v112, v114
	v_and_b32_e32 v114, 0xffff0000, v115
	v_lshlrev_b32_e32 v113, 16, v115
	v_mul_f32_e32 v114, v114, v114
	v_fmac_f32_e32 v114, v113, v113
	v_add_f32_e32 v112, v112, v114
	v_mov_b32_e32 v113, v112
	s_nop 1
	v_permlane16_swap_b32_e32 v113, v112
	s_waitcnt lgkmcnt(0)
	v_add_f32_e32 v112, v112, v113
	v_mov_b32_e32 v113, v112
	s_nop 1
	v_permlane32_swap_b32_e32 v113, v112
	s_and_saveexec_b64 s[6:7], vcc
	s_cbranch_execz .LBB0_152
	s_waitcnt lgkmcnt(0)
	v_add_f32_e32 v114, v112, v113
	v_lshlrev_b64 v[112:113], 6, v[170:171]
	v_lshl_add_u64 v[112:113], s[48:49], 0, v[112:113]
	v_lshl_add_u64 v[112:113], s[74:75], 2, v[112:113]
	s_lshl_b32 s38, s8, 2
	v_lshl_add_u64 v[112:113], v[112:113], 0, s[38:39]
	global_store_dword v[112:113], v114, off
.LBB0_152:
	s_or_b64 exec, exec, s[6:7]
	v_lshlrev_b32_e32 v112, 16, v132
	s_waitcnt lgkmcnt(0)
	v_and_b32_e32 v113, 0xffff0000, v132
	v_lshlrev_b32_e32 v116, 16, v134
	v_and_b32_e32 v117, 0xffff0000, v134
	v_lshlrev_b32_e32 v118, 16, v135
	v_and_b32_e32 v119, 0xffff0000, v135
	v_pk_add_f32 v[108:109], v[108:109], v[112:113]
	v_lshlrev_b32_e32 v114, 16, v133
	v_and_b32_e32 v115, 0xffff0000, v133
	v_pk_add_f32 v[112:113], v[106:107], v[118:119]
	v_pk_add_f32 v[106:107], v[104:105], v[116:117]
	v_cvt_pk_bf16_f32 v104, v108, v109
	v_lshl_add_u64 v[108:109], s[68:69], 0, v[176:177]
	v_pk_add_f32 v[110:111], v[110:111], v[114:115]
	v_lshl_add_u64 v[108:109], v[168:169], 1, v[108:109]
	v_cvt_pk_bf16_f32 v105, v110, v111
	v_cvt_pk_bf16_f32 v106, v106, v107
	v_cvt_pk_bf16_f32 v107, v112, v113
	global_store_dwordx4 v[108:109], v[104:107], off nt
	v_lshlrev_b32_e32 v110, 16, v104
	v_and_b32_e32 v111, 0xffff0000, v130
	v_and_b32_e32 v104, 0xffff0000, v104
	v_mul_f32_e32 v104, v104, v104
	v_fmac_f32_e32 v104, v110, v110
	v_lshlrev_b32_e32 v110, 16, v105
	v_and_b32_e32 v105, 0xffff0000, v105
	v_mul_f32_e32 v105, v105, v105
	v_fmac_f32_e32 v105, v110, v110
	v_add_f32_e32 v104, v104, v105
	v_lshlrev_b32_e32 v105, 16, v106
	v_and_b32_e32 v106, 0xffff0000, v106
	v_mul_f32_e32 v106, v106, v106
	v_fmac_f32_e32 v106, v105, v105
	v_add_f32_e32 v104, v104, v106
	v_and_b32_e32 v106, 0xffff0000, v107
	v_lshlrev_b32_e32 v105, 16, v107
	v_mul_f32_e32 v106, v106, v106
	v_fmac_f32_e32 v106, v105, v105
	v_add_f32_e32 v114, v104, v106
	v_lshlrev_b32_e32 v104, 16, v128
	v_and_b32_e32 v105, 0xffff0000, v128
	v_lshlrev_b32_e32 v110, 16, v130
	v_lshlrev_b32_e32 v106, 16, v129
	v_and_b32_e32 v107, 0xffff0000, v129
	v_lshlrev_b32_e32 v112, 16, v131
	v_and_b32_e32 v113, 0xffff0000, v131
	v_pk_add_f32 v[100:101], v[100:101], v[104:105]
	v_pk_add_f32 v[96:97], v[96:97], v[110:111]
	v_pk_add_f32 v[102:103], v[102:103], v[106:107]
	v_pk_add_f32 v[104:105], v[98:99], v[112:113]
	v_cvt_pk_bf16_f32 v98, v100, v101
	v_cvt_pk_bf16_f32 v99, v102, v103
	v_cvt_pk_bf16_f32 v100, v96, v97
	s_nop 0
	v_and_b32_e32 v97, 0xffff0000, v98
	v_lshlrev_b32_e32 v96, 16, v98
	v_mul_f32_e32 v97, v97, v97
	v_fmac_f32_e32 v97, v96, v96
	v_and_b32_e32 v102, 0xffff0000, v99
	v_add_f32_e32 v96, v114, v97
	v_lshlrev_b32_e32 v97, 16, v99
	v_mul_f32_e32 v102, v102, v102
	v_fmac_f32_e32 v102, v97, v97
	v_add_f32_e32 v96, v96, v102
	v_and_b32_e32 v102, 0xffff0000, v100
	v_lshlrev_b32_e32 v97, 16, v100
	v_mul_f32_e32 v102, v102, v102
	v_fmac_f32_e32 v102, v97, v97
	v_cvt_pk_bf16_f32 v101, v104, v105
	v_add_f32_e32 v96, v96, v102
	v_and_b32_e32 v102, 0xffff0000, v101
	v_lshlrev_b32_e32 v97, 16, v101
	v_mul_f32_e32 v102, v102, v102
	v_fmac_f32_e32 v102, v97, v97
	v_add_f32_e32 v96, v96, v102
	v_mov_b32_e32 v97, v96
	s_nop 1
	v_permlane16_swap_b32_e32 v97, v96
	global_store_dwordx4 v[108:109], v[98:101], off offset:256 nt
	s_waitcnt lgkmcnt(0)
	v_add_f32_e32 v96, v96, v97
	v_mov_b32_e32 v97, v96
	s_nop 1
	v_permlane32_swap_b32_e32 v97, v96
	s_and_saveexec_b64 s[6:7], vcc
	s_cbranch_execz .LBB0_154
	s_waitcnt lgkmcnt(0)
	v_add_f32_e32 v98, v96, v97
	v_lshlrev_b64 v[96:97], 6, v[174:175]
	v_lshl_add_u64 v[96:97], s[48:49], 0, v[96:97]
	v_lshl_add_u64 v[96:97], s[74:75], 2, v[96:97]
	s_lshl_b32 s38, s8, 2
	v_lshl_add_u64 v[96:97], v[96:97], 0, s[38:39]
	global_store_dword v[96:97], v98, off
.LBB0_154:
	s_or_b64 exec, exec, s[6:7]
	v_or_b32_e32 v112, 32, v170
	v_ashrrev_i32_e32 v113, 31, v112
	v_lshlrev_b64 v[118:119], 11, v[112:113]
	s_waitcnt lgkmcnt(0)
	v_lshl_add_u64 v[96:97], v[172:173], 0, v[118:119]
	global_load_dwordx4 v[114:117], v[96:97], off
	global_load_dwordx4 v[104:107], v[96:97], off offset:256
	v_or_b32_e32 v108, 48, v170
	v_ashrrev_i32_e32 v109, 31, v108
	v_lshlrev_b64 v[110:111], 11, v[108:109]
	v_lshl_add_u64 v[96:97], v[172:173], 0, v[110:111]
	global_load_dwordx4 v[100:103], v[96:97], off
	s_nop 0
	global_load_dwordx4 v[96:99], v[96:97], off offset:256
	s_waitcnt vmcnt(0)
	v_lshlrev_b32_e32 v120, 16, v114
	v_and_b32_e32 v121, 0xffff0000, v114
	v_lshlrev_b32_e32 v114, 16, v115
	v_and_b32_e32 v115, 0xffff0000, v115
	v_lshlrev_b32_e32 v122, 16, v116
	v_and_b32_e32 v123, 0xffff0000, v116
	v_lshlrev_b32_e32 v116, 16, v117
	v_and_b32_e32 v117, 0xffff0000, v117
	v_pk_add_f32 v[92:93], v[92:93], v[120:121]
	v_pk_add_f32 v[94:95], v[94:95], v[114:115]
	v_pk_add_f32 v[114:115], v[90:91], v[116:117]
	v_pk_add_f32 v[90:91], v[88:89], v[122:123]
	v_cvt_pk_bf16_f32 v88, v92, v93
	v_lshl_add_u64 v[92:93], s[68:69], 0, v[118:119]
	v_lshl_add_u64 v[92:93], v[168:169], 1, v[92:93]
	v_cvt_pk_bf16_f32 v89, v94, v95
	v_cvt_pk_bf16_f32 v90, v90, v91
	v_cvt_pk_bf16_f32 v91, v114, v115
	global_store_dwordx4 v[92:93], v[88:91], off nt
	v_lshlrev_b32_e32 v94, 16, v88
	v_and_b32_e32 v95, 0xffff0000, v106
	v_and_b32_e32 v88, 0xffff0000, v88
	v_mul_f32_e32 v88, v88, v88
	v_fmac_f32_e32 v88, v94, v94
	v_lshlrev_b32_e32 v94, 16, v89
	v_and_b32_e32 v89, 0xffff0000, v89
	v_mul_f32_e32 v89, v89, v89
	v_fmac_f32_e32 v89, v94, v94
	v_add_f32_e32 v88, v88, v89
	v_lshlrev_b32_e32 v89, 16, v90
	v_and_b32_e32 v90, 0xffff0000, v90
	v_mul_f32_e32 v90, v90, v90
	v_fmac_f32_e32 v90, v89, v89
	v_add_f32_e32 v88, v88, v90
	v_and_b32_e32 v90, 0xffff0000, v91
	v_lshlrev_b32_e32 v89, 16, v91
	v_mul_f32_e32 v90, v90, v90
	v_fmac_f32_e32 v90, v89, v89
	v_add_f32_e32 v114, v88, v90
	v_lshlrev_b32_e32 v88, 16, v104
	v_and_b32_e32 v89, 0xffff0000, v104
	v_lshlrev_b32_e32 v90, 16, v105
	v_and_b32_e32 v91, 0xffff0000, v105
	v_lshlrev_b32_e32 v94, 16, v106
	v_lshlrev_b32_e32 v104, 16, v107
	v_and_b32_e32 v105, 0xffff0000, v107
	v_pk_add_f32 v[84:85], v[84:85], v[88:89]
	v_pk_add_f32 v[88:89], v[82:83], v[104:105]
	v_pk_add_f32 v[82:83], v[80:81], v[94:95]
	v_cvt_pk_bf16_f32 v80, v84, v85
	v_pk_add_f32 v[86:87], v[86:87], v[90:91]
	v_lshlrev_b32_e32 v84, 16, v80
	v_cvt_pk_bf16_f32 v81, v86, v87
	v_cvt_pk_bf16_f32 v82, v82, v83
	v_cvt_pk_bf16_f32 v83, v88, v89
	global_store_dwordx4 v[92:93], v[80:83], off offset:256 nt
	s_nop 1
	v_and_b32_e32 v80, 0xffff0000, v80
	v_mul_f32_e32 v80, v80, v80
	v_fmac_f32_e32 v80, v84, v84
	v_lshlrev_b32_e32 v84, 16, v81
	v_and_b32_e32 v81, 0xffff0000, v81
	v_mul_f32_e32 v81, v81, v81
	v_add_f32_e32 v80, v114, v80
	v_fmac_f32_e32 v81, v84, v84
	v_add_f32_e32 v80, v80, v81
	v_lshlrev_b32_e32 v81, 16, v82
	v_and_b32_e32 v82, 0xffff0000, v82
	v_mul_f32_e32 v82, v82, v82
	v_fmac_f32_e32 v82, v81, v81
	v_add_f32_e32 v80, v80, v82
	v_and_b32_e32 v82, 0xffff0000, v83
	v_lshlrev_b32_e32 v81, 16, v83
	v_mul_f32_e32 v82, v82, v82
	v_fmac_f32_e32 v82, v81, v81
	v_add_f32_e32 v80, v80, v82
	v_mov_b32_e32 v81, v80
	s_nop 1
	v_permlane16_swap_b32_e32 v81, v80
	s_waitcnt lgkmcnt(0)
	v_add_f32_e32 v80, v80, v81
	v_mov_b32_e32 v81, v80
	s_nop 1
	v_permlane32_swap_b32_e32 v81, v80
	s_mov_b64 s[6:7], exec
	s_and_b64 s[4:5], s[6:7], vcc
	v_mov_b32_e32 v198, v216
	v_mov_b32_e32 v199, v217
	v_mov_b32_e32 v248, v218
	v_mov_b32_e32 v205, v219
	v_mov_b32_e32 v196, v220
	s_mov_b64 exec, s[4:5]
	s_cbranch_execz .LBB0_156
	s_waitcnt lgkmcnt(0)
	v_add_f32_e32 v82, v80, v81
	v_lshlrev_b64 v[80:81], 6, v[112:113]
	v_lshl_add_u64 v[80:81], s[48:49], 0, v[80:81]
	v_lshl_add_u64 v[80:81], s[74:75], 2, v[80:81]
	s_lshl_b32 s38, s8, 2
	v_lshl_add_u64 v[80:81], v[80:81], 0, s[38:39]
	global_store_dword v[80:81], v82, off
.LBB0_156:
	s_or_b64 exec, exec, s[6:7]
	v_lshlrev_b32_e32 v80, 16, v100
	s_waitcnt lgkmcnt(0)
	v_and_b32_e32 v81, 0xffff0000, v100
	v_lshlrev_b32_e32 v84, 16, v102
	v_and_b32_e32 v85, 0xffff0000, v102
	v_lshlrev_b32_e32 v86, 16, v103
	v_and_b32_e32 v87, 0xffff0000, v103
	v_pk_add_f32 v[76:77], v[76:77], v[80:81]
	v_lshlrev_b32_e32 v82, 16, v101
	v_and_b32_e32 v83, 0xffff0000, v101
	v_pk_add_f32 v[80:81], v[74:75], v[86:87]
	v_pk_add_f32 v[74:75], v[72:73], v[84:85]
	v_cvt_pk_bf16_f32 v72, v76, v77
	v_lshl_add_u64 v[76:77], s[68:69], 0, v[110:111]
	v_pk_add_f32 v[78:79], v[78:79], v[82:83]
	v_lshl_add_u64 v[76:77], v[168:169], 1, v[76:77]
	v_cvt_pk_bf16_f32 v73, v78, v79
	v_cvt_pk_bf16_f32 v74, v74, v75
	v_cvt_pk_bf16_f32 v75, v80, v81
	global_store_dwordx4 v[76:77], v[72:75], off nt
	v_lshlrev_b32_e32 v78, 16, v72
	v_and_b32_e32 v79, 0xffff0000, v98
	v_and_b32_e32 v72, 0xffff0000, v72
	v_mul_f32_e32 v72, v72, v72
	v_fmac_f32_e32 v72, v78, v78
	v_lshlrev_b32_e32 v78, 16, v73
	v_and_b32_e32 v73, 0xffff0000, v73
	v_mul_f32_e32 v73, v73, v73
	v_fmac_f32_e32 v73, v78, v78
	v_add_f32_e32 v72, v72, v73
	v_lshlrev_b32_e32 v73, 16, v74
	v_and_b32_e32 v74, 0xffff0000, v74
	v_mul_f32_e32 v74, v74, v74
	v_fmac_f32_e32 v74, v73, v73
	v_add_f32_e32 v72, v72, v74
	v_and_b32_e32 v74, 0xffff0000, v75
	v_lshlrev_b32_e32 v73, 16, v75
	v_mul_f32_e32 v74, v74, v74
	v_fmac_f32_e32 v74, v73, v73
	v_add_f32_e32 v82, v72, v74
	v_lshlrev_b32_e32 v72, 16, v96
	v_and_b32_e32 v73, 0xffff0000, v96
	v_lshlrev_b32_e32 v78, 16, v98
	v_lshlrev_b32_e32 v74, 16, v97
	v_and_b32_e32 v75, 0xffff0000, v97
	v_lshlrev_b32_e32 v80, 16, v99
	v_and_b32_e32 v81, 0xffff0000, v99
	v_pk_add_f32 v[68:69], v[68:69], v[72:73]
	v_pk_add_f32 v[64:65], v[64:65], v[78:79]
	v_pk_add_f32 v[70:71], v[70:71], v[74:75]
	v_pk_add_f32 v[72:73], v[66:67], v[80:81]
	v_cvt_pk_bf16_f32 v66, v68, v69
	v_cvt_pk_bf16_f32 v67, v70, v71
	v_cvt_pk_bf16_f32 v68, v64, v65
	s_nop 0
	v_and_b32_e32 v65, 0xffff0000, v66
	v_lshlrev_b32_e32 v64, 16, v66
	v_mul_f32_e32 v65, v65, v65
	v_fmac_f32_e32 v65, v64, v64
	v_and_b32_e32 v70, 0xffff0000, v67
	v_add_f32_e32 v64, v82, v65
	v_lshlrev_b32_e32 v65, 16, v67
	v_mul_f32_e32 v70, v70, v70
	v_fmac_f32_e32 v70, v65, v65
	v_add_f32_e32 v64, v64, v70
	v_and_b32_e32 v70, 0xffff0000, v68
	v_lshlrev_b32_e32 v65, 16, v68
	v_mul_f32_e32 v70, v70, v70
	v_fmac_f32_e32 v70, v65, v65
	v_cvt_pk_bf16_f32 v69, v72, v73
	v_add_f32_e32 v64, v64, v70
	v_and_b32_e32 v70, 0xffff0000, v69
	v_lshlrev_b32_e32 v65, 16, v69
	v_mul_f32_e32 v70, v70, v70
	v_fmac_f32_e32 v70, v65, v65
	v_add_f32_e32 v64, v64, v70
	v_mov_b32_e32 v65, v64
	s_nop 1
	v_permlane16_swap_b32_e32 v65, v64
	global_store_dwordx4 v[76:77], v[66:69], off offset:256 nt
	s_waitcnt lgkmcnt(0)
	v_add_f32_e32 v64, v64, v65
	v_mov_b32_e32 v65, v64
	s_nop 1
	v_permlane32_swap_b32_e32 v65, v64
	s_and_saveexec_b64 s[6:7], vcc
	s_cbranch_execz .LBB0_158
	s_waitcnt lgkmcnt(0)
	v_add_f32_e32 v66, v64, v65
	v_lshlrev_b64 v[64:65], 6, v[108:109]
	v_lshl_add_u64 v[64:65], s[48:49], 0, v[64:65]
	v_lshl_add_u64 v[64:65], s[74:75], 2, v[64:65]
	s_lshl_b32 s38, s8, 2
	v_lshl_add_u64 v[64:65], v[64:65], 0, s[38:39]
	global_store_dword v[64:65], v66, off
.LBB0_158:
	s_or_b64 exec, exec, s[6:7]
	v_add_u32_e32 v80, 0x80, v170
	v_ashrrev_i32_e32 v81, 31, v80
	v_lshlrev_b64 v[86:87], 11, v[80:81]
	s_waitcnt lgkmcnt(0)
	v_lshl_add_u64 v[64:65], v[172:173], 0, v[86:87]
	global_load_dwordx4 v[82:85], v[64:65], off
	global_load_dwordx4 v[72:75], v[64:65], off offset:256
	v_add_u32_e32 v76, 0x90, v170
	v_ashrrev_i32_e32 v77, 31, v76
	v_lshlrev_b64 v[78:79], 11, v[76:77]
	v_lshl_add_u64 v[64:65], v[172:173], 0, v[78:79]
	global_load_dwordx4 v[68:71], v[64:65], off
	s_nop 0
	global_load_dwordx4 v[64:67], v[64:65], off offset:256
	s_waitcnt vmcnt(0)
	v_lshlrev_b32_e32 v88, 16, v82
	v_and_b32_e32 v89, 0xffff0000, v82
	v_lshlrev_b32_e32 v82, 16, v83
	v_and_b32_e32 v83, 0xffff0000, v83
	v_lshlrev_b32_e32 v90, 16, v84
	v_and_b32_e32 v91, 0xffff0000, v84
	v_lshlrev_b32_e32 v84, 16, v85
	v_and_b32_e32 v85, 0xffff0000, v85
	v_pk_add_f32 v[60:61], v[60:61], v[88:89]
	v_pk_add_f32 v[62:63], v[62:63], v[82:83]
	v_pk_add_f32 v[82:83], v[58:59], v[84:85]
	v_pk_add_f32 v[58:59], v[56:57], v[90:91]
	v_cvt_pk_bf16_f32 v56, v60, v61
	v_lshl_add_u64 v[60:61], s[68:69], 0, v[86:87]
	v_lshl_add_u64 v[60:61], v[168:169], 1, v[60:61]
	v_cvt_pk_bf16_f32 v57, v62, v63
	v_cvt_pk_bf16_f32 v58, v58, v59
	v_cvt_pk_bf16_f32 v59, v82, v83
	global_store_dwordx4 v[60:61], v[56:59], off nt
	v_lshlrev_b32_e32 v62, 16, v56
	v_and_b32_e32 v63, 0xffff0000, v74
	v_and_b32_e32 v56, 0xffff0000, v56
	v_mul_f32_e32 v56, v56, v56
	v_fmac_f32_e32 v56, v62, v62
	v_lshlrev_b32_e32 v62, 16, v57
	v_and_b32_e32 v57, 0xffff0000, v57
	v_mul_f32_e32 v57, v57, v57
	v_fmac_f32_e32 v57, v62, v62
	v_add_f32_e32 v56, v56, v57
	v_lshlrev_b32_e32 v57, 16, v58
	v_and_b32_e32 v58, 0xffff0000, v58
	v_mul_f32_e32 v58, v58, v58
	v_fmac_f32_e32 v58, v57, v57
	v_add_f32_e32 v56, v56, v58
	v_and_b32_e32 v58, 0xffff0000, v59
	v_lshlrev_b32_e32 v57, 16, v59
	v_mul_f32_e32 v58, v58, v58
	v_fmac_f32_e32 v58, v57, v57
	v_add_f32_e32 v82, v56, v58
	v_lshlrev_b32_e32 v56, 16, v72
	v_and_b32_e32 v57, 0xffff0000, v72
	v_lshlrev_b32_e32 v58, 16, v73
	v_and_b32_e32 v59, 0xffff0000, v73
	v_lshlrev_b32_e32 v62, 16, v74
	v_lshlrev_b32_e32 v72, 16, v75
	v_and_b32_e32 v73, 0xffff0000, v75
	v_pk_add_f32 v[52:53], v[52:53], v[56:57]
	v_pk_add_f32 v[56:57], v[50:51], v[72:73]
	v_pk_add_f32 v[50:51], v[48:49], v[62:63]
	v_cvt_pk_bf16_f32 v48, v52, v53
	v_pk_add_f32 v[54:55], v[54:55], v[58:59]
	v_lshlrev_b32_e32 v52, 16, v48
	v_cvt_pk_bf16_f32 v49, v54, v55
	v_cvt_pk_bf16_f32 v50, v50, v51
	v_cvt_pk_bf16_f32 v51, v56, v57
	global_store_dwordx4 v[60:61], v[48:51], off offset:256 nt
	s_nop 1
	v_and_b32_e32 v48, 0xffff0000, v48
	v_mul_f32_e32 v48, v48, v48
	v_fmac_f32_e32 v48, v52, v52
	v_lshlrev_b32_e32 v52, 16, v49
	v_and_b32_e32 v49, 0xffff0000, v49
	v_mul_f32_e32 v49, v49, v49
	v_add_f32_e32 v48, v82, v48
	v_fmac_f32_e32 v49, v52, v52
	v_add_f32_e32 v48, v48, v49
	v_lshlrev_b32_e32 v49, 16, v50
	v_and_b32_e32 v50, 0xffff0000, v50
	v_mul_f32_e32 v50, v50, v50
	v_fmac_f32_e32 v50, v49, v49
	v_add_f32_e32 v48, v48, v50
	v_and_b32_e32 v50, 0xffff0000, v51
	v_lshlrev_b32_e32 v49, 16, v51
	v_mul_f32_e32 v50, v50, v50
	v_fmac_f32_e32 v50, v49, v49
	v_add_f32_e32 v48, v48, v50
	v_mov_b32_e32 v49, v48
	s_nop 1
	v_permlane16_swap_b32_e32 v49, v48
	s_waitcnt lgkmcnt(0)
	v_add_f32_e32 v48, v48, v49
	v_mov_b32_e32 v49, v48
	s_nop 1
	v_permlane32_swap_b32_e32 v49, v48
	s_and_saveexec_b64 s[6:7], vcc
	s_cbranch_execz .LBB0_160
	s_waitcnt lgkmcnt(0)
	v_add_f32_e32 v50, v48, v49
	v_lshlrev_b64 v[48:49], 6, v[80:81]
	v_lshl_add_u64 v[48:49], s[48:49], 0, v[48:49]
	v_lshl_add_u64 v[48:49], s[74:75], 2, v[48:49]
	s_lshl_b32 s38, s8, 2
	v_lshl_add_u64 v[48:49], v[48:49], 0, s[38:39]
	global_store_dword v[48:49], v50, off
.LBB0_160:
	s_or_b64 exec, exec, s[6:7]
	v_lshlrev_b32_e32 v48, 16, v68
	s_waitcnt lgkmcnt(0)
	v_and_b32_e32 v49, 0xffff0000, v68
	v_lshlrev_b32_e32 v52, 16, v70
	v_and_b32_e32 v53, 0xffff0000, v70
	v_lshlrev_b32_e32 v54, 16, v71
	v_and_b32_e32 v55, 0xffff0000, v71
	v_pk_add_f32 v[44:45], v[44:45], v[48:49]
	v_lshlrev_b32_e32 v50, 16, v69
	v_and_b32_e32 v51, 0xffff0000, v69
	v_pk_add_f32 v[48:49], v[42:43], v[54:55]
	v_pk_add_f32 v[42:43], v[40:41], v[52:53]
	v_cvt_pk_bf16_f32 v40, v44, v45
	v_lshl_add_u64 v[44:45], s[68:69], 0, v[78:79]
	v_pk_add_f32 v[46:47], v[46:47], v[50:51]
	v_lshl_add_u64 v[44:45], v[168:169], 1, v[44:45]
	v_cvt_pk_bf16_f32 v41, v46, v47
	v_cvt_pk_bf16_f32 v42, v42, v43
	v_cvt_pk_bf16_f32 v43, v48, v49
	global_store_dwordx4 v[44:45], v[40:43], off nt
	v_lshlrev_b32_e32 v46, 16, v40
	v_and_b32_e32 v47, 0xffff0000, v66
	v_and_b32_e32 v40, 0xffff0000, v40
	v_mul_f32_e32 v40, v40, v40
	v_fmac_f32_e32 v40, v46, v46
	v_lshlrev_b32_e32 v46, 16, v41
	v_and_b32_e32 v41, 0xffff0000, v41
	v_mul_f32_e32 v41, v41, v41
	v_fmac_f32_e32 v41, v46, v46
	v_add_f32_e32 v40, v40, v41
	v_lshlrev_b32_e32 v41, 16, v42
	v_and_b32_e32 v42, 0xffff0000, v42
	v_mul_f32_e32 v42, v42, v42
	v_fmac_f32_e32 v42, v41, v41
	v_add_f32_e32 v40, v40, v42
	v_and_b32_e32 v42, 0xffff0000, v43
	v_lshlrev_b32_e32 v41, 16, v43
	v_mul_f32_e32 v42, v42, v42
	v_fmac_f32_e32 v42, v41, v41
	v_add_f32_e32 v50, v40, v42
	v_lshlrev_b32_e32 v40, 16, v64
	v_and_b32_e32 v41, 0xffff0000, v64
	v_lshlrev_b32_e32 v46, 16, v66
	v_lshlrev_b32_e32 v42, 16, v65
	v_and_b32_e32 v43, 0xffff0000, v65
	v_lshlrev_b32_e32 v48, 16, v67
	v_and_b32_e32 v49, 0xffff0000, v67
	v_pk_add_f32 v[36:37], v[36:37], v[40:41]
	v_pk_add_f32 v[32:33], v[32:33], v[46:47]
	v_pk_add_f32 v[38:39], v[38:39], v[42:43]
	v_pk_add_f32 v[40:41], v[34:35], v[48:49]
	v_cvt_pk_bf16_f32 v34, v36, v37
	v_cvt_pk_bf16_f32 v35, v38, v39
	v_cvt_pk_bf16_f32 v36, v32, v33
	s_nop 0
	v_and_b32_e32 v33, 0xffff0000, v34
	v_lshlrev_b32_e32 v32, 16, v34
	v_mul_f32_e32 v33, v33, v33
	v_fmac_f32_e32 v33, v32, v32
	v_and_b32_e32 v38, 0xffff0000, v35
	v_add_f32_e32 v32, v50, v33
	v_lshlrev_b32_e32 v33, 16, v35
	v_mul_f32_e32 v38, v38, v38
	v_fmac_f32_e32 v38, v33, v33
	v_add_f32_e32 v32, v32, v38
	v_and_b32_e32 v38, 0xffff0000, v36
	v_lshlrev_b32_e32 v33, 16, v36
	v_mul_f32_e32 v38, v38, v38
	v_fmac_f32_e32 v38, v33, v33
	v_cvt_pk_bf16_f32 v37, v40, v41
	v_add_f32_e32 v32, v32, v38
	v_and_b32_e32 v38, 0xffff0000, v37
	v_lshlrev_b32_e32 v33, 16, v37
	v_mul_f32_e32 v38, v38, v38
	v_fmac_f32_e32 v38, v33, v33
	v_add_f32_e32 v32, v32, v38
	v_mov_b32_e32 v33, v32
	s_nop 1
	v_permlane16_swap_b32_e32 v33, v32
	global_store_dwordx4 v[44:45], v[34:37], off offset:256 nt
	s_waitcnt lgkmcnt(0)
	v_add_f32_e32 v32, v32, v33
	v_mov_b32_e32 v33, v32
	s_nop 1
	v_permlane32_swap_b32_e32 v33, v32
	s_and_saveexec_b64 s[6:7], vcc
	s_cbranch_execz .LBB0_162
	s_waitcnt lgkmcnt(0)
	v_add_f32_e32 v34, v32, v33
	v_lshlrev_b64 v[32:33], 6, v[76:77]
	v_lshl_add_u64 v[32:33], s[48:49], 0, v[32:33]
	v_lshl_add_u64 v[32:33], s[74:75], 2, v[32:33]
	s_lshl_b32 s38, s8, 2
	v_lshl_add_u64 v[32:33], v[32:33], 0, s[38:39]
	global_store_dword v[32:33], v34, off
.LBB0_162:
	s_or_b64 exec, exec, s[6:7]
	v_add_u32_e32 v48, 0xa0, v170
	v_ashrrev_i32_e32 v49, 31, v48
	v_lshlrev_b64 v[54:55], 11, v[48:49]
	s_waitcnt lgkmcnt(0)
	v_lshl_add_u64 v[32:33], v[172:173], 0, v[54:55]
	global_load_dwordx4 v[50:53], v[32:33], off
	global_load_dwordx4 v[40:43], v[32:33], off offset:256
	v_add_u32_e32 v44, 0xb0, v170
	v_ashrrev_i32_e32 v45, 31, v44
	v_lshlrev_b64 v[46:47], 11, v[44:45]
	v_lshl_add_u64 v[32:33], v[172:173], 0, v[46:47]
	global_load_dwordx4 v[36:39], v[32:33], off
	s_nop 0
	global_load_dwordx4 v[32:35], v[32:33], off offset:256
	s_waitcnt vmcnt(0)
	v_lshlrev_b32_e32 v56, 16, v50
	v_and_b32_e32 v57, 0xffff0000, v50
	v_lshlrev_b32_e32 v50, 16, v51
	v_and_b32_e32 v51, 0xffff0000, v51
	v_lshlrev_b32_e32 v58, 16, v52
	v_and_b32_e32 v59, 0xffff0000, v52
	v_lshlrev_b32_e32 v52, 16, v53
	v_and_b32_e32 v53, 0xffff0000, v53
	v_pk_add_f32 v[28:29], v[28:29], v[56:57]
	v_pk_add_f32 v[30:31], v[30:31], v[50:51]
	v_pk_add_f32 v[50:51], v[26:27], v[52:53]
	v_pk_add_f32 v[26:27], v[24:25], v[58:59]
	v_cvt_pk_bf16_f32 v24, v28, v29
	v_lshl_add_u64 v[28:29], s[68:69], 0, v[54:55]
	v_lshl_add_u64 v[28:29], v[168:169], 1, v[28:29]
	v_cvt_pk_bf16_f32 v25, v30, v31
	v_cvt_pk_bf16_f32 v26, v26, v27
	v_cvt_pk_bf16_f32 v27, v50, v51
	global_store_dwordx4 v[28:29], v[24:27], off nt
	v_lshlrev_b32_e32 v30, 16, v24
	v_and_b32_e32 v31, 0xffff0000, v42
	v_and_b32_e32 v24, 0xffff0000, v24
	v_mul_f32_e32 v24, v24, v24
	v_fmac_f32_e32 v24, v30, v30
	v_lshlrev_b32_e32 v30, 16, v25
	v_and_b32_e32 v25, 0xffff0000, v25
	v_mul_f32_e32 v25, v25, v25
	v_fmac_f32_e32 v25, v30, v30
	v_add_f32_e32 v24, v24, v25
	v_lshlrev_b32_e32 v25, 16, v26
	v_and_b32_e32 v26, 0xffff0000, v26
	v_mul_f32_e32 v26, v26, v26
	v_fmac_f32_e32 v26, v25, v25
	v_add_f32_e32 v24, v24, v26
	v_and_b32_e32 v26, 0xffff0000, v27
	v_lshlrev_b32_e32 v25, 16, v27
	v_mul_f32_e32 v26, v26, v26
	v_fmac_f32_e32 v26, v25, v25
	v_add_f32_e32 v50, v24, v26
	v_lshlrev_b32_e32 v24, 16, v40
	v_and_b32_e32 v25, 0xffff0000, v40
	v_lshlrev_b32_e32 v26, 16, v41
	v_and_b32_e32 v27, 0xffff0000, v41
	v_lshlrev_b32_e32 v30, 16, v42
	v_lshlrev_b32_e32 v40, 16, v43
	v_and_b32_e32 v41, 0xffff0000, v43
	v_pk_add_f32 v[20:21], v[20:21], v[24:25]
	v_pk_add_f32 v[24:25], v[18:19], v[40:41]
	v_pk_add_f32 v[18:19], v[16:17], v[30:31]
	v_cvt_pk_bf16_f32 v16, v20, v21
	v_pk_add_f32 v[22:23], v[22:23], v[26:27]
	v_lshlrev_b32_e32 v20, 16, v16
	v_cvt_pk_bf16_f32 v17, v22, v23
	v_cvt_pk_bf16_f32 v18, v18, v19
	v_cvt_pk_bf16_f32 v19, v24, v25
	global_store_dwordx4 v[28:29], v[16:19], off offset:256 nt
	s_nop 1
	v_and_b32_e32 v16, 0xffff0000, v16
	v_mul_f32_e32 v16, v16, v16
	v_fmac_f32_e32 v16, v20, v20
	v_lshlrev_b32_e32 v20, 16, v17
	v_and_b32_e32 v17, 0xffff0000, v17
	v_mul_f32_e32 v17, v17, v17
	v_add_f32_e32 v16, v50, v16
	v_fmac_f32_e32 v17, v20, v20
	v_add_f32_e32 v16, v16, v17
	v_lshlrev_b32_e32 v17, 16, v18
	v_and_b32_e32 v18, 0xffff0000, v18
	v_mul_f32_e32 v18, v18, v18
	v_fmac_f32_e32 v18, v17, v17
	v_add_f32_e32 v16, v16, v18
	v_and_b32_e32 v18, 0xffff0000, v19
	v_lshlrev_b32_e32 v17, 16, v19
	v_mul_f32_e32 v18, v18, v18
	v_fmac_f32_e32 v18, v17, v17
	v_add_f32_e32 v16, v16, v18
	v_mov_b32_e32 v17, v16
	s_nop 1
	v_permlane16_swap_b32_e32 v17, v16
	s_waitcnt lgkmcnt(0)
	v_add_f32_e32 v16, v16, v17
	v_mov_b32_e32 v17, v16
	s_nop 1
	v_permlane32_swap_b32_e32 v17, v16
	s_and_saveexec_b64 s[6:7], vcc
	s_cbranch_execz .LBB0_164
	s_waitcnt lgkmcnt(0)
	v_add_f32_e32 v18, v16, v17
	v_lshlrev_b64 v[16:17], 6, v[48:49]
	v_lshl_add_u64 v[16:17], s[48:49], 0, v[16:17]
	v_lshl_add_u64 v[16:17], s[74:75], 2, v[16:17]
	s_lshl_b32 s38, s8, 2
	v_lshl_add_u64 v[16:17], v[16:17], 0, s[38:39]
	global_store_dword v[16:17], v18, off
.LBB0_164:
	s_or_b64 exec, exec, s[6:7]
	v_lshlrev_b32_e32 v16, 16, v36
	s_waitcnt lgkmcnt(0)
	v_and_b32_e32 v17, 0xffff0000, v36
	v_lshlrev_b32_e32 v20, 16, v38
	v_and_b32_e32 v21, 0xffff0000, v38
	v_lshlrev_b32_e32 v22, 16, v39
	v_and_b32_e32 v23, 0xffff0000, v39
	v_pk_add_f32 v[12:13], v[12:13], v[16:17]
	v_lshlrev_b32_e32 v18, 16, v37
	v_and_b32_e32 v19, 0xffff0000, v37
	v_pk_add_f32 v[16:17], v[10:11], v[22:23]
	v_pk_add_f32 v[10:11], v[8:9], v[20:21]
	v_cvt_pk_bf16_f32 v8, v12, v13
	v_lshl_add_u64 v[12:13], s[68:69], 0, v[46:47]
	v_pk_add_f32 v[14:15], v[14:15], v[18:19]
	v_lshl_add_u64 v[12:13], v[168:169], 1, v[12:13]
	v_cvt_pk_bf16_f32 v9, v14, v15
	v_cvt_pk_bf16_f32 v10, v10, v11
	v_cvt_pk_bf16_f32 v11, v16, v17
	global_store_dwordx4 v[12:13], v[8:11], off nt
	v_lshlrev_b32_e32 v14, 16, v8
	v_and_b32_e32 v15, 0xffff0000, v34
	v_and_b32_e32 v8, 0xffff0000, v8
	v_mul_f32_e32 v8, v8, v8
	v_fmac_f32_e32 v8, v14, v14
	v_lshlrev_b32_e32 v14, 16, v9
	v_and_b32_e32 v9, 0xffff0000, v9
	v_mul_f32_e32 v9, v9, v9
	v_fmac_f32_e32 v9, v14, v14
	v_add_f32_e32 v8, v8, v9
	v_lshlrev_b32_e32 v9, 16, v10
	v_and_b32_e32 v10, 0xffff0000, v10
	v_mul_f32_e32 v10, v10, v10
	v_fmac_f32_e32 v10, v9, v9
	v_add_f32_e32 v8, v8, v10
	v_and_b32_e32 v10, 0xffff0000, v11
	v_lshlrev_b32_e32 v9, 16, v11
	v_mul_f32_e32 v10, v10, v10
	v_fmac_f32_e32 v10, v9, v9
	v_add_f32_e32 v18, v8, v10
	v_lshlrev_b32_e32 v8, 16, v32
	v_and_b32_e32 v9, 0xffff0000, v32
	v_lshlrev_b32_e32 v14, 16, v34
	v_lshlrev_b32_e32 v10, 16, v33
	v_and_b32_e32 v11, 0xffff0000, v33
	v_lshlrev_b32_e32 v16, 16, v35
	v_and_b32_e32 v17, 0xffff0000, v35
	v_pk_add_f32 v[4:5], v[4:5], v[8:9]
	v_pk_add_f32 v[0:1], v[0:1], v[14:15]
	v_pk_add_f32 v[6:7], v[6:7], v[10:11]
	v_pk_add_f32 v[8:9], v[2:3], v[16:17]
	v_cvt_pk_bf16_f32 v2, v4, v5
	v_cvt_pk_bf16_f32 v3, v6, v7
	v_cvt_pk_bf16_f32 v4, v0, v1
	s_nop 0
	v_and_b32_e32 v1, 0xffff0000, v2
	v_lshlrev_b32_e32 v0, 16, v2
	v_mul_f32_e32 v1, v1, v1
	v_fmac_f32_e32 v1, v0, v0
	v_and_b32_e32 v6, 0xffff0000, v3
	v_add_f32_e32 v0, v18, v1
	v_lshlrev_b32_e32 v1, 16, v3
	v_mul_f32_e32 v6, v6, v6
	v_fmac_f32_e32 v6, v1, v1
	v_add_f32_e32 v0, v0, v6
	v_and_b32_e32 v6, 0xffff0000, v4
	v_lshlrev_b32_e32 v1, 16, v4
	v_mul_f32_e32 v6, v6, v6
	v_fmac_f32_e32 v6, v1, v1
	v_cvt_pk_bf16_f32 v5, v8, v9
	v_add_f32_e32 v0, v0, v6
	v_and_b32_e32 v6, 0xffff0000, v5
	v_lshlrev_b32_e32 v1, 16, v5
	v_mul_f32_e32 v6, v6, v6
	v_fmac_f32_e32 v6, v1, v1
	v_add_f32_e32 v0, v0, v6
	v_mov_b32_e32 v1, v0
	s_nop 1
	v_permlane16_swap_b32_e32 v1, v0
	global_store_dwordx4 v[12:13], v[2:5], off offset:256 nt
	s_waitcnt lgkmcnt(0)
	v_add_f32_e32 v0, v0, v1
	v_mov_b32_e32 v1, v0
	s_nop 1
	v_permlane32_swap_b32_e32 v1, v0
	s_and_saveexec_b64 s[6:7], vcc
	s_cbranch_execz .LBB0_166
	s_waitcnt lgkmcnt(0)
	v_add_f32_e32 v2, v0, v1
	v_lshlrev_b64 v[0:1], 6, v[44:45]
	v_lshl_add_u64 v[0:1], s[48:49], 0, v[0:1]
	v_lshl_add_u64 v[0:1], s[74:75], 2, v[0:1]
	s_lshl_b32 s38, s8, 2
	v_lshl_add_u64 v[0:1], v[0:1], 0, s[38:39]
	global_store_dword v[0:1], v2, off

.LBB0_207:
	s_or_b64 exec, exec, s[8:9]
	s_bitcmp1_b32 s14, 3
	v_readlane_b32 s2, v255, 29
	s_cselect_b32 s44, s2, s66
	v_and_b32_e32 v3, 0xff, v0
	v_readlane_b32 s2, v255, 13
	v_readlane_b32 s3, v255, 30
	s_cselect_b32 s45, s3, s67
	v_lshl_add_u32 v1, v3, 2, s2
	v_cmp_lt_i32_e32 vcc, -1, v4
	v_lshl_add_u32 v1, v2, 10, v1
	s_and_saveexec_b64 s[6:7], vcc
	s_cbranch_execz .LBB0_209
	v_lshl_or_b32 v140, v4, 8, v3
	v_lshlrev_b64 v[4:5], 6, v[140:141]
	v_lshl_add_u64 v[16:17], s[44:45], 0, v[4:5]
	global_load_dwordx4 v[4:7], v[16:17], off
	global_load_dwordx4 v[8:11], v[16:17], off offset:32
	global_load_dwordx4 v[12:15], v[16:17], off offset:16
	s_nop 0
	global_load_dwordx4 v[16:19], v[16:17], off offset:48
	s_waitcnt vmcnt(0) lgkmcnt(0)
	v_mov_b32_e32 v20, v4
	v_mov_b32_e32 v21, v8
	v_mov_b32_e32 v8, v5
	v_mov_b32_e32 v4, v6
	v_mov_b32_e32 v5, v10
	v_mov_b32_e32 v10, v7
	v_mov_b32_e32 v6, v12
	v_mov_b32_e32 v7, v16
	v_mov_b32_e32 v16, v13
	v_mov_b32_e32 v12, v14
	v_mov_b32_e32 v13, v18
	v_mov_b32_e32 v18, v15
	v_pk_add_f32 v[8:9], v[20:21], v[8:9]
	v_pk_add_f32 v[4:5], v[4:5], v[10:11]
	v_pk_add_f32 v[6:7], v[6:7], v[16:17]
	v_pk_add_f32 v[10:11], v[12:13], v[18:19]
	v_pk_add_f32 v[4:5], v[8:9], v[4:5]
	v_pk_add_f32 v[6:7], v[6:7], v[10:11]
	s_nop 0
	v_pk_add_f32 v[4:5], v[4:5], v[6:7]
	s_nop 0
	v_add_f32_e32 v4, v4, v5
	v_fmamk_f32 v4, v4, 0x3a800000, v250
	v_rsq_f32_e32 v4, v4
	ds_write_b32 v1, v4

.LBB0_237:
	s_mov_b32 s4, -1
	s_getreg_b32 s5, hwreg(HW_REG_HW_ID, 0, 6)
	s_and_b32 s5, s5, 63
	s_lshl_b32 s5, s5, 2
	s_add_i32 s5, s5, 0
	s_add_i32 s5, s5, 0x20200
	v_mov_b32_e32 v140, s5
	ds_read_b32 v140, v140
	v_mbcnt_lo_u32_b32 v142, s4, 0
	v_mbcnt_hi_u32_b32 v142, s4, v142
	s_mov_b64 s[8:9], -1
	s_waitcnt lgkmcnt(0)
	v_readfirstlane_b32 s4, v140
	s_nop 1
	v_lshl_add_u32 v140, s4, 6, v142
	v_bfrev_b32_e32 v142, 0.5
	v_readfirstlane_b32 s4, v140
	s_ashr_i32 s5, s4, 2
	s_andn2_b32 s5, s5, 63
	v_bfe_u32 v208, v140, 4, 2
	v_and_or_b32 v172, v140, 15, s5
	v_lshlrev_b32_e32 v140, 2, v140
	s_cmp_gt_u32 s58, 3
	v_bitop3_b32 v211, v140, 64, v142 bitop3:0x6c
	v_bitop3_b32 v210, v140, s84, v142 bitop3:0x6c
	v_lshlrev_b32_e32 v140, 2, v208
	s_cselect_b64 s[6:7], -1, 0
	s_and_b64 vcc, exec, s[6:7]
	v_lshl_add_u32 v158, s74, 8, v172
	v_lshlrev_b32_e32 v140, 2, v140
	s_cbranch_vccz .LBB0_239
	v_ashrrev_i32_e32 v159, 31, v158
	v_lshlrev_b64 v[142:143], 6, v[158:159]
	v_lshl_add_u64 v[142:143], s[44:45], 0, v[142:143]
	v_lshl_add_u64 v[142:143], v[142:143], 0, v[140:141]
	global_load_dwordx4 v[142:145], v[142:143], off
	s_mov_b64 s[8:9], 0
	s_waitcnt vmcnt(0) lgkmcnt(0)
	v_mov_b32_e32 v146, v143
	v_mov_b32_e32 v147, v144
	v_mov_b32_e32 v143, v145
	v_pk_add_f32 v[142:143], v[146:147], v[142:143]
	s_nop 0
	v_add_f32_e32 v142, v142, v143
	v_mov_b32_e32 v143, v142
	s_nop 1
	v_permlane16_swap_b32_e32 v143, v142
	s_waitcnt lgkmcnt(0)
	v_add_f32_e32 v142, v142, v143
	v_mov_b32_e32 v143, v142
	s_nop 1
	v_permlane32_swap_b32_e32 v143, v142
	s_waitcnt lgkmcnt(0)
	v_add_f32_e32 v142, v142, v143
	v_fmamk_f32 v142, v142, 0x3a800000, v250
	v_rsq_f32_e32 v160, v142

.LBB0_243:
	s_or_b64 exec, exec, s[8:9]
	v_or_b32_e32 v209, 16, v172
	s_mov_b64 s[8:9], -1
	s_and_b64 vcc, exec, s[6:7]
	s_cbranch_vccz .LBB0_245
	v_lshl_add_u32 v142, s74, 8, v209
	v_ashrrev_i32_e32 v143, 31, v142
	v_lshlrev_b64 v[142:143], 6, v[142:143]
	v_lshl_add_u64 v[142:143], s[44:45], 0, v[142:143]
	v_lshl_add_u64 v[142:143], v[142:143], 0, v[140:141]
	global_load_dwordx4 v[142:145], v[142:143], off
	s_mov_b64 s[8:9], 0
	s_waitcnt vmcnt(0) lgkmcnt(0)
	v_mov_b32_e32 v146, v143
	v_mov_b32_e32 v147, v144
	v_mov_b32_e32 v143, v145
	v_pk_add_f32 v[142:143], v[146:147], v[142:143]
	s_nop 0
	v_add_f32_e32 v142, v142, v143
	v_mov_b32_e32 v143, v142
	s_nop 1
	v_permlane16_swap_b32_e32 v143, v142
	s_waitcnt lgkmcnt(0)
	v_add_f32_e32 v142, v142, v143
	v_mov_b32_e32 v143, v142
	s_nop 1
	v_permlane32_swap_b32_e32 v143, v142
	s_waitcnt lgkmcnt(0)
	v_add_f32_e32 v142, v142, v143
	v_fmamk_f32 v142, v142, 0x3a800000, v250
	v_rsq_f32_e32 v160, v142

.LBB0_249:
	s_or_b64 exec, exec, s[8:9]
	v_or_b32_e32 v212, 32, v172
	s_mov_b64 s[8:9], -1
	s_and_b64 vcc, exec, s[6:7]
	s_cbranch_vccz .LBB0_251
	v_lshl_add_u32 v142, s74, 8, v212
	v_ashrrev_i32_e32 v143, 31, v142
	v_lshlrev_b64 v[142:143], 6, v[142:143]
	v_lshl_add_u64 v[142:143], s[44:45], 0, v[142:143]
	v_lshl_add_u64 v[142:143], v[142:143], 0, v[140:141]
	global_load_dwordx4 v[142:145], v[142:143], off
	s_mov_b64 s[8:9], 0
	s_waitcnt vmcnt(0) lgkmcnt(0)
	v_mov_b32_e32 v146, v143
	v_mov_b32_e32 v147, v144
	v_mov_b32_e32 v143, v145
	v_pk_add_f32 v[142:143], v[146:147], v[142:143]
	s_nop 0
	v_add_f32_e32 v142, v142, v143
	v_mov_b32_e32 v143, v142
	s_nop 1
	v_permlane16_swap_b32_e32 v143, v142
	s_waitcnt lgkmcnt(0)
	v_add_f32_e32 v142, v142, v143
	v_mov_b32_e32 v143, v142
	s_nop 1
	v_permlane32_swap_b32_e32 v143, v142
	s_waitcnt lgkmcnt(0)
	v_add_f32_e32 v142, v142, v143
	v_fmamk_f32 v142, v142, 0x3a800000, v250
	v_rsq_f32_e32 v160, v142

.LBB0_255:
	s_or_b64 exec, exec, s[8:9]
	v_or_b32_e32 v213, 48, v172
	s_mov_b64 s[8:9], -1
	s_and_b64 vcc, exec, s[6:7]
	s_cbranch_vccz .LBB0_257
	v_lshl_add_u32 v142, s74, 8, v213
	v_ashrrev_i32_e32 v143, 31, v142
	v_lshlrev_b64 v[142:143], 6, v[142:143]
	v_lshl_add_u64 v[142:143], s[44:45], 0, v[142:143]
	v_lshl_add_u64 v[142:143], v[142:143], 0, v[140:141]
	global_load_dwordx4 v[142:145], v[142:143], off
	s_mov_b64 s[8:9], 0
	s_waitcnt vmcnt(0) lgkmcnt(0)
	v_mov_b32_e32 v146, v143
	v_mov_b32_e32 v147, v144
	v_mov_b32_e32 v143, v145
	v_pk_add_f32 v[142:143], v[146:147], v[142:143]
	s_nop 0
	v_add_f32_e32 v142, v142, v143
	v_mov_b32_e32 v143, v142
	s_nop 1
	v_permlane16_swap_b32_e32 v143, v142
	s_waitcnt lgkmcnt(0)
	v_add_f32_e32 v142, v142, v143
	v_mov_b32_e32 v143, v142
	s_nop 1
	v_permlane32_swap_b32_e32 v143, v142
	s_waitcnt lgkmcnt(0)
	v_add_f32_e32 v142, v142, v143
	v_fmamk_f32 v142, v142, 0x3a800000, v250
	v_rsq_f32_e32 v162, v142

.LBB0_261:
	s_or_b64 exec, exec, s[8:9]
	v_add_u32_e32 v214, 0x80, v172
	s_mov_b64 s[8:9], -1
	s_and_b64 vcc, exec, s[6:7]
	s_cbranch_vccz .LBB0_263
	v_lshl_add_u32 v76, s74, 8, v214
	s_waitcnt lgkmcnt(0)
	v_ashrrev_i32_e32 v77, 31, v76
	v_lshlrev_b64 v[76:77], 6, v[76:77]
	v_lshl_add_u64 v[76:77], s[44:45], 0, v[76:77]
	v_lshl_add_u64 v[76:77], v[76:77], 0, v[140:141]
	global_load_dwordx4 v[142:145], v[76:77], off
	s_mov_b64 s[8:9], 0
	s_waitcnt vmcnt(0) lgkmcnt(0)
	v_mov_b32_e32 v76, v143
	v_mov_b32_e32 v77, v144
	v_mov_b32_e32 v143, v145
	v_pk_add_f32 v[76:77], v[76:77], v[142:143]
	s_nop 0
	v_add_f32_e32 v76, v76, v77
	v_mov_b32_e32 v77, v76
	s_nop 1
	v_permlane16_swap_b32_e32 v77, v76
	s_waitcnt lgkmcnt(0)
	v_add_f32_e32 v76, v76, v77
	v_mov_b32_e32 v77, v76
	s_nop 1
	v_permlane32_swap_b32_e32 v77, v76
	s_waitcnt lgkmcnt(0)
	v_add_f32_e32 v76, v76, v77
	v_fmamk_f32 v76, v76, 0x3a800000, v250
	v_rsq_f32_e32 v168, v76

.LBB0_267:
	s_or_b64 exec, exec, s[8:9]
	v_add_u32_e32 v215, 0x90, v172
	s_mov_b64 s[8:9], -1
	s_and_b64 vcc, exec, s[6:7]
	s_cbranch_vccz .LBB0_269
	v_lshl_add_u32 v50, s74, 8, v215
	s_waitcnt lgkmcnt(0)
	v_ashrrev_i32_e32 v51, 31, v50
	v_lshlrev_b64 v[50:51], 6, v[50:51]
	v_lshl_add_u64 v[50:51], s[44:45], 0, v[50:51]
	v_lshl_add_u64 v[50:51], v[50:51], 0, v[140:141]
	global_load_dwordx4 v[50:53], v[50:51], off
	s_mov_b64 s[8:9], 0
	s_waitcnt vmcnt(0) lgkmcnt(0)
	v_mov_b32_e32 v56, v51
	v_mov_b32_e32 v57, v52
	v_mov_b32_e32 v51, v53
	v_pk_add_f32 v[50:51], v[56:57], v[50:51]
	s_nop 0
	v_add_f32_e32 v50, v50, v51
	v_mov_b32_e32 v51, v50
	s_nop 1
	v_permlane16_swap_b32_e32 v51, v50
	s_waitcnt lgkmcnt(0)
	v_add_f32_e32 v50, v50, v51
	ds_bpermute_b32 v51, v210, v50
	s_waitcnt lgkmcnt(0)
	v_add_f32_e32 v50, v50, v51
	v_fmamk_f32 v50, v50, 0x3a800000, v250
	v_rsq_f32_e32 v50, v50

.LBB0_273:
	s_or_b64 exec, exec, s[8:9]
	v_add_u32_e32 v216, 0xa0, v172
	s_mov_b64 s[8:9], -1
	s_and_b64 vcc, exec, s[6:7]
	s_cbranch_vccz .LBB0_275
	v_lshl_add_u32 v34, s74, 8, v216
	s_waitcnt lgkmcnt(0)
	v_ashrrev_i32_e32 v35, 31, v34
	v_lshlrev_b64 v[34:35], 6, v[34:35]
	v_lshl_add_u64 v[34:35], s[44:45], 0, v[34:35]
	v_lshl_add_u64 v[34:35], v[34:35], 0, v[140:141]
	global_load_dwordx4 v[34:37], v[34:35], off
	s_mov_b64 s[8:9], 0
	s_waitcnt vmcnt(0) lgkmcnt(0)
	v_mov_b32_e32 v40, v35
	v_mov_b32_e32 v41, v36
	v_mov_b32_e32 v35, v37
	v_pk_add_f32 v[34:35], v[40:41], v[34:35]
	s_nop 0
	v_add_f32_e32 v34, v34, v35
	v_mov_b32_e32 v35, v34
	s_nop 1
	v_permlane16_swap_b32_e32 v35, v34
	s_waitcnt lgkmcnt(0)
	v_add_f32_e32 v34, v34, v35
	ds_bpermute_b32 v35, v210, v34
	s_waitcnt lgkmcnt(0)
	v_add_f32_e32 v34, v34, v35
	v_fmamk_f32 v34, v34, 0x3a800000, v250
	v_rsq_f32_e32 v34, v34

.LBB0_279:
	s_or_b64 exec, exec, s[8:9]
	v_add_u32_e32 v217, 0xb0, v172
	s_mov_b64 s[8:9], -1
	s_and_b64 vcc, exec, s[6:7]
	s_cbranch_vccz .LBB0_281
	v_lshl_add_u32 v18, s74, 8, v217
	s_waitcnt lgkmcnt(0)
	v_ashrrev_i32_e32 v19, 31, v18
	v_lshlrev_b64 v[18:19], 6, v[18:19]
	v_lshl_add_u64 v[18:19], s[44:45], 0, v[18:19]
	v_lshl_add_u64 v[18:19], v[18:19], 0, v[140:141]
	global_load_dwordx4 v[22:25], v[18:19], off
	s_mov_b64 s[8:9], 0
	s_waitcnt vmcnt(0) lgkmcnt(0)
	v_mov_b32_e32 v18, v23
	v_mov_b32_e32 v19, v24
	v_mov_b32_e32 v23, v25
	v_pk_add_f32 v[18:19], v[18:19], v[22:23]
	s_nop 0
	v_add_f32_e32 v18, v18, v19
	v_mov_b32_e32 v19, v18
	s_nop 1
	v_permlane16_swap_b32_e32 v19, v18
	s_waitcnt lgkmcnt(0)
	v_add_f32_e32 v18, v18, v19
	ds_bpermute_b32 v19, v210, v18
	s_waitcnt lgkmcnt(0)
	v_add_f32_e32 v18, v18, v19
	v_fmamk_f32 v18, v18, 0x3a800000, v250
	v_rsq_f32_e32 v18, v18

.LBB0_336:
	s_mov_b32 s6, -1
	s_lshl_b32 s5, s5, 8
	v_mbcnt_lo_u32_b32 v128, s6, 0
	v_mbcnt_hi_u32_b32 v128, s6, v128
	s_getreg_b32 s6, hwreg(HW_REG_HW_ID, 0, 6)
	s_and_b32 s6, s6, 63
	s_lshl_b32 s6, s6, 2
	s_add_i32 s6, s6, 0
	s_add_i32 s6, s6, 0x20200
	v_mov_b32_e32 v129, s6
	ds_read_b32 v129, v129
	v_bfrev_b32_e32 v130, 0.5
	s_lshl_b32 s56, s4, 2
	s_ashr_i32 s57, s56, 31
	s_waitcnt lgkmcnt(0)
	v_readfirstlane_b32 s6, v129
	s_nop 1
	v_lshl_add_u32 v128, s6, 6, v128
	s_nop 0
	v_readfirstlane_b32 s6, v128
	s_bfe_u32 s8, s6, 0x20006
	s_ashr_i32 s6, s6, 2
	s_andn2_b32 s6, s6, 63
	s_add_i32 s6, s6, s5
	v_and_or_b32 v170, v128, 15, s6
	s_lshl_b32 s5, s4, 8
	s_lshl_b32 s6, s8, 5
	v_bfe_u32 v129, v128, 4, 2
	s_or_b32 s5, s6, s5
	v_lshl_or_b32 v168, v129, 3, s5
	v_ashrrev_i32_e32 v169, 31, v168
	v_lshlrev_b64 v[146:147], 1, v[168:169]
	v_ashrrev_i32_e32 v171, 31, v170
	v_lshlrev_b32_e32 v128, 2, v128
	v_lshl_add_u64 v[172:173], s[68:69], 0, v[146:147]
	v_lshlrev_b64 v[148:149], 11, v[170:171]
	v_bitop3_b32 v181, v128, 64, v130 bitop3:0x6c
	v_bitop3_b32 v180, v128, s84, v130 bitop3:0x6c
	v_cmp_eq_u32_e32 vcc, 0, v129
	v_lshl_add_u64 v[128:129], v[172:173], 0, v[148:149]
	global_load_dwordx4 v[142:145], v[128:129], off
	global_load_dwordx4 v[136:139], v[128:129], off offset:256
	v_or_b32_e32 v174, 16, v170
	v_ashrrev_i32_e32 v175, 31, v174
	v_lshlrev_b64 v[176:177], 11, v[174:175]
	v_lshl_add_u64 v[128:129], v[172:173], 0, v[176:177]
	global_load_dwordx4 v[132:135], v[128:129], off
	s_nop 0
	global_load_dwordx4 v[128:131], v[128:129], off offset:256
	s_waitcnt vmcnt(0)
	v_lshlrev_b32_e32 v150, 16, v142
	v_and_b32_e32 v151, 0xffff0000, v142
	v_lshlrev_b32_e32 v142, 16, v143
	v_and_b32_e32 v143, 0xffff0000, v143
	v_lshlrev_b32_e32 v152, 16, v144
	v_and_b32_e32 v153, 0xffff0000, v144
	v_lshlrev_b32_e32 v144, 16, v145
	v_and_b32_e32 v145, 0xffff0000, v145
	v_pk_add_f32 v[124:125], v[124:125], v[150:151]
	v_pk_add_f32 v[126:127], v[126:127], v[142:143]
	v_pk_add_f32 v[142:143], v[122:123], v[144:145]
	v_pk_add_f32 v[122:123], v[120:121], v[152:153]
	v_cvt_pk_bf16_f32 v120, v124, v125
	v_lshl_add_u64 v[124:125], s[68:69], 0, v[148:149]
	v_lshl_add_u64 v[124:125], v[124:125], 0, v[146:147]
	v_cvt_pk_bf16_f32 v121, v126, v127
	v_cvt_pk_bf16_f32 v122, v122, v123
	v_cvt_pk_bf16_f32 v123, v142, v143
	global_store_dwordx4 v[124:125], v[120:123], off nt
	v_lshlrev_b32_e32 v126, 16, v120
	v_and_b32_e32 v127, 0xffff0000, v138
	v_and_b32_e32 v120, 0xffff0000, v120
	v_mul_f32_e32 v120, v120, v120
	v_fmac_f32_e32 v120, v126, v126
	v_lshlrev_b32_e32 v126, 16, v121
	v_and_b32_e32 v121, 0xffff0000, v121
	v_mul_f32_e32 v121, v121, v121
	v_fmac_f32_e32 v121, v126, v126
	v_add_f32_e32 v120, v120, v121
	v_lshlrev_b32_e32 v121, 16, v122
	v_and_b32_e32 v122, 0xffff0000, v122
	v_mul_f32_e32 v122, v122, v122
	v_fmac_f32_e32 v122, v121, v121
	v_add_f32_e32 v120, v120, v122
	v_and_b32_e32 v122, 0xffff0000, v123
	v_lshlrev_b32_e32 v121, 16, v123
	v_mul_f32_e32 v122, v122, v122
	v_fmac_f32_e32 v122, v121, v121
	v_add_f32_e32 v142, v120, v122
	v_lshlrev_b32_e32 v120, 16, v136
	v_and_b32_e32 v121, 0xffff0000, v136
	v_lshlrev_b32_e32 v122, 16, v137
	v_and_b32_e32 v123, 0xffff0000, v137
	v_lshlrev_b32_e32 v126, 16, v138
	v_lshlrev_b32_e32 v136, 16, v139
	v_and_b32_e32 v137, 0xffff0000, v139
	v_pk_add_f32 v[116:117], v[116:117], v[120:121]
	v_pk_add_f32 v[120:121], v[114:115], v[136:137]
	v_pk_add_f32 v[114:115], v[112:113], v[126:127]
	v_cvt_pk_bf16_f32 v112, v116, v117
	v_pk_add_f32 v[118:119], v[118:119], v[122:123]
	v_lshlrev_b32_e32 v116, 16, v112
	v_cvt_pk_bf16_f32 v113, v118, v119
	v_cvt_pk_bf16_f32 v114, v114, v115
	v_cvt_pk_bf16_f32 v115, v120, v121
	global_store_dwordx4 v[124:125], v[112:115], off offset:256 nt
	s_nop 1
	v_and_b32_e32 v112, 0xffff0000, v112
	v_mul_f32_e32 v112, v112, v112
	v_fmac_f32_e32 v112, v116, v116
	v_lshlrev_b32_e32 v116, 16, v113
	v_and_b32_e32 v113, 0xffff0000, v113
	v_mul_f32_e32 v113, v113, v113
	v_add_f32_e32 v112, v142, v112
	v_fmac_f32_e32 v113, v116, v116
	v_add_f32_e32 v112, v112, v113
	v_lshlrev_b32_e32 v113, 16, v114
	v_and_b32_e32 v114, 0xffff0000, v114
	v_mul_f32_e32 v114, v114, v114
	v_fmac_f32_e32 v114, v113, v113
	v_add_f32_e32 v112, v112, v114
	v_and_b32_e32 v114, 0xffff0000, v115
	v_lshlrev_b32_e32 v113, 16, v115
	v_mul_f32_e32 v114, v114, v114
	v_fmac_f32_e32 v114, v113, v113
	v_add_f32_e32 v112, v112, v114
	v_mov_b32_e32 v113, v112
	s_nop 1
	v_permlane16_swap_b32_e32 v113, v112
	s_waitcnt lgkmcnt(0)
	v_add_f32_e32 v112, v112, v113
	v_mov_b32_e32 v113, v112
	s_nop 1
	v_permlane32_swap_b32_e32 v113, v112
	s_and_saveexec_b64 s[6:7], vcc
	s_cbranch_execz .LBB0_338
	s_waitcnt lgkmcnt(0)
	v_add_f32_e32 v114, v112, v113
	v_lshlrev_b64 v[112:113], 6, v[170:171]
	v_lshl_add_u64 v[112:113], s[46:47], 0, v[112:113]
	v_lshl_add_u64 v[112:113], s[56:57], 2, v[112:113]
	s_lshl_b32 s38, s8, 2
	v_lshl_add_u64 v[112:113], v[112:113], 0, s[38:39]
	global_store_dword v[112:113], v114, off
.LBB0_338:
	s_or_b64 exec, exec, s[6:7]
	v_lshlrev_b32_e32 v112, 16, v132
	s_waitcnt lgkmcnt(0)
	v_and_b32_e32 v113, 0xffff0000, v132
	v_lshlrev_b32_e32 v116, 16, v134
	v_and_b32_e32 v117, 0xffff0000, v134
	v_lshlrev_b32_e32 v118, 16, v135
	v_and_b32_e32 v119, 0xffff0000, v135
	v_pk_add_f32 v[108:109], v[108:109], v[112:113]
	v_lshlrev_b32_e32 v114, 16, v133
	v_and_b32_e32 v115, 0xffff0000, v133
	v_pk_add_f32 v[112:113], v[106:107], v[118:119]
	v_pk_add_f32 v[106:107], v[104:105], v[116:117]
	v_cvt_pk_bf16_f32 v104, v108, v109
	v_lshl_add_u64 v[108:109], s[68:69], 0, v[176:177]
	v_pk_add_f32 v[110:111], v[110:111], v[114:115]
	v_lshl_add_u64 v[108:109], v[168:169], 1, v[108:109]
	v_cvt_pk_bf16_f32 v105, v110, v111
	v_cvt_pk_bf16_f32 v106, v106, v107
	v_cvt_pk_bf16_f32 v107, v112, v113
	global_store_dwordx4 v[108:109], v[104:107], off nt
	v_lshlrev_b32_e32 v110, 16, v104
	v_and_b32_e32 v111, 0xffff0000, v130
	v_and_b32_e32 v104, 0xffff0000, v104
	v_mul_f32_e32 v104, v104, v104
	v_fmac_f32_e32 v104, v110, v110
	v_lshlrev_b32_e32 v110, 16, v105
	v_and_b32_e32 v105, 0xffff0000, v105
	v_mul_f32_e32 v105, v105, v105
	v_fmac_f32_e32 v105, v110, v110
	v_add_f32_e32 v104, v104, v105
	v_lshlrev_b32_e32 v105, 16, v106
	v_and_b32_e32 v106, 0xffff0000, v106
	v_mul_f32_e32 v106, v106, v106
	v_fmac_f32_e32 v106, v105, v105
	v_add_f32_e32 v104, v104, v106
	v_and_b32_e32 v106, 0xffff0000, v107
	v_lshlrev_b32_e32 v105, 16, v107
	v_mul_f32_e32 v106, v106, v106
	v_fmac_f32_e32 v106, v105, v105
	v_add_f32_e32 v114, v104, v106
	v_lshlrev_b32_e32 v104, 16, v128
	v_and_b32_e32 v105, 0xffff0000, v128
	v_lshlrev_b32_e32 v110, 16, v130
	v_lshlrev_b32_e32 v106, 16, v129
	v_and_b32_e32 v107, 0xffff0000, v129
	v_lshlrev_b32_e32 v112, 16, v131
	v_and_b32_e32 v113, 0xffff0000, v131
	v_pk_add_f32 v[100:101], v[100:101], v[104:105]
	v_pk_add_f32 v[96:97], v[96:97], v[110:111]
	v_pk_add_f32 v[102:103], v[102:103], v[106:107]
	v_pk_add_f32 v[104:105], v[98:99], v[112:113]
	v_cvt_pk_bf16_f32 v98, v100, v101
	v_cvt_pk_bf16_f32 v99, v102, v103
	v_cvt_pk_bf16_f32 v100, v96, v97
	s_nop 0
	v_and_b32_e32 v97, 0xffff0000, v98
	v_lshlrev_b32_e32 v96, 16, v98
	v_mul_f32_e32 v97, v97, v97
	v_fmac_f32_e32 v97, v96, v96
	v_and_b32_e32 v102, 0xffff0000, v99
	v_add_f32_e32 v96, v114, v97
	v_lshlrev_b32_e32 v97, 16, v99
	v_mul_f32_e32 v102, v102, v102
	v_fmac_f32_e32 v102, v97, v97
	v_add_f32_e32 v96, v96, v102
	v_and_b32_e32 v102, 0xffff0000, v100
	v_lshlrev_b32_e32 v97, 16, v100
	v_mul_f32_e32 v102, v102, v102
	v_fmac_f32_e32 v102, v97, v97
	v_cvt_pk_bf16_f32 v101, v104, v105
	v_add_f32_e32 v96, v96, v102
	v_and_b32_e32 v102, 0xffff0000, v101
	v_lshlrev_b32_e32 v97, 16, v101
	v_mul_f32_e32 v102, v102, v102
	v_fmac_f32_e32 v102, v97, v97
	v_add_f32_e32 v96, v96, v102
	v_mov_b32_e32 v97, v96
	s_nop 1
	v_permlane16_swap_b32_e32 v97, v96
	global_store_dwordx4 v[108:109], v[98:101], off offset:256 nt
	s_waitcnt lgkmcnt(0)
	v_add_f32_e32 v96, v96, v97
	v_mov_b32_e32 v97, v96
	s_nop 1
	v_permlane32_swap_b32_e32 v97, v96
	s_and_saveexec_b64 s[6:7], vcc
	s_cbranch_execz .LBB0_340
	s_waitcnt lgkmcnt(0)
	v_add_f32_e32 v98, v96, v97
	v_lshlrev_b64 v[96:97], 6, v[174:175]
	v_lshl_add_u64 v[96:97], s[46:47], 0, v[96:97]
	v_lshl_add_u64 v[96:97], s[56:57], 2, v[96:97]
	s_lshl_b32 s38, s8, 2
	v_lshl_add_u64 v[96:97], v[96:97], 0, s[38:39]
	global_store_dword v[96:97], v98, off
.LBB0_340:
	s_or_b64 exec, exec, s[6:7]
	v_or_b32_e32 v112, 32, v170
	v_ashrrev_i32_e32 v113, 31, v112
	v_lshlrev_b64 v[118:119], 11, v[112:113]
	s_waitcnt lgkmcnt(0)
	v_lshl_add_u64 v[96:97], v[172:173], 0, v[118:119]
	global_load_dwordx4 v[114:117], v[96:97], off
	global_load_dwordx4 v[104:107], v[96:97], off offset:256
	v_or_b32_e32 v108, 48, v170
	v_ashrrev_i32_e32 v109, 31, v108
	v_lshlrev_b64 v[110:111], 11, v[108:109]
	v_lshl_add_u64 v[96:97], v[172:173], 0, v[110:111]
	global_load_dwordx4 v[100:103], v[96:97], off
	s_nop 0
	global_load_dwordx4 v[96:99], v[96:97], off offset:256
	s_waitcnt vmcnt(0)
	v_lshlrev_b32_e32 v120, 16, v114
	v_and_b32_e32 v121, 0xffff0000, v114
	v_lshlrev_b32_e32 v114, 16, v115
	v_and_b32_e32 v115, 0xffff0000, v115
	v_lshlrev_b32_e32 v122, 16, v116
	v_and_b32_e32 v123, 0xffff0000, v116
	v_lshlrev_b32_e32 v116, 16, v117
	v_and_b32_e32 v117, 0xffff0000, v117
	v_pk_add_f32 v[92:93], v[92:93], v[120:121]
	v_pk_add_f32 v[94:95], v[94:95], v[114:115]
	v_pk_add_f32 v[114:115], v[90:91], v[116:117]
	v_pk_add_f32 v[90:91], v[88:89], v[122:123]
	v_cvt_pk_bf16_f32 v88, v92, v93
	v_lshl_add_u64 v[92:93], s[68:69], 0, v[118:119]
	v_lshl_add_u64 v[92:93], v[168:169], 1, v[92:93]
	v_cvt_pk_bf16_f32 v89, v94, v95
	v_cvt_pk_bf16_f32 v90, v90, v91
	v_cvt_pk_bf16_f32 v91, v114, v115
	global_store_dwordx4 v[92:93], v[88:91], off nt
	v_lshlrev_b32_e32 v94, 16, v88
	v_and_b32_e32 v95, 0xffff0000, v106
	v_and_b32_e32 v88, 0xffff0000, v88
	v_mul_f32_e32 v88, v88, v88
	v_fmac_f32_e32 v88, v94, v94
	v_lshlrev_b32_e32 v94, 16, v89
	v_and_b32_e32 v89, 0xffff0000, v89
	v_mul_f32_e32 v89, v89, v89
	v_fmac_f32_e32 v89, v94, v94
	v_add_f32_e32 v88, v88, v89
	v_lshlrev_b32_e32 v89, 16, v90
	v_and_b32_e32 v90, 0xffff0000, v90
	v_mul_f32_e32 v90, v90, v90
	v_fmac_f32_e32 v90, v89, v89
	v_add_f32_e32 v88, v88, v90
	v_and_b32_e32 v90, 0xffff0000, v91
	v_lshlrev_b32_e32 v89, 16, v91
	v_mul_f32_e32 v90, v90, v90
	v_fmac_f32_e32 v90, v89, v89
	v_add_f32_e32 v114, v88, v90
	v_lshlrev_b32_e32 v88, 16, v104
	v_and_b32_e32 v89, 0xffff0000, v104
	v_lshlrev_b32_e32 v90, 16, v105
	v_and_b32_e32 v91, 0xffff0000, v105
	v_lshlrev_b32_e32 v94, 16, v106
	v_lshlrev_b32_e32 v104, 16, v107
	v_and_b32_e32 v105, 0xffff0000, v107
	v_pk_add_f32 v[84:85], v[84:85], v[88:89]
	v_pk_add_f32 v[88:89], v[82:83], v[104:105]
	v_pk_add_f32 v[82:83], v[80:81], v[94:95]
	v_cvt_pk_bf16_f32 v80, v84, v85
	v_pk_add_f32 v[86:87], v[86:87], v[90:91]
	v_lshlrev_b32_e32 v84, 16, v80
	v_cvt_pk_bf16_f32 v81, v86, v87
	v_cvt_pk_bf16_f32 v82, v82, v83
	v_cvt_pk_bf16_f32 v83, v88, v89
	global_store_dwordx4 v[92:93], v[80:83], off offset:256 nt
	s_nop 1
	v_and_b32_e32 v80, 0xffff0000, v80
	v_mul_f32_e32 v80, v80, v80
	v_fmac_f32_e32 v80, v84, v84
	v_lshlrev_b32_e32 v84, 16, v81
	v_and_b32_e32 v81, 0xffff0000, v81
	v_mul_f32_e32 v81, v81, v81
	v_add_f32_e32 v80, v114, v80
	v_fmac_f32_e32 v81, v84, v84
	v_add_f32_e32 v80, v80, v81
	v_lshlrev_b32_e32 v81, 16, v82
	v_and_b32_e32 v82, 0xffff0000, v82
	v_mul_f32_e32 v82, v82, v82
	v_fmac_f32_e32 v82, v81, v81
	v_add_f32_e32 v80, v80, v82
	v_and_b32_e32 v82, 0xffff0000, v83
	v_lshlrev_b32_e32 v81, 16, v83
	v_mul_f32_e32 v82, v82, v82
	v_fmac_f32_e32 v82, v81, v81
	v_add_f32_e32 v80, v80, v82
	v_mov_b32_e32 v81, v80
	s_nop 1
	v_permlane16_swap_b32_e32 v81, v80
	s_waitcnt lgkmcnt(0)
	v_add_f32_e32 v80, v80, v81
	v_mov_b32_e32 v81, v80
	s_nop 1
	v_permlane32_swap_b32_e32 v81, v80
	s_mov_b64 s[6:7], exec
	s_and_b64 s[4:5], s[6:7], vcc
	v_mov_b32_e32 v198, v216
	v_mov_b32_e32 v199, v217
	v_mov_b32_e32 v248, v218
	v_mov_b32_e32 v205, v219
	v_mov_b32_e32 v196, v220
	s_mov_b64 exec, s[4:5]
	s_cbranch_execz .LBB0_342
	s_waitcnt lgkmcnt(0)
	v_add_f32_e32 v82, v80, v81
	v_lshlrev_b64 v[80:81], 6, v[112:113]
	v_lshl_add_u64 v[80:81], s[46:47], 0, v[80:81]
	v_lshl_add_u64 v[80:81], s[56:57], 2, v[80:81]
	s_lshl_b32 s38, s8, 2
	v_lshl_add_u64 v[80:81], v[80:81], 0, s[38:39]
	global_store_dword v[80:81], v82, off
.LBB0_342:
	s_or_b64 exec, exec, s[6:7]
	v_lshlrev_b32_e32 v80, 16, v100
	s_waitcnt lgkmcnt(0)
	v_and_b32_e32 v81, 0xffff0000, v100
	v_lshlrev_b32_e32 v84, 16, v102
	v_and_b32_e32 v85, 0xffff0000, v102
	v_lshlrev_b32_e32 v86, 16, v103
	v_and_b32_e32 v87, 0xffff0000, v103
	v_pk_add_f32 v[76:77], v[76:77], v[80:81]
	v_lshlrev_b32_e32 v82, 16, v101
	v_and_b32_e32 v83, 0xffff0000, v101
	v_pk_add_f32 v[80:81], v[74:75], v[86:87]
	v_pk_add_f32 v[74:75], v[72:73], v[84:85]
	v_cvt_pk_bf16_f32 v72, v76, v77
	v_lshl_add_u64 v[76:77], s[68:69], 0, v[110:111]
	v_pk_add_f32 v[78:79], v[78:79], v[82:83]
	v_lshl_add_u64 v[76:77], v[168:169], 1, v[76:77]
	v_cvt_pk_bf16_f32 v73, v78, v79
	v_cvt_pk_bf16_f32 v74, v74, v75
	v_cvt_pk_bf16_f32 v75, v80, v81
	global_store_dwordx4 v[76:77], v[72:75], off nt
	v_lshlrev_b32_e32 v78, 16, v72
	v_and_b32_e32 v79, 0xffff0000, v98
	v_and_b32_e32 v72, 0xffff0000, v72
	v_mul_f32_e32 v72, v72, v72
	v_fmac_f32_e32 v72, v78, v78
	v_lshlrev_b32_e32 v78, 16, v73
	v_and_b32_e32 v73, 0xffff0000, v73
	v_mul_f32_e32 v73, v73, v73
	v_fmac_f32_e32 v73, v78, v78
	v_add_f32_e32 v72, v72, v73
	v_lshlrev_b32_e32 v73, 16, v74
	v_and_b32_e32 v74, 0xffff0000, v74
	v_mul_f32_e32 v74, v74, v74
	v_fmac_f32_e32 v74, v73, v73
	v_add_f32_e32 v72, v72, v74
	v_and_b32_e32 v74, 0xffff0000, v75
	v_lshlrev_b32_e32 v73, 16, v75
	v_mul_f32_e32 v74, v74, v74
	v_fmac_f32_e32 v74, v73, v73
	v_add_f32_e32 v82, v72, v74
	v_lshlrev_b32_e32 v72, 16, v96
	v_and_b32_e32 v73, 0xffff0000, v96
	v_lshlrev_b32_e32 v78, 16, v98
	v_lshlrev_b32_e32 v74, 16, v97
	v_and_b32_e32 v75, 0xffff0000, v97
	v_lshlrev_b32_e32 v80, 16, v99
	v_and_b32_e32 v81, 0xffff0000, v99
	v_pk_add_f32 v[68:69], v[68:69], v[72:73]
	v_pk_add_f32 v[64:65], v[64:65], v[78:79]
	v_pk_add_f32 v[70:71], v[70:71], v[74:75]
	v_pk_add_f32 v[72:73], v[66:67], v[80:81]
	v_cvt_pk_bf16_f32 v66, v68, v69
	v_cvt_pk_bf16_f32 v67, v70, v71
	v_cvt_pk_bf16_f32 v68, v64, v65
	s_nop 0
	v_and_b32_e32 v65, 0xffff0000, v66
	v_lshlrev_b32_e32 v64, 16, v66
	v_mul_f32_e32 v65, v65, v65
	v_fmac_f32_e32 v65, v64, v64
	v_and_b32_e32 v70, 0xffff0000, v67
	v_add_f32_e32 v64, v82, v65
	v_lshlrev_b32_e32 v65, 16, v67
	v_mul_f32_e32 v70, v70, v70
	v_fmac_f32_e32 v70, v65, v65
	v_add_f32_e32 v64, v64, v70
	v_and_b32_e32 v70, 0xffff0000, v68
	v_lshlrev_b32_e32 v65, 16, v68
	v_mul_f32_e32 v70, v70, v70
	v_fmac_f32_e32 v70, v65, v65
	v_cvt_pk_bf16_f32 v69, v72, v73
	v_add_f32_e32 v64, v64, v70
	v_and_b32_e32 v70, 0xffff0000, v69
	v_lshlrev_b32_e32 v65, 16, v69
	v_mul_f32_e32 v70, v70, v70
	v_fmac_f32_e32 v70, v65, v65
	v_add_f32_e32 v64, v64, v70
	v_mov_b32_e32 v65, v64
	s_nop 1
	v_permlane16_swap_b32_e32 v65, v64
	global_store_dwordx4 v[76:77], v[66:69], off offset:256 nt
	s_waitcnt lgkmcnt(0)
	v_add_f32_e32 v64, v64, v65
	v_mov_b32_e32 v65, v64
	s_nop 1
	v_permlane32_swap_b32_e32 v65, v64
	s_and_saveexec_b64 s[6:7], vcc
	s_cbranch_execz .LBB0_344
	s_waitcnt lgkmcnt(0)
	v_add_f32_e32 v66, v64, v65
	v_lshlrev_b64 v[64:65], 6, v[108:109]
	v_lshl_add_u64 v[64:65], s[46:47], 0, v[64:65]
	v_lshl_add_u64 v[64:65], s[56:57], 2, v[64:65]
	s_lshl_b32 s38, s8, 2
	v_lshl_add_u64 v[64:65], v[64:65], 0, s[38:39]
	global_store_dword v[64:65], v66, off
.LBB0_344:
	s_or_b64 exec, exec, s[6:7]
	v_add_u32_e32 v80, 0x80, v170
	v_ashrrev_i32_e32 v81, 31, v80
	v_lshlrev_b64 v[86:87], 11, v[80:81]
	s_waitcnt lgkmcnt(0)
	v_lshl_add_u64 v[64:65], v[172:173], 0, v[86:87]
	global_load_dwordx4 v[82:85], v[64:65], off
	global_load_dwordx4 v[72:75], v[64:65], off offset:256
	v_add_u32_e32 v76, 0x90, v170
	v_ashrrev_i32_e32 v77, 31, v76
	v_lshlrev_b64 v[78:79], 11, v[76:77]
	v_lshl_add_u64 v[64:65], v[172:173], 0, v[78:79]
	global_load_dwordx4 v[68:71], v[64:65], off
	s_nop 0
	global_load_dwordx4 v[64:67], v[64:65], off offset:256
	s_waitcnt vmcnt(0)
	v_lshlrev_b32_e32 v88, 16, v82
	v_and_b32_e32 v89, 0xffff0000, v82
	v_lshlrev_b32_e32 v82, 16, v83
	v_and_b32_e32 v83, 0xffff0000, v83
	v_lshlrev_b32_e32 v90, 16, v84
	v_and_b32_e32 v91, 0xffff0000, v84
	v_lshlrev_b32_e32 v84, 16, v85
	v_and_b32_e32 v85, 0xffff0000, v85
	v_pk_add_f32 v[60:61], v[60:61], v[88:89]
	v_pk_add_f32 v[62:63], v[62:63], v[82:83]
	v_pk_add_f32 v[82:83], v[58:59], v[84:85]
	v_pk_add_f32 v[58:59], v[56:57], v[90:91]
	v_cvt_pk_bf16_f32 v56, v60, v61
	v_lshl_add_u64 v[60:61], s[68:69], 0, v[86:87]
	v_lshl_add_u64 v[60:61], v[168:169], 1, v[60:61]
	v_cvt_pk_bf16_f32 v57, v62, v63
	v_cvt_pk_bf16_f32 v58, v58, v59
	v_cvt_pk_bf16_f32 v59, v82, v83
	global_store_dwordx4 v[60:61], v[56:59], off nt
	v_lshlrev_b32_e32 v62, 16, v56
	v_and_b32_e32 v63, 0xffff0000, v74
	v_and_b32_e32 v56, 0xffff0000, v56
	v_mul_f32_e32 v56, v56, v56
	v_fmac_f32_e32 v56, v62, v62
	v_lshlrev_b32_e32 v62, 16, v57
	v_and_b32_e32 v57, 0xffff0000, v57
	v_mul_f32_e32 v57, v57, v57
	v_fmac_f32_e32 v57, v62, v62
	v_add_f32_e32 v56, v56, v57
	v_lshlrev_b32_e32 v57, 16, v58
	v_and_b32_e32 v58, 0xffff0000, v58
	v_mul_f32_e32 v58, v58, v58
	v_fmac_f32_e32 v58, v57, v57
	v_add_f32_e32 v56, v56, v58
	v_and_b32_e32 v58, 0xffff0000, v59
	v_lshlrev_b32_e32 v57, 16, v59
	v_mul_f32_e32 v58, v58, v58
	v_fmac_f32_e32 v58, v57, v57
	v_add_f32_e32 v82, v56, v58
	v_lshlrev_b32_e32 v56, 16, v72
	v_and_b32_e32 v57, 0xffff0000, v72
	v_lshlrev_b32_e32 v58, 16, v73
	v_and_b32_e32 v59, 0xffff0000, v73
	v_lshlrev_b32_e32 v62, 16, v74
	v_lshlrev_b32_e32 v72, 16, v75
	v_and_b32_e32 v73, 0xffff0000, v75
	v_pk_add_f32 v[52:53], v[52:53], v[56:57]
	v_pk_add_f32 v[56:57], v[50:51], v[72:73]
	v_pk_add_f32 v[50:51], v[48:49], v[62:63]
	v_cvt_pk_bf16_f32 v48, v52, v53
	v_pk_add_f32 v[54:55], v[54:55], v[58:59]
	v_lshlrev_b32_e32 v52, 16, v48
	v_cvt_pk_bf16_f32 v49, v54, v55
	v_cvt_pk_bf16_f32 v50, v50, v51
	v_cvt_pk_bf16_f32 v51, v56, v57
	global_store_dwordx4 v[60:61], v[48:51], off offset:256 nt
	s_nop 1
	v_and_b32_e32 v48, 0xffff0000, v48
	v_mul_f32_e32 v48, v48, v48
	v_fmac_f32_e32 v48, v52, v52
	v_lshlrev_b32_e32 v52, 16, v49
	v_and_b32_e32 v49, 0xffff0000, v49
	v_mul_f32_e32 v49, v49, v49
	v_add_f32_e32 v48, v82, v48
	v_fmac_f32_e32 v49, v52, v52
	v_add_f32_e32 v48, v48, v49
	v_lshlrev_b32_e32 v49, 16, v50
	v_and_b32_e32 v50, 0xffff0000, v50
	v_mul_f32_e32 v50, v50, v50
	v_fmac_f32_e32 v50, v49, v49
	v_add_f32_e32 v48, v48, v50
	v_and_b32_e32 v50, 0xffff0000, v51
	v_lshlrev_b32_e32 v49, 16, v51
	v_mul_f32_e32 v50, v50, v50
	v_fmac_f32_e32 v50, v49, v49
	v_add_f32_e32 v48, v48, v50
	v_mov_b32_e32 v49, v48
	s_nop 1
	v_permlane16_swap_b32_e32 v49, v48
	s_waitcnt lgkmcnt(0)
	v_add_f32_e32 v48, v48, v49
	v_mov_b32_e32 v49, v48
	s_nop 1
	v_permlane32_swap_b32_e32 v49, v48
	s_and_saveexec_b64 s[6:7], vcc
	s_cbranch_execz .LBB0_346
	s_waitcnt lgkmcnt(0)
	v_add_f32_e32 v50, v48, v49
	v_lshlrev_b64 v[48:49], 6, v[80:81]
	v_lshl_add_u64 v[48:49], s[46:47], 0, v[48:49]
	v_lshl_add_u64 v[48:49], s[56:57], 2, v[48:49]
	s_lshl_b32 s38, s8, 2
	v_lshl_add_u64 v[48:49], v[48:49], 0, s[38:39]
	global_store_dword v[48:49], v50, off
.LBB0_346:
	s_or_b64 exec, exec, s[6:7]
	v_lshlrev_b32_e32 v48, 16, v68
	s_waitcnt lgkmcnt(0)
	v_and_b32_e32 v49, 0xffff0000, v68
	v_lshlrev_b32_e32 v52, 16, v70
	v_and_b32_e32 v53, 0xffff0000, v70
	v_lshlrev_b32_e32 v54, 16, v71
	v_and_b32_e32 v55, 0xffff0000, v71
	v_pk_add_f32 v[44:45], v[44:45], v[48:49]
	v_lshlrev_b32_e32 v50, 16, v69
	v_and_b32_e32 v51, 0xffff0000, v69
	v_pk_add_f32 v[48:49], v[42:43], v[54:55]
	v_pk_add_f32 v[42:43], v[40:41], v[52:53]
	v_cvt_pk_bf16_f32 v40, v44, v45
	v_lshl_add_u64 v[44:45], s[68:69], 0, v[78:79]
	v_pk_add_f32 v[46:47], v[46:47], v[50:51]
	v_lshl_add_u64 v[44:45], v[168:169], 1, v[44:45]
	v_cvt_pk_bf16_f32 v41, v46, v47
	v_cvt_pk_bf16_f32 v42, v42, v43
	v_cvt_pk_bf16_f32 v43, v48, v49
	global_store_dwordx4 v[44:45], v[40:43], off nt
	v_lshlrev_b32_e32 v46, 16, v40
	v_and_b32_e32 v47, 0xffff0000, v66
	v_and_b32_e32 v40, 0xffff0000, v40
	v_mul_f32_e32 v40, v40, v40
	v_fmac_f32_e32 v40, v46, v46
	v_lshlrev_b32_e32 v46, 16, v41
	v_and_b32_e32 v41, 0xffff0000, v41
	v_mul_f32_e32 v41, v41, v41
	v_fmac_f32_e32 v41, v46, v46
	v_add_f32_e32 v40, v40, v41
	v_lshlrev_b32_e32 v41, 16, v42
	v_and_b32_e32 v42, 0xffff0000, v42
	v_mul_f32_e32 v42, v42, v42
	v_fmac_f32_e32 v42, v41, v41
	v_add_f32_e32 v40, v40, v42
	v_and_b32_e32 v42, 0xffff0000, v43
	v_lshlrev_b32_e32 v41, 16, v43
	v_mul_f32_e32 v42, v42, v42
	v_fmac_f32_e32 v42, v41, v41
	v_add_f32_e32 v50, v40, v42
	v_lshlrev_b32_e32 v40, 16, v64
	v_and_b32_e32 v41, 0xffff0000, v64
	v_lshlrev_b32_e32 v46, 16, v66
	v_lshlrev_b32_e32 v42, 16, v65
	v_and_b32_e32 v43, 0xffff0000, v65
	v_lshlrev_b32_e32 v48, 16, v67
	v_and_b32_e32 v49, 0xffff0000, v67
	v_pk_add_f32 v[36:37], v[36:37], v[40:41]
	v_pk_add_f32 v[32:33], v[32:33], v[46:47]
	v_pk_add_f32 v[38:39], v[38:39], v[42:43]
	v_pk_add_f32 v[40:41], v[34:35], v[48:49]
	v_cvt_pk_bf16_f32 v34, v36, v37
	v_cvt_pk_bf16_f32 v35, v38, v39
	v_cvt_pk_bf16_f32 v36, v32, v33
	s_nop 0
	v_and_b32_e32 v33, 0xffff0000, v34
	v_lshlrev_b32_e32 v32, 16, v34
	v_mul_f32_e32 v33, v33, v33
	v_fmac_f32_e32 v33, v32, v32
	v_and_b32_e32 v38, 0xffff0000, v35
	v_add_f32_e32 v32, v50, v33
	v_lshlrev_b32_e32 v33, 16, v35
	v_mul_f32_e32 v38, v38, v38
	v_fmac_f32_e32 v38, v33, v33
	v_add_f32_e32 v32, v32, v38
	v_and_b32_e32 v38, 0xffff0000, v36
	v_lshlrev_b32_e32 v33, 16, v36
	v_mul_f32_e32 v38, v38, v38
	v_fmac_f32_e32 v38, v33, v33
	v_cvt_pk_bf16_f32 v37, v40, v41
	v_add_f32_e32 v32, v32, v38
	v_and_b32_e32 v38, 0xffff0000, v37
	v_lshlrev_b32_e32 v33, 16, v37
	v_mul_f32_e32 v38, v38, v38
	v_fmac_f32_e32 v38, v33, v33
	v_add_f32_e32 v32, v32, v38
	v_mov_b32_e32 v33, v32
	s_nop 1
	v_permlane16_swap_b32_e32 v33, v32
	global_store_dwordx4 v[44:45], v[34:37], off offset:256 nt
	s_waitcnt lgkmcnt(0)
	v_add_f32_e32 v32, v32, v33
	v_mov_b32_e32 v33, v32
	s_nop 1
	v_permlane32_swap_b32_e32 v33, v32
	s_and_saveexec_b64 s[6:7], vcc
	s_cbranch_execz .LBB0_348
	s_waitcnt lgkmcnt(0)
	v_add_f32_e32 v34, v32, v33
	v_lshlrev_b64 v[32:33], 6, v[76:77]
	v_lshl_add_u64 v[32:33], s[46:47], 0, v[32:33]
	v_lshl_add_u64 v[32:33], s[56:57], 2, v[32:33]
	s_lshl_b32 s38, s8, 2
	v_lshl_add_u64 v[32:33], v[32:33], 0, s[38:39]
	global_store_dword v[32:33], v34, off
.LBB0_348:
	s_or_b64 exec, exec, s[6:7]
	v_add_u32_e32 v48, 0xa0, v170
	v_ashrrev_i32_e32 v49, 31, v48
	v_lshlrev_b64 v[54:55], 11, v[48:49]
	s_waitcnt lgkmcnt(0)
	v_lshl_add_u64 v[32:33], v[172:173], 0, v[54:55]
	global_load_dwordx4 v[50:53], v[32:33], off
	global_load_dwordx4 v[40:43], v[32:33], off offset:256
	v_add_u32_e32 v44, 0xb0, v170
	v_ashrrev_i32_e32 v45, 31, v44
	v_lshlrev_b64 v[46:47], 11, v[44:45]
	v_lshl_add_u64 v[32:33], v[172:173], 0, v[46:47]
	global_load_dwordx4 v[36:39], v[32:33], off
	s_nop 0
	global_load_dwordx4 v[32:35], v[32:33], off offset:256
	s_waitcnt vmcnt(0)
	v_lshlrev_b32_e32 v56, 16, v50
	v_and_b32_e32 v57, 0xffff0000, v50
	v_lshlrev_b32_e32 v50, 16, v51
	v_and_b32_e32 v51, 0xffff0000, v51
	v_lshlrev_b32_e32 v58, 16, v52
	v_and_b32_e32 v59, 0xffff0000, v52
	v_lshlrev_b32_e32 v52, 16, v53
	v_and_b32_e32 v53, 0xffff0000, v53
	v_pk_add_f32 v[28:29], v[28:29], v[56:57]
	v_pk_add_f32 v[30:31], v[30:31], v[50:51]
	v_pk_add_f32 v[50:51], v[26:27], v[52:53]
	v_pk_add_f32 v[26:27], v[24:25], v[58:59]
	v_cvt_pk_bf16_f32 v24, v28, v29
	v_lshl_add_u64 v[28:29], s[68:69], 0, v[54:55]
	v_lshl_add_u64 v[28:29], v[168:169], 1, v[28:29]
	v_cvt_pk_bf16_f32 v25, v30, v31
	v_cvt_pk_bf16_f32 v26, v26, v27
	v_cvt_pk_bf16_f32 v27, v50, v51
	global_store_dwordx4 v[28:29], v[24:27], off nt
	v_lshlrev_b32_e32 v30, 16, v24
	v_and_b32_e32 v31, 0xffff0000, v42
	v_and_b32_e32 v24, 0xffff0000, v24
	v_mul_f32_e32 v24, v24, v24
	v_fmac_f32_e32 v24, v30, v30
	v_lshlrev_b32_e32 v30, 16, v25
	v_and_b32_e32 v25, 0xffff0000, v25
	v_mul_f32_e32 v25, v25, v25
	v_fmac_f32_e32 v25, v30, v30
	v_add_f32_e32 v24, v24, v25
	v_lshlrev_b32_e32 v25, 16, v26
	v_and_b32_e32 v26, 0xffff0000, v26
	v_mul_f32_e32 v26, v26, v26
	v_fmac_f32_e32 v26, v25, v25
	v_add_f32_e32 v24, v24, v26
	v_and_b32_e32 v26, 0xffff0000, v27
	v_lshlrev_b32_e32 v25, 16, v27
	v_mul_f32_e32 v26, v26, v26
	v_fmac_f32_e32 v26, v25, v25
	v_add_f32_e32 v50, v24, v26
	v_lshlrev_b32_e32 v24, 16, v40
	v_and_b32_e32 v25, 0xffff0000, v40
	v_lshlrev_b32_e32 v26, 16, v41
	v_and_b32_e32 v27, 0xffff0000, v41
	v_lshlrev_b32_e32 v30, 16, v42
	v_lshlrev_b32_e32 v40, 16, v43
	v_and_b32_e32 v41, 0xffff0000, v43
	v_pk_add_f32 v[20:21], v[20:21], v[24:25]
	v_pk_add_f32 v[24:25], v[18:19], v[40:41]
	v_pk_add_f32 v[18:19], v[16:17], v[30:31]
	v_cvt_pk_bf16_f32 v16, v20, v21
	v_pk_add_f32 v[22:23], v[22:23], v[26:27]
	v_lshlrev_b32_e32 v20, 16, v16
	v_cvt_pk_bf16_f32 v17, v22, v23
	v_cvt_pk_bf16_f32 v18, v18, v19
	v_cvt_pk_bf16_f32 v19, v24, v25
	global_store_dwordx4 v[28:29], v[16:19], off offset:256 nt
	s_nop 1
	v_and_b32_e32 v16, 0xffff0000, v16
	v_mul_f32_e32 v16, v16, v16
	v_fmac_f32_e32 v16, v20, v20
	v_lshlrev_b32_e32 v20, 16, v17
	v_and_b32_e32 v17, 0xffff0000, v17
	v_mul_f32_e32 v17, v17, v17
	v_add_f32_e32 v16, v50, v16
	v_fmac_f32_e32 v17, v20, v20
	v_add_f32_e32 v16, v16, v17
	v_lshlrev_b32_e32 v17, 16, v18
	v_and_b32_e32 v18, 0xffff0000, v18
	v_mul_f32_e32 v18, v18, v18
	v_fmac_f32_e32 v18, v17, v17
	v_add_f32_e32 v16, v16, v18
	v_and_b32_e32 v18, 0xffff0000, v19
	v_lshlrev_b32_e32 v17, 16, v19
	v_mul_f32_e32 v18, v18, v18
	v_fmac_f32_e32 v18, v17, v17
	v_add_f32_e32 v16, v16, v18
	v_mov_b32_e32 v17, v16
	s_nop 1
	v_permlane16_swap_b32_e32 v17, v16
	s_waitcnt lgkmcnt(0)
	v_add_f32_e32 v16, v16, v17
	v_mov_b32_e32 v17, v16
	s_nop 1
	v_permlane32_swap_b32_e32 v17, v16
	s_and_saveexec_b64 s[6:7], vcc
	s_cbranch_execz .LBB0_350
	s_waitcnt lgkmcnt(0)
	v_add_f32_e32 v18, v16, v17
	v_lshlrev_b64 v[16:17], 6, v[48:49]
	v_lshl_add_u64 v[16:17], s[46:47], 0, v[16:17]
	v_lshl_add_u64 v[16:17], s[56:57], 2, v[16:17]
	s_lshl_b32 s38, s8, 2
	v_lshl_add_u64 v[16:17], v[16:17], 0, s[38:39]
	global_store_dword v[16:17], v18, off
.LBB0_350:
	s_or_b64 exec, exec, s[6:7]
	v_lshlrev_b32_e32 v16, 16, v36
	s_waitcnt lgkmcnt(0)
	v_and_b32_e32 v17, 0xffff0000, v36
	v_lshlrev_b32_e32 v20, 16, v38
	v_and_b32_e32 v21, 0xffff0000, v38
	v_lshlrev_b32_e32 v22, 16, v39
	v_and_b32_e32 v23, 0xffff0000, v39
	v_pk_add_f32 v[12:13], v[12:13], v[16:17]
	v_lshlrev_b32_e32 v18, 16, v37
	v_and_b32_e32 v19, 0xffff0000, v37
	v_pk_add_f32 v[16:17], v[10:11], v[22:23]
	v_pk_add_f32 v[10:11], v[8:9], v[20:21]
	v_cvt_pk_bf16_f32 v8, v12, v13
	v_lshl_add_u64 v[12:13], s[68:69], 0, v[46:47]
	v_pk_add_f32 v[14:15], v[14:15], v[18:19]
	v_lshl_add_u64 v[12:13], v[168:169], 1, v[12:13]
	v_cvt_pk_bf16_f32 v9, v14, v15
	v_cvt_pk_bf16_f32 v10, v10, v11
	v_cvt_pk_bf16_f32 v11, v16, v17
	global_store_dwordx4 v[12:13], v[8:11], off nt
	v_lshlrev_b32_e32 v14, 16, v8
	v_and_b32_e32 v15, 0xffff0000, v34
	v_and_b32_e32 v8, 0xffff0000, v8
	v_mul_f32_e32 v8, v8, v8
	v_fmac_f32_e32 v8, v14, v14
	v_lshlrev_b32_e32 v14, 16, v9
	v_and_b32_e32 v9, 0xffff0000, v9
	v_mul_f32_e32 v9, v9, v9
	v_fmac_f32_e32 v9, v14, v14
	v_add_f32_e32 v8, v8, v9
	v_lshlrev_b32_e32 v9, 16, v10
	v_and_b32_e32 v10, 0xffff0000, v10
	v_mul_f32_e32 v10, v10, v10
	v_fmac_f32_e32 v10, v9, v9
	v_add_f32_e32 v8, v8, v10
	v_and_b32_e32 v10, 0xffff0000, v11
	v_lshlrev_b32_e32 v9, 16, v11
	v_mul_f32_e32 v10, v10, v10
	v_fmac_f32_e32 v10, v9, v9
	v_add_f32_e32 v18, v8, v10
	v_lshlrev_b32_e32 v8, 16, v32
	v_and_b32_e32 v9, 0xffff0000, v32
	v_lshlrev_b32_e32 v14, 16, v34
	v_lshlrev_b32_e32 v10, 16, v33
	v_and_b32_e32 v11, 0xffff0000, v33
	v_lshlrev_b32_e32 v16, 16, v35
	v_and_b32_e32 v17, 0xffff0000, v35
	v_pk_add_f32 v[4:5], v[4:5], v[8:9]
	v_pk_add_f32 v[0:1], v[0:1], v[14:15]
	v_pk_add_f32 v[6:7], v[6:7], v[10:11]
	v_pk_add_f32 v[8:9], v[2:3], v[16:17]
	v_cvt_pk_bf16_f32 v2, v4, v5
	v_cvt_pk_bf16_f32 v3, v6, v7
	v_cvt_pk_bf16_f32 v4, v0, v1
	s_nop 0
	v_and_b32_e32 v1, 0xffff0000, v2
	v_lshlrev_b32_e32 v0, 16, v2
	v_mul_f32_e32 v1, v1, v1
	v_fmac_f32_e32 v1, v0, v0
	v_and_b32_e32 v6, 0xffff0000, v3
	v_add_f32_e32 v0, v18, v1
	v_lshlrev_b32_e32 v1, 16, v3
	v_mul_f32_e32 v6, v6, v6
	v_fmac_f32_e32 v6, v1, v1
	v_add_f32_e32 v0, v0, v6
	v_and_b32_e32 v6, 0xffff0000, v4
	v_lshlrev_b32_e32 v1, 16, v4
	v_mul_f32_e32 v6, v6, v6
	v_fmac_f32_e32 v6, v1, v1
	v_cvt_pk_bf16_f32 v5, v8, v9
	v_add_f32_e32 v0, v0, v6
	v_and_b32_e32 v6, 0xffff0000, v5
	v_lshlrev_b32_e32 v1, 16, v5
	v_mul_f32_e32 v6, v6, v6
	v_fmac_f32_e32 v6, v1, v1
	v_add_f32_e32 v0, v0, v6
	v_mov_b32_e32 v1, v0
	s_nop 1
	v_permlane16_swap_b32_e32 v1, v0
	global_store_dwordx4 v[12:13], v[2:5], off offset:256 nt
	s_waitcnt lgkmcnt(0)
	v_add_f32_e32 v0, v0, v1
	v_mov_b32_e32 v1, v0
	s_nop 1
	v_permlane32_swap_b32_e32 v1, v0
	s_and_saveexec_b64 s[6:7], vcc
	s_cbranch_execz .LBB0_352
	s_waitcnt lgkmcnt(0)
	v_add_f32_e32 v2, v0, v1
	v_lshlrev_b64 v[0:1], 6, v[44:45]
	v_lshl_add_u64 v[0:1], s[46:47], 0, v[0:1]
	v_lshl_add_u64 v[0:1], s[56:57], 2, v[0:1]
	s_lshl_b32 s38, s8, 2
	v_lshl_add_u64 v[0:1], v[0:1], 0, s[38:39]
	global_store_dword v[0:1], v2, off

.LBB0_378:
	s_mov_b32 s6, -1
	s_lshl_b32 s5, s5, 8
	v_mbcnt_lo_u32_b32 v128, s6, 0
	v_mbcnt_hi_u32_b32 v128, s6, v128
	s_getreg_b32 s6, hwreg(HW_REG_HW_ID, 0, 6)
	s_and_b32 s6, s6, 63
	s_lshl_b32 s6, s6, 2
	s_add_i32 s6, s6, 0
	s_add_i32 s6, s6, 0x20200
	v_mov_b32_e32 v129, s6
	ds_read_b32 v129, v129
	v_bfrev_b32_e32 v130, 0.5
	s_lshl_b32 s56, s4, 2
	s_ashr_i32 s57, s56, 31
	s_waitcnt lgkmcnt(0)
	v_readfirstlane_b32 s6, v129
	s_nop 1
	v_lshl_add_u32 v128, s6, 6, v128
	s_nop 0
	v_readfirstlane_b32 s6, v128
	s_bfe_u32 s8, s6, 0x20006
	s_ashr_i32 s6, s6, 2
	s_andn2_b32 s6, s6, 63
	s_add_i32 s6, s6, s5
	v_and_or_b32 v170, v128, 15, s6
	s_lshl_b32 s5, s4, 8
	s_lshl_b32 s6, s8, 5
	v_bfe_u32 v129, v128, 4, 2
	s_or_b32 s5, s6, s5
	v_lshl_or_b32 v168, v129, 3, s5
	v_ashrrev_i32_e32 v169, 31, v168
	v_lshlrev_b64 v[146:147], 1, v[168:169]
	v_ashrrev_i32_e32 v171, 31, v170
	v_lshlrev_b32_e32 v128, 2, v128
	v_lshl_add_u64 v[172:173], s[68:69], 0, v[146:147]
	v_lshlrev_b64 v[148:149], 11, v[170:171]
	v_bitop3_b32 v181, v128, 64, v130 bitop3:0x6c
	v_bitop3_b32 v180, v128, s84, v130 bitop3:0x6c
	v_cmp_eq_u32_e32 vcc, 0, v129
	v_lshl_add_u64 v[128:129], v[172:173], 0, v[148:149]
	global_load_dwordx4 v[142:145], v[128:129], off
	global_load_dwordx4 v[136:139], v[128:129], off offset:256
	v_or_b32_e32 v174, 16, v170
	v_ashrrev_i32_e32 v175, 31, v174
	v_lshlrev_b64 v[176:177], 11, v[174:175]
	v_lshl_add_u64 v[128:129], v[172:173], 0, v[176:177]
	global_load_dwordx4 v[132:135], v[128:129], off
	s_nop 0
	global_load_dwordx4 v[128:131], v[128:129], off offset:256
	s_waitcnt vmcnt(0)
	v_lshlrev_b32_e32 v150, 16, v142
	v_and_b32_e32 v151, 0xffff0000, v142
	v_lshlrev_b32_e32 v142, 16, v143
	v_and_b32_e32 v143, 0xffff0000, v143
	v_lshlrev_b32_e32 v152, 16, v144
	v_and_b32_e32 v153, 0xffff0000, v144
	v_lshlrev_b32_e32 v144, 16, v145
	v_and_b32_e32 v145, 0xffff0000, v145
	v_pk_add_f32 v[124:125], v[124:125], v[150:151]
	v_pk_add_f32 v[126:127], v[126:127], v[142:143]
	v_pk_add_f32 v[142:143], v[122:123], v[144:145]
	v_pk_add_f32 v[122:123], v[120:121], v[152:153]
	v_cvt_pk_bf16_f32 v120, v124, v125
	v_lshl_add_u64 v[124:125], s[68:69], 0, v[148:149]
	v_lshl_add_u64 v[124:125], v[124:125], 0, v[146:147]
	v_cvt_pk_bf16_f32 v121, v126, v127
	v_cvt_pk_bf16_f32 v122, v122, v123
	v_cvt_pk_bf16_f32 v123, v142, v143
	global_store_dwordx4 v[124:125], v[120:123], off nt
	v_lshlrev_b32_e32 v126, 16, v120
	v_and_b32_e32 v127, 0xffff0000, v138
	v_and_b32_e32 v120, 0xffff0000, v120
	v_mul_f32_e32 v120, v120, v120
	v_fmac_f32_e32 v120, v126, v126
	v_lshlrev_b32_e32 v126, 16, v121
	v_and_b32_e32 v121, 0xffff0000, v121
	v_mul_f32_e32 v121, v121, v121
	v_fmac_f32_e32 v121, v126, v126
	v_add_f32_e32 v120, v120, v121
	v_lshlrev_b32_e32 v121, 16, v122
	v_and_b32_e32 v122, 0xffff0000, v122
	v_mul_f32_e32 v122, v122, v122
	v_fmac_f32_e32 v122, v121, v121
	v_add_f32_e32 v120, v120, v122
	v_and_b32_e32 v122, 0xffff0000, v123
	v_lshlrev_b32_e32 v121, 16, v123
	v_mul_f32_e32 v122, v122, v122
	v_fmac_f32_e32 v122, v121, v121
	v_add_f32_e32 v142, v120, v122
	v_lshlrev_b32_e32 v120, 16, v136
	v_and_b32_e32 v121, 0xffff0000, v136
	v_lshlrev_b32_e32 v122, 16, v137
	v_and_b32_e32 v123, 0xffff0000, v137
	v_lshlrev_b32_e32 v126, 16, v138
	v_lshlrev_b32_e32 v136, 16, v139
	v_and_b32_e32 v137, 0xffff0000, v139
	v_pk_add_f32 v[116:117], v[116:117], v[120:121]
	v_pk_add_f32 v[120:121], v[114:115], v[136:137]
	v_pk_add_f32 v[114:115], v[112:113], v[126:127]
	v_cvt_pk_bf16_f32 v112, v116, v117
	v_pk_add_f32 v[118:119], v[118:119], v[122:123]
	v_lshlrev_b32_e32 v116, 16, v112
	v_cvt_pk_bf16_f32 v113, v118, v119
	v_cvt_pk_bf16_f32 v114, v114, v115
	v_cvt_pk_bf16_f32 v115, v120, v121
	global_store_dwordx4 v[124:125], v[112:115], off offset:256 nt
	s_nop 1
	v_and_b32_e32 v112, 0xffff0000, v112
	v_mul_f32_e32 v112, v112, v112
	v_fmac_f32_e32 v112, v116, v116
	v_lshlrev_b32_e32 v116, 16, v113
	v_and_b32_e32 v113, 0xffff0000, v113
	v_mul_f32_e32 v113, v113, v113
	v_add_f32_e32 v112, v142, v112
	v_fmac_f32_e32 v113, v116, v116
	v_add_f32_e32 v112, v112, v113
	v_lshlrev_b32_e32 v113, 16, v114
	v_and_b32_e32 v114, 0xffff0000, v114
	v_mul_f32_e32 v114, v114, v114
	v_fmac_f32_e32 v114, v113, v113
	v_add_f32_e32 v112, v112, v114
	v_and_b32_e32 v114, 0xffff0000, v115
	v_lshlrev_b32_e32 v113, 16, v115
	v_mul_f32_e32 v114, v114, v114
	v_fmac_f32_e32 v114, v113, v113
	v_add_f32_e32 v112, v112, v114
	v_mov_b32_e32 v113, v112
	s_nop 1
	v_permlane16_swap_b32_e32 v113, v112
	s_waitcnt lgkmcnt(0)
	v_add_f32_e32 v112, v112, v113
	v_mov_b32_e32 v113, v112
	s_nop 1
	v_permlane32_swap_b32_e32 v113, v112
	s_and_saveexec_b64 s[6:7], vcc
	s_cbranch_execz .LBB0_380
	v_lshlrev_b64 v[114:115], 6, v[170:171]
	v_lshl_add_u64 v[114:115], s[46:47], 0, v[114:115]
	v_lshl_add_u64 v[114:115], s[56:57], 2, v[114:115]
	s_lshl_b32 s38, s8, 2
	v_lshl_add_u64 v[114:115], v[114:115], 0, s[38:39]
	s_waitcnt lgkmcnt(0)
	v_add_f32_e32 v112, v112, v113
	global_store_dword v[114:115], v112, off
.LBB0_380:
	s_or_b64 exec, exec, s[6:7]
	v_lshlrev_b32_e32 v112, 16, v132
	s_waitcnt lgkmcnt(0)
	v_and_b32_e32 v113, 0xffff0000, v132
	v_lshlrev_b32_e32 v116, 16, v134
	v_and_b32_e32 v117, 0xffff0000, v134
	v_lshlrev_b32_e32 v118, 16, v135
	v_and_b32_e32 v119, 0xffff0000, v135
	v_pk_add_f32 v[108:109], v[108:109], v[112:113]
	v_lshlrev_b32_e32 v114, 16, v133
	v_and_b32_e32 v115, 0xffff0000, v133
	v_pk_add_f32 v[112:113], v[106:107], v[118:119]
	v_pk_add_f32 v[106:107], v[104:105], v[116:117]
	v_cvt_pk_bf16_f32 v104, v108, v109
	v_lshl_add_u64 v[108:109], s[68:69], 0, v[176:177]
	v_pk_add_f32 v[110:111], v[110:111], v[114:115]
	v_lshl_add_u64 v[108:109], v[168:169], 1, v[108:109]
	v_cvt_pk_bf16_f32 v105, v110, v111
	v_cvt_pk_bf16_f32 v106, v106, v107
	v_cvt_pk_bf16_f32 v107, v112, v113
	global_store_dwordx4 v[108:109], v[104:107], off nt
	v_lshlrev_b32_e32 v110, 16, v104
	v_and_b32_e32 v111, 0xffff0000, v130
	v_and_b32_e32 v104, 0xffff0000, v104
	v_mul_f32_e32 v104, v104, v104
	v_fmac_f32_e32 v104, v110, v110
	v_lshlrev_b32_e32 v110, 16, v105
	v_and_b32_e32 v105, 0xffff0000, v105
	v_mul_f32_e32 v105, v105, v105
	v_fmac_f32_e32 v105, v110, v110
	v_add_f32_e32 v104, v104, v105
	v_lshlrev_b32_e32 v105, 16, v106
	v_and_b32_e32 v106, 0xffff0000, v106
	v_mul_f32_e32 v106, v106, v106
	v_fmac_f32_e32 v106, v105, v105
	v_add_f32_e32 v104, v104, v106
	v_and_b32_e32 v106, 0xffff0000, v107
	v_lshlrev_b32_e32 v105, 16, v107
	v_mul_f32_e32 v106, v106, v106
	v_fmac_f32_e32 v106, v105, v105
	v_add_f32_e32 v114, v104, v106
	v_lshlrev_b32_e32 v104, 16, v128
	v_and_b32_e32 v105, 0xffff0000, v128
	v_lshlrev_b32_e32 v110, 16, v130
	v_lshlrev_b32_e32 v106, 16, v129
	v_and_b32_e32 v107, 0xffff0000, v129
	v_lshlrev_b32_e32 v112, 16, v131
	v_and_b32_e32 v113, 0xffff0000, v131
	v_pk_add_f32 v[100:101], v[100:101], v[104:105]
	v_pk_add_f32 v[96:97], v[96:97], v[110:111]
	v_pk_add_f32 v[102:103], v[102:103], v[106:107]
	v_pk_add_f32 v[104:105], v[98:99], v[112:113]
	v_cvt_pk_bf16_f32 v98, v100, v101
	v_cvt_pk_bf16_f32 v99, v102, v103
	v_cvt_pk_bf16_f32 v100, v96, v97
	s_nop 0
	v_and_b32_e32 v97, 0xffff0000, v98
	v_lshlrev_b32_e32 v96, 16, v98
	v_mul_f32_e32 v97, v97, v97
	v_fmac_f32_e32 v97, v96, v96
	v_and_b32_e32 v102, 0xffff0000, v99
	v_add_f32_e32 v96, v114, v97
	v_lshlrev_b32_e32 v97, 16, v99
	v_mul_f32_e32 v102, v102, v102
	v_fmac_f32_e32 v102, v97, v97
	v_add_f32_e32 v96, v96, v102
	v_and_b32_e32 v102, 0xffff0000, v100
	v_lshlrev_b32_e32 v97, 16, v100
	v_mul_f32_e32 v102, v102, v102
	v_fmac_f32_e32 v102, v97, v97
	v_cvt_pk_bf16_f32 v101, v104, v105
	v_add_f32_e32 v96, v96, v102
	v_and_b32_e32 v102, 0xffff0000, v101
	v_lshlrev_b32_e32 v97, 16, v101
	v_mul_f32_e32 v102, v102, v102
	v_fmac_f32_e32 v102, v97, v97
	v_add_f32_e32 v96, v96, v102
	v_mov_b32_e32 v97, v96
	s_nop 1
	v_permlane16_swap_b32_e32 v97, v96
	global_store_dwordx4 v[108:109], v[98:101], off offset:256 nt
	s_waitcnt lgkmcnt(0)
	v_add_f32_e32 v96, v96, v97
	v_mov_b32_e32 v97, v96
	s_nop 1
	v_permlane32_swap_b32_e32 v97, v96
	s_and_saveexec_b64 s[6:7], vcc
	s_cbranch_execz .LBB0_382
	v_lshlrev_b64 v[98:99], 6, v[174:175]
	v_lshl_add_u64 v[98:99], s[46:47], 0, v[98:99]
	v_lshl_add_u64 v[98:99], s[56:57], 2, v[98:99]
	s_lshl_b32 s38, s8, 2
	v_lshl_add_u64 v[98:99], v[98:99], 0, s[38:39]
	s_waitcnt lgkmcnt(0)
	v_add_f32_e32 v96, v96, v97
	global_store_dword v[98:99], v96, off
.LBB0_382:
	s_or_b64 exec, exec, s[6:7]
	v_or_b32_e32 v112, 32, v170
	v_ashrrev_i32_e32 v113, 31, v112
	v_lshlrev_b64 v[118:119], 11, v[112:113]
	s_waitcnt lgkmcnt(0)
	v_lshl_add_u64 v[96:97], v[172:173], 0, v[118:119]
	global_load_dwordx4 v[114:117], v[96:97], off
	global_load_dwordx4 v[104:107], v[96:97], off offset:256
	v_or_b32_e32 v108, 48, v170
	v_ashrrev_i32_e32 v109, 31, v108
	v_lshlrev_b64 v[110:111], 11, v[108:109]
	v_lshl_add_u64 v[96:97], v[172:173], 0, v[110:111]
	global_load_dwordx4 v[100:103], v[96:97], off
	s_nop 0
	global_load_dwordx4 v[96:99], v[96:97], off offset:256
	s_waitcnt vmcnt(0)
	v_lshlrev_b32_e32 v120, 16, v114
	v_and_b32_e32 v121, 0xffff0000, v114
	v_lshlrev_b32_e32 v114, 16, v115
	v_and_b32_e32 v115, 0xffff0000, v115
	v_lshlrev_b32_e32 v122, 16, v116
	v_and_b32_e32 v123, 0xffff0000, v116
	v_lshlrev_b32_e32 v116, 16, v117
	v_and_b32_e32 v117, 0xffff0000, v117
	v_pk_add_f32 v[92:93], v[92:93], v[120:121]
	v_pk_add_f32 v[94:95], v[94:95], v[114:115]
	v_pk_add_f32 v[114:115], v[90:91], v[116:117]
	v_pk_add_f32 v[90:91], v[88:89], v[122:123]
	v_cvt_pk_bf16_f32 v88, v92, v93
	v_lshl_add_u64 v[92:93], s[68:69], 0, v[118:119]
	v_lshl_add_u64 v[92:93], v[168:169], 1, v[92:93]
	v_cvt_pk_bf16_f32 v89, v94, v95
	v_cvt_pk_bf16_f32 v90, v90, v91
	v_cvt_pk_bf16_f32 v91, v114, v115
	global_store_dwordx4 v[92:93], v[88:91], off nt
	v_lshlrev_b32_e32 v94, 16, v88
	v_and_b32_e32 v95, 0xffff0000, v106
	v_and_b32_e32 v88, 0xffff0000, v88
	v_mul_f32_e32 v88, v88, v88
	v_fmac_f32_e32 v88, v94, v94
	v_lshlrev_b32_e32 v94, 16, v89
	v_and_b32_e32 v89, 0xffff0000, v89
	v_mul_f32_e32 v89, v89, v89
	v_fmac_f32_e32 v89, v94, v94
	v_add_f32_e32 v88, v88, v89
	v_lshlrev_b32_e32 v89, 16, v90
	v_and_b32_e32 v90, 0xffff0000, v90
	v_mul_f32_e32 v90, v90, v90
	v_fmac_f32_e32 v90, v89, v89
	v_add_f32_e32 v88, v88, v90
	v_and_b32_e32 v90, 0xffff0000, v91
	v_lshlrev_b32_e32 v89, 16, v91
	v_mul_f32_e32 v90, v90, v90
	v_fmac_f32_e32 v90, v89, v89
	v_add_f32_e32 v114, v88, v90
	v_lshlrev_b32_e32 v88, 16, v104
	v_and_b32_e32 v89, 0xffff0000, v104
	v_lshlrev_b32_e32 v90, 16, v105
	v_and_b32_e32 v91, 0xffff0000, v105
	v_lshlrev_b32_e32 v94, 16, v106
	v_lshlrev_b32_e32 v104, 16, v107
	v_and_b32_e32 v105, 0xffff0000, v107
	v_pk_add_f32 v[84:85], v[84:85], v[88:89]
	v_pk_add_f32 v[88:89], v[82:83], v[104:105]
	v_pk_add_f32 v[82:83], v[80:81], v[94:95]
	v_cvt_pk_bf16_f32 v80, v84, v85
	v_pk_add_f32 v[86:87], v[86:87], v[90:91]
	v_lshlrev_b32_e32 v84, 16, v80
	v_cvt_pk_bf16_f32 v81, v86, v87
	v_cvt_pk_bf16_f32 v82, v82, v83
	v_cvt_pk_bf16_f32 v83, v88, v89
	global_store_dwordx4 v[92:93], v[80:83], off offset:256 nt
	s_nop 1
	v_and_b32_e32 v80, 0xffff0000, v80
	v_mul_f32_e32 v80, v80, v80
	v_fmac_f32_e32 v80, v84, v84
	v_lshlrev_b32_e32 v84, 16, v81
	v_and_b32_e32 v81, 0xffff0000, v81
	v_mul_f32_e32 v81, v81, v81
	v_add_f32_e32 v80, v114, v80
	v_fmac_f32_e32 v81, v84, v84
	v_add_f32_e32 v80, v80, v81
	v_lshlrev_b32_e32 v81, 16, v82
	v_and_b32_e32 v82, 0xffff0000, v82
	v_mul_f32_e32 v82, v82, v82
	v_fmac_f32_e32 v82, v81, v81
	v_add_f32_e32 v80, v80, v82
	v_and_b32_e32 v82, 0xffff0000, v83
	v_lshlrev_b32_e32 v81, 16, v83
	v_mul_f32_e32 v82, v82, v82
	v_fmac_f32_e32 v82, v81, v81
	v_add_f32_e32 v80, v80, v82
	v_mov_b32_e32 v81, v80
	s_nop 1
	v_permlane16_swap_b32_e32 v81, v80
	s_waitcnt lgkmcnt(0)
	v_add_f32_e32 v80, v80, v81
	v_mov_b32_e32 v81, v80
	s_nop 1
	v_permlane32_swap_b32_e32 v81, v80
	s_mov_b64 s[6:7], exec
	s_and_b64 s[4:5], s[6:7], vcc
	v_mov_b32_e32 v198, v220
	v_mov_b32_e32 v199, v221
	v_mov_b32_e32 v248, v222
	v_mov_b32_e32 v205, v223
	v_mov_b32_e32 v196, v224
	s_mov_b64 exec, s[4:5]
	s_cbranch_execz .LBB0_384
	v_lshlrev_b64 v[82:83], 6, v[112:113]
	v_lshl_add_u64 v[82:83], s[46:47], 0, v[82:83]
	v_lshl_add_u64 v[82:83], s[56:57], 2, v[82:83]
	s_lshl_b32 s38, s8, 2
	v_lshl_add_u64 v[82:83], v[82:83], 0, s[38:39]
	s_waitcnt lgkmcnt(0)
	v_add_f32_e32 v80, v80, v81
	global_store_dword v[82:83], v80, off
.LBB0_384:
	s_or_b64 exec, exec, s[6:7]
	v_lshlrev_b32_e32 v80, 16, v100
	s_waitcnt lgkmcnt(0)
	v_and_b32_e32 v81, 0xffff0000, v100
	v_lshlrev_b32_e32 v84, 16, v102
	v_and_b32_e32 v85, 0xffff0000, v102
	v_lshlrev_b32_e32 v86, 16, v103
	v_and_b32_e32 v87, 0xffff0000, v103
	v_pk_add_f32 v[76:77], v[76:77], v[80:81]
	v_lshlrev_b32_e32 v82, 16, v101
	v_and_b32_e32 v83, 0xffff0000, v101
	v_pk_add_f32 v[80:81], v[74:75], v[86:87]
	v_pk_add_f32 v[74:75], v[72:73], v[84:85]
	v_cvt_pk_bf16_f32 v72, v76, v77
	v_lshl_add_u64 v[76:77], s[68:69], 0, v[110:111]
	v_pk_add_f32 v[78:79], v[78:79], v[82:83]
	v_lshl_add_u64 v[76:77], v[168:169], 1, v[76:77]
	v_cvt_pk_bf16_f32 v73, v78, v79
	v_cvt_pk_bf16_f32 v74, v74, v75
	v_cvt_pk_bf16_f32 v75, v80, v81
	global_store_dwordx4 v[76:77], v[72:75], off nt
	v_lshlrev_b32_e32 v78, 16, v72
	v_and_b32_e32 v79, 0xffff0000, v98
	v_and_b32_e32 v72, 0xffff0000, v72
	v_mul_f32_e32 v72, v72, v72
	v_fmac_f32_e32 v72, v78, v78
	v_lshlrev_b32_e32 v78, 16, v73
	v_and_b32_e32 v73, 0xffff0000, v73
	v_mul_f32_e32 v73, v73, v73
	v_fmac_f32_e32 v73, v78, v78
	v_add_f32_e32 v72, v72, v73
	v_lshlrev_b32_e32 v73, 16, v74
	v_and_b32_e32 v74, 0xffff0000, v74
	v_mul_f32_e32 v74, v74, v74
	v_fmac_f32_e32 v74, v73, v73
	v_add_f32_e32 v72, v72, v74
	v_and_b32_e32 v74, 0xffff0000, v75
	v_lshlrev_b32_e32 v73, 16, v75
	v_mul_f32_e32 v74, v74, v74
	v_fmac_f32_e32 v74, v73, v73
	v_add_f32_e32 v82, v72, v74
	v_lshlrev_b32_e32 v72, 16, v96
	v_and_b32_e32 v73, 0xffff0000, v96
	v_lshlrev_b32_e32 v78, 16, v98
	v_lshlrev_b32_e32 v74, 16, v97
	v_and_b32_e32 v75, 0xffff0000, v97
	v_lshlrev_b32_e32 v80, 16, v99
	v_and_b32_e32 v81, 0xffff0000, v99
	v_pk_add_f32 v[68:69], v[68:69], v[72:73]
	v_pk_add_f32 v[64:65], v[64:65], v[78:79]
	v_pk_add_f32 v[70:71], v[70:71], v[74:75]
	v_pk_add_f32 v[72:73], v[66:67], v[80:81]
	v_cvt_pk_bf16_f32 v66, v68, v69
	v_cvt_pk_bf16_f32 v67, v70, v71
	v_cvt_pk_bf16_f32 v68, v64, v65
	s_nop 0
	v_and_b32_e32 v65, 0xffff0000, v66
	v_lshlrev_b32_e32 v64, 16, v66
	v_mul_f32_e32 v65, v65, v65
	v_fmac_f32_e32 v65, v64, v64
	v_and_b32_e32 v70, 0xffff0000, v67
	v_add_f32_e32 v64, v82, v65
	v_lshlrev_b32_e32 v65, 16, v67
	v_mul_f32_e32 v70, v70, v70
	v_fmac_f32_e32 v70, v65, v65
	v_add_f32_e32 v64, v64, v70
	v_and_b32_e32 v70, 0xffff0000, v68
	v_lshlrev_b32_e32 v65, 16, v68
	v_mul_f32_e32 v70, v70, v70
	v_fmac_f32_e32 v70, v65, v65
	v_cvt_pk_bf16_f32 v69, v72, v73
	v_add_f32_e32 v64, v64, v70
	v_and_b32_e32 v70, 0xffff0000, v69
	v_lshlrev_b32_e32 v65, 16, v69
	v_mul_f32_e32 v70, v70, v70
	v_fmac_f32_e32 v70, v65, v65
	v_add_f32_e32 v64, v64, v70
	v_mov_b32_e32 v65, v64
	s_nop 1
	v_permlane16_swap_b32_e32 v65, v64
	global_store_dwordx4 v[76:77], v[66:69], off offset:256 nt
	s_waitcnt lgkmcnt(0)
	v_add_f32_e32 v64, v64, v65
	v_mov_b32_e32 v65, v64
	s_nop 1
	v_permlane32_swap_b32_e32 v65, v64
	s_and_saveexec_b64 s[6:7], vcc
	s_cbranch_execz .LBB0_386
	v_lshlrev_b64 v[66:67], 6, v[108:109]
	v_lshl_add_u64 v[66:67], s[46:47], 0, v[66:67]
	v_lshl_add_u64 v[66:67], s[56:57], 2, v[66:67]
	s_lshl_b32 s38, s8, 2
	v_lshl_add_u64 v[66:67], v[66:67], 0, s[38:39]
	s_waitcnt lgkmcnt(0)
	v_add_f32_e32 v64, v64, v65
	global_store_dword v[66:67], v64, off
.LBB0_386:
	s_or_b64 exec, exec, s[6:7]
	v_add_u32_e32 v80, 0x80, v170
	v_ashrrev_i32_e32 v81, 31, v80
	v_lshlrev_b64 v[86:87], 11, v[80:81]
	s_waitcnt lgkmcnt(0)
	v_lshl_add_u64 v[64:65], v[172:173], 0, v[86:87]
	global_load_dwordx4 v[82:85], v[64:65], off
	global_load_dwordx4 v[72:75], v[64:65], off offset:256
	v_add_u32_e32 v76, 0x90, v170
	v_ashrrev_i32_e32 v77, 31, v76
	v_lshlrev_b64 v[78:79], 11, v[76:77]
	v_lshl_add_u64 v[64:65], v[172:173], 0, v[78:79]
	global_load_dwordx4 v[68:71], v[64:65], off
	s_nop 0
	global_load_dwordx4 v[64:67], v[64:65], off offset:256
	s_waitcnt vmcnt(0)
	v_lshlrev_b32_e32 v88, 16, v82
	v_and_b32_e32 v89, 0xffff0000, v82
	v_lshlrev_b32_e32 v82, 16, v83
	v_and_b32_e32 v83, 0xffff0000, v83
	v_lshlrev_b32_e32 v90, 16, v84
	v_and_b32_e32 v91, 0xffff0000, v84
	v_lshlrev_b32_e32 v84, 16, v85
	v_and_b32_e32 v85, 0xffff0000, v85
	v_pk_add_f32 v[60:61], v[60:61], v[88:89]
	v_pk_add_f32 v[62:63], v[62:63], v[82:83]
	v_pk_add_f32 v[82:83], v[58:59], v[84:85]
	v_pk_add_f32 v[58:59], v[56:57], v[90:91]
	v_cvt_pk_bf16_f32 v56, v60, v61
	v_lshl_add_u64 v[60:61], s[68:69], 0, v[86:87]
	v_lshl_add_u64 v[60:61], v[168:169], 1, v[60:61]
	v_cvt_pk_bf16_f32 v57, v62, v63
	v_cvt_pk_bf16_f32 v58, v58, v59
	v_cvt_pk_bf16_f32 v59, v82, v83
	global_store_dwordx4 v[60:61], v[56:59], off nt
	v_lshlrev_b32_e32 v62, 16, v56
	v_and_b32_e32 v63, 0xffff0000, v74
	v_and_b32_e32 v56, 0xffff0000, v56
	v_mul_f32_e32 v56, v56, v56
	v_fmac_f32_e32 v56, v62, v62
	v_lshlrev_b32_e32 v62, 16, v57
	v_and_b32_e32 v57, 0xffff0000, v57
	v_mul_f32_e32 v57, v57, v57
	v_fmac_f32_e32 v57, v62, v62
	v_add_f32_e32 v56, v56, v57
	v_lshlrev_b32_e32 v57, 16, v58
	v_and_b32_e32 v58, 0xffff0000, v58
	v_mul_f32_e32 v58, v58, v58
	v_fmac_f32_e32 v58, v57, v57
	v_add_f32_e32 v56, v56, v58
	v_and_b32_e32 v58, 0xffff0000, v59
	v_lshlrev_b32_e32 v57, 16, v59
	v_mul_f32_e32 v58, v58, v58
	v_fmac_f32_e32 v58, v57, v57
	v_add_f32_e32 v82, v56, v58
	v_lshlrev_b32_e32 v56, 16, v72
	v_and_b32_e32 v57, 0xffff0000, v72
	v_lshlrev_b32_e32 v58, 16, v73
	v_and_b32_e32 v59, 0xffff0000, v73
	v_lshlrev_b32_e32 v62, 16, v74
	v_lshlrev_b32_e32 v72, 16, v75
	v_and_b32_e32 v73, 0xffff0000, v75
	v_pk_add_f32 v[52:53], v[52:53], v[56:57]
	v_pk_add_f32 v[56:57], v[50:51], v[72:73]
	v_pk_add_f32 v[50:51], v[48:49], v[62:63]
	v_cvt_pk_bf16_f32 v48, v52, v53
	v_pk_add_f32 v[54:55], v[54:55], v[58:59]
	v_lshlrev_b32_e32 v52, 16, v48
	v_cvt_pk_bf16_f32 v49, v54, v55
	v_cvt_pk_bf16_f32 v50, v50, v51
	v_cvt_pk_bf16_f32 v51, v56, v57
	global_store_dwordx4 v[60:61], v[48:51], off offset:256 nt
	s_nop 1
	v_and_b32_e32 v48, 0xffff0000, v48
	v_mul_f32_e32 v48, v48, v48
	v_fmac_f32_e32 v48, v52, v52
	v_lshlrev_b32_e32 v52, 16, v49
	v_and_b32_e32 v49, 0xffff0000, v49
	v_mul_f32_e32 v49, v49, v49
	v_add_f32_e32 v48, v82, v48
	v_fmac_f32_e32 v49, v52, v52
	v_add_f32_e32 v48, v48, v49
	v_lshlrev_b32_e32 v49, 16, v50
	v_and_b32_e32 v50, 0xffff0000, v50
	v_mul_f32_e32 v50, v50, v50
	v_fmac_f32_e32 v50, v49, v49
	v_add_f32_e32 v48, v48, v50
	v_and_b32_e32 v50, 0xffff0000, v51
	v_lshlrev_b32_e32 v49, 16, v51
	v_mul_f32_e32 v50, v50, v50
	v_fmac_f32_e32 v50, v49, v49
	v_add_f32_e32 v48, v48, v50
	v_mov_b32_e32 v49, v48
	s_nop 1
	v_permlane16_swap_b32_e32 v49, v48
	s_waitcnt lgkmcnt(0)
	v_add_f32_e32 v48, v48, v49
	v_mov_b32_e32 v49, v48
	s_nop 1
	v_permlane32_swap_b32_e32 v49, v48
	s_and_saveexec_b64 s[6:7], vcc
	s_cbranch_execz .LBB0_388
	v_lshlrev_b64 v[50:51], 6, v[80:81]
	v_lshl_add_u64 v[50:51], s[46:47], 0, v[50:51]
	v_lshl_add_u64 v[50:51], s[56:57], 2, v[50:51]
	s_lshl_b32 s38, s8, 2
	v_lshl_add_u64 v[50:51], v[50:51], 0, s[38:39]
	s_waitcnt lgkmcnt(0)
	v_add_f32_e32 v48, v48, v49
	global_store_dword v[50:51], v48, off
.LBB0_388:
	s_or_b64 exec, exec, s[6:7]
	v_lshlrev_b32_e32 v48, 16, v68
	s_waitcnt lgkmcnt(0)
	v_and_b32_e32 v49, 0xffff0000, v68
	v_lshlrev_b32_e32 v52, 16, v70
	v_and_b32_e32 v53, 0xffff0000, v70
	v_lshlrev_b32_e32 v54, 16, v71
	v_and_b32_e32 v55, 0xffff0000, v71
	v_pk_add_f32 v[44:45], v[44:45], v[48:49]
	v_lshlrev_b32_e32 v50, 16, v69
	v_and_b32_e32 v51, 0xffff0000, v69
	v_pk_add_f32 v[48:49], v[42:43], v[54:55]
	v_pk_add_f32 v[42:43], v[40:41], v[52:53]
	v_cvt_pk_bf16_f32 v40, v44, v45
	v_lshl_add_u64 v[44:45], s[68:69], 0, v[78:79]
	v_pk_add_f32 v[46:47], v[46:47], v[50:51]
	v_lshl_add_u64 v[44:45], v[168:169], 1, v[44:45]
	v_cvt_pk_bf16_f32 v41, v46, v47
	v_cvt_pk_bf16_f32 v42, v42, v43
	v_cvt_pk_bf16_f32 v43, v48, v49
	global_store_dwordx4 v[44:45], v[40:43], off nt
	v_lshlrev_b32_e32 v46, 16, v40
	v_and_b32_e32 v47, 0xffff0000, v66
	v_and_b32_e32 v40, 0xffff0000, v40
	v_mul_f32_e32 v40, v40, v40
	v_fmac_f32_e32 v40, v46, v46
	v_lshlrev_b32_e32 v46, 16, v41
	v_and_b32_e32 v41, 0xffff0000, v41
	v_mul_f32_e32 v41, v41, v41
	v_fmac_f32_e32 v41, v46, v46
	v_add_f32_e32 v40, v40, v41
	v_lshlrev_b32_e32 v41, 16, v42
	v_and_b32_e32 v42, 0xffff0000, v42
	v_mul_f32_e32 v42, v42, v42
	v_fmac_f32_e32 v42, v41, v41
	v_add_f32_e32 v40, v40, v42
	v_and_b32_e32 v42, 0xffff0000, v43
	v_lshlrev_b32_e32 v41, 16, v43
	v_mul_f32_e32 v42, v42, v42
	v_fmac_f32_e32 v42, v41, v41
	v_add_f32_e32 v50, v40, v42
	v_lshlrev_b32_e32 v40, 16, v64
	v_and_b32_e32 v41, 0xffff0000, v64
	v_lshlrev_b32_e32 v46, 16, v66
	v_lshlrev_b32_e32 v42, 16, v65
	v_and_b32_e32 v43, 0xffff0000, v65
	v_lshlrev_b32_e32 v48, 16, v67
	v_and_b32_e32 v49, 0xffff0000, v67
	v_pk_add_f32 v[36:37], v[36:37], v[40:41]
	v_pk_add_f32 v[32:33], v[32:33], v[46:47]
	v_pk_add_f32 v[38:39], v[38:39], v[42:43]
	v_pk_add_f32 v[40:41], v[34:35], v[48:49]
	v_cvt_pk_bf16_f32 v34, v36, v37
	v_cvt_pk_bf16_f32 v35, v38, v39
	v_cvt_pk_bf16_f32 v36, v32, v33
	s_nop 0
	v_and_b32_e32 v33, 0xffff0000, v34
	v_lshlrev_b32_e32 v32, 16, v34
	v_mul_f32_e32 v33, v33, v33
	v_fmac_f32_e32 v33, v32, v32
	v_and_b32_e32 v38, 0xffff0000, v35
	v_add_f32_e32 v32, v50, v33
	v_lshlrev_b32_e32 v33, 16, v35
	v_mul_f32_e32 v38, v38, v38
	v_fmac_f32_e32 v38, v33, v33
	v_add_f32_e32 v32, v32, v38
	v_and_b32_e32 v38, 0xffff0000, v36
	v_lshlrev_b32_e32 v33, 16, v36
	v_mul_f32_e32 v38, v38, v38
	v_fmac_f32_e32 v38, v33, v33
	v_cvt_pk_bf16_f32 v37, v40, v41
	v_add_f32_e32 v32, v32, v38
	v_and_b32_e32 v38, 0xffff0000, v37
	v_lshlrev_b32_e32 v33, 16, v37
	v_mul_f32_e32 v38, v38, v38
	v_fmac_f32_e32 v38, v33, v33
	v_add_f32_e32 v32, v32, v38
	v_mov_b32_e32 v33, v32
	s_nop 1
	v_permlane16_swap_b32_e32 v33, v32
	global_store_dwordx4 v[44:45], v[34:37], off offset:256 nt
	s_waitcnt lgkmcnt(0)
	v_add_f32_e32 v32, v32, v33
	v_mov_b32_e32 v33, v32
	s_nop 1
	v_permlane32_swap_b32_e32 v33, v32
	s_and_saveexec_b64 s[6:7], vcc
	s_cbranch_execz .LBB0_390
	v_lshlrev_b64 v[34:35], 6, v[76:77]
	v_lshl_add_u64 v[34:35], s[46:47], 0, v[34:35]
	v_lshl_add_u64 v[34:35], s[56:57], 2, v[34:35]
	s_lshl_b32 s38, s8, 2
	v_lshl_add_u64 v[34:35], v[34:35], 0, s[38:39]
	s_waitcnt lgkmcnt(0)
	v_add_f32_e32 v32, v32, v33
	global_store_dword v[34:35], v32, off
.LBB0_390:
	s_or_b64 exec, exec, s[6:7]
	v_add_u32_e32 v48, 0xa0, v170
	v_ashrrev_i32_e32 v49, 31, v48
	v_lshlrev_b64 v[54:55], 11, v[48:49]
	s_waitcnt lgkmcnt(0)
	v_lshl_add_u64 v[32:33], v[172:173], 0, v[54:55]
	global_load_dwordx4 v[50:53], v[32:33], off
	global_load_dwordx4 v[40:43], v[32:33], off offset:256
	v_add_u32_e32 v44, 0xb0, v170
	v_ashrrev_i32_e32 v45, 31, v44
	v_lshlrev_b64 v[46:47], 11, v[44:45]
	v_lshl_add_u64 v[32:33], v[172:173], 0, v[46:47]
	global_load_dwordx4 v[36:39], v[32:33], off
	s_nop 0
	global_load_dwordx4 v[32:35], v[32:33], off offset:256
	s_waitcnt vmcnt(0)
	v_lshlrev_b32_e32 v56, 16, v50
	v_and_b32_e32 v57, 0xffff0000, v50
	v_lshlrev_b32_e32 v50, 16, v51
	v_and_b32_e32 v51, 0xffff0000, v51
	v_lshlrev_b32_e32 v58, 16, v52
	v_and_b32_e32 v59, 0xffff0000, v52
	v_lshlrev_b32_e32 v52, 16, v53
	v_and_b32_e32 v53, 0xffff0000, v53
	v_pk_add_f32 v[28:29], v[28:29], v[56:57]
	v_pk_add_f32 v[30:31], v[30:31], v[50:51]
	v_pk_add_f32 v[50:51], v[26:27], v[52:53]
	v_pk_add_f32 v[26:27], v[24:25], v[58:59]
	v_cvt_pk_bf16_f32 v24, v28, v29
	v_lshl_add_u64 v[28:29], s[68:69], 0, v[54:55]
	v_lshl_add_u64 v[28:29], v[168:169], 1, v[28:29]
	v_cvt_pk_bf16_f32 v25, v30, v31
	v_cvt_pk_bf16_f32 v26, v26, v27
	v_cvt_pk_bf16_f32 v27, v50, v51
	global_store_dwordx4 v[28:29], v[24:27], off nt
	v_lshlrev_b32_e32 v30, 16, v24
	v_and_b32_e32 v31, 0xffff0000, v42
	v_and_b32_e32 v24, 0xffff0000, v24
	v_mul_f32_e32 v24, v24, v24
	v_fmac_f32_e32 v24, v30, v30
	v_lshlrev_b32_e32 v30, 16, v25
	v_and_b32_e32 v25, 0xffff0000, v25
	v_mul_f32_e32 v25, v25, v25
	v_fmac_f32_e32 v25, v30, v30
	v_add_f32_e32 v24, v24, v25
	v_lshlrev_b32_e32 v25, 16, v26
	v_and_b32_e32 v26, 0xffff0000, v26
	v_mul_f32_e32 v26, v26, v26
	v_fmac_f32_e32 v26, v25, v25
	v_add_f32_e32 v24, v24, v26
	v_and_b32_e32 v26, 0xffff0000, v27
	v_lshlrev_b32_e32 v25, 16, v27
	v_mul_f32_e32 v26, v26, v26
	v_fmac_f32_e32 v26, v25, v25
	v_add_f32_e32 v50, v24, v26
	v_lshlrev_b32_e32 v24, 16, v40
	v_and_b32_e32 v25, 0xffff0000, v40
	v_lshlrev_b32_e32 v26, 16, v41
	v_and_b32_e32 v27, 0xffff0000, v41
	v_lshlrev_b32_e32 v30, 16, v42
	v_lshlrev_b32_e32 v40, 16, v43
	v_and_b32_e32 v41, 0xffff0000, v43
	v_pk_add_f32 v[20:21], v[20:21], v[24:25]
	v_pk_add_f32 v[24:25], v[18:19], v[40:41]
	v_pk_add_f32 v[18:19], v[16:17], v[30:31]
	v_cvt_pk_bf16_f32 v16, v20, v21
	v_pk_add_f32 v[22:23], v[22:23], v[26:27]
	v_lshlrev_b32_e32 v20, 16, v16
	v_cvt_pk_bf16_f32 v17, v22, v23
	v_cvt_pk_bf16_f32 v18, v18, v19
	v_cvt_pk_bf16_f32 v19, v24, v25
	global_store_dwordx4 v[28:29], v[16:19], off offset:256 nt
	s_nop 1
	v_and_b32_e32 v16, 0xffff0000, v16
	v_mul_f32_e32 v16, v16, v16
	v_fmac_f32_e32 v16, v20, v20
	v_lshlrev_b32_e32 v20, 16, v17
	v_and_b32_e32 v17, 0xffff0000, v17
	v_mul_f32_e32 v17, v17, v17
	v_add_f32_e32 v16, v50, v16
	v_fmac_f32_e32 v17, v20, v20
	v_add_f32_e32 v16, v16, v17
	v_lshlrev_b32_e32 v17, 16, v18
	v_and_b32_e32 v18, 0xffff0000, v18
	v_mul_f32_e32 v18, v18, v18
	v_fmac_f32_e32 v18, v17, v17
	v_add_f32_e32 v16, v16, v18
	v_and_b32_e32 v18, 0xffff0000, v19
	v_lshlrev_b32_e32 v17, 16, v19
	v_mul_f32_e32 v18, v18, v18
	v_fmac_f32_e32 v18, v17, v17
	v_add_f32_e32 v16, v16, v18
	v_mov_b32_e32 v17, v16
	s_nop 1
	v_permlane16_swap_b32_e32 v17, v16
	s_waitcnt lgkmcnt(0)
	v_add_f32_e32 v16, v16, v17
	v_mov_b32_e32 v17, v16
	s_nop 1
	v_permlane32_swap_b32_e32 v17, v16
	s_and_saveexec_b64 s[6:7], vcc
	s_cbranch_execz .LBB0_392
	v_lshlrev_b64 v[18:19], 6, v[48:49]
	v_lshl_add_u64 v[18:19], s[46:47], 0, v[18:19]
	v_lshl_add_u64 v[18:19], s[56:57], 2, v[18:19]
	s_lshl_b32 s38, s8, 2
	v_lshl_add_u64 v[18:19], v[18:19], 0, s[38:39]
	s_waitcnt lgkmcnt(0)
	v_add_f32_e32 v16, v16, v17
	global_store_dword v[18:19], v16, off
.LBB0_392:
	s_or_b64 exec, exec, s[6:7]
	v_lshlrev_b32_e32 v16, 16, v36
	s_waitcnt lgkmcnt(0)
	v_and_b32_e32 v17, 0xffff0000, v36
	v_lshlrev_b32_e32 v20, 16, v38
	v_and_b32_e32 v21, 0xffff0000, v38
	v_lshlrev_b32_e32 v22, 16, v39
	v_and_b32_e32 v23, 0xffff0000, v39
	v_pk_add_f32 v[12:13], v[12:13], v[16:17]
	v_lshlrev_b32_e32 v18, 16, v37
	v_and_b32_e32 v19, 0xffff0000, v37
	v_pk_add_f32 v[16:17], v[10:11], v[22:23]
	v_pk_add_f32 v[10:11], v[8:9], v[20:21]
	v_cvt_pk_bf16_f32 v8, v12, v13
	v_lshl_add_u64 v[12:13], s[68:69], 0, v[46:47]
	v_pk_add_f32 v[14:15], v[14:15], v[18:19]
	v_lshl_add_u64 v[12:13], v[168:169], 1, v[12:13]
	v_cvt_pk_bf16_f32 v9, v14, v15
	v_cvt_pk_bf16_f32 v10, v10, v11
	v_cvt_pk_bf16_f32 v11, v16, v17
	global_store_dwordx4 v[12:13], v[8:11], off nt
	v_lshlrev_b32_e32 v14, 16, v8
	v_and_b32_e32 v15, 0xffff0000, v34
	v_and_b32_e32 v8, 0xffff0000, v8
	v_mul_f32_e32 v8, v8, v8
	v_fmac_f32_e32 v8, v14, v14
	v_lshlrev_b32_e32 v14, 16, v9
	v_and_b32_e32 v9, 0xffff0000, v9
	v_mul_f32_e32 v9, v9, v9
	v_fmac_f32_e32 v9, v14, v14
	v_add_f32_e32 v8, v8, v9
	v_lshlrev_b32_e32 v9, 16, v10
	v_and_b32_e32 v10, 0xffff0000, v10
	v_mul_f32_e32 v10, v10, v10
	v_fmac_f32_e32 v10, v9, v9
	v_add_f32_e32 v8, v8, v10
	v_and_b32_e32 v10, 0xffff0000, v11
	v_lshlrev_b32_e32 v9, 16, v11
	v_mul_f32_e32 v10, v10, v10
	v_fmac_f32_e32 v10, v9, v9
	v_add_f32_e32 v18, v8, v10
	v_lshlrev_b32_e32 v8, 16, v32
	v_and_b32_e32 v9, 0xffff0000, v32
	v_lshlrev_b32_e32 v14, 16, v34
	v_lshlrev_b32_e32 v10, 16, v33
	v_and_b32_e32 v11, 0xffff0000, v33
	v_lshlrev_b32_e32 v16, 16, v35
	v_and_b32_e32 v17, 0xffff0000, v35
	v_pk_add_f32 v[4:5], v[4:5], v[8:9]
	v_pk_add_f32 v[0:1], v[0:1], v[14:15]
	v_pk_add_f32 v[6:7], v[6:7], v[10:11]
	v_pk_add_f32 v[8:9], v[2:3], v[16:17]
	v_cvt_pk_bf16_f32 v2, v4, v5
	v_cvt_pk_bf16_f32 v3, v6, v7
	v_cvt_pk_bf16_f32 v4, v0, v1
	s_nop 0
	v_and_b32_e32 v1, 0xffff0000, v2
	v_lshlrev_b32_e32 v0, 16, v2
	v_mul_f32_e32 v1, v1, v1
	v_fmac_f32_e32 v1, v0, v0
	v_and_b32_e32 v6, 0xffff0000, v3
	v_add_f32_e32 v0, v18, v1
	v_lshlrev_b32_e32 v1, 16, v3
	v_mul_f32_e32 v6, v6, v6
	v_fmac_f32_e32 v6, v1, v1
	v_add_f32_e32 v0, v0, v6
	v_and_b32_e32 v6, 0xffff0000, v4
	v_lshlrev_b32_e32 v1, 16, v4
	v_mul_f32_e32 v6, v6, v6
	v_fmac_f32_e32 v6, v1, v1
	v_cvt_pk_bf16_f32 v5, v8, v9
	v_add_f32_e32 v0, v0, v6
	v_and_b32_e32 v6, 0xffff0000, v5
	v_lshlrev_b32_e32 v1, 16, v5
	v_mul_f32_e32 v6, v6, v6
	v_fmac_f32_e32 v6, v1, v1
	v_add_f32_e32 v0, v0, v6
	v_mov_b32_e32 v1, v0
	s_nop 1
	v_permlane16_swap_b32_e32 v1, v0
	global_store_dwordx4 v[12:13], v[2:5], off offset:256 nt
	s_waitcnt lgkmcnt(0)
	v_add_f32_e32 v0, v0, v1
	v_mov_b32_e32 v1, v0
	s_nop 1
	v_permlane32_swap_b32_e32 v1, v0
	s_and_saveexec_b64 s[6:7], vcc
	s_cbranch_execz .LBB0_394
	v_lshlrev_b64 v[2:3], 6, v[44:45]
	v_lshl_add_u64 v[2:3], s[46:47], 0, v[2:3]
	v_lshl_add_u64 v[2:3], s[56:57], 2, v[2:3]
	s_lshl_b32 s38, s8, 2
	v_lshl_add_u64 v[2:3], v[2:3], 0, s[38:39]
	s_waitcnt lgkmcnt(0)
	v_add_f32_e32 v0, v0, v1
	global_store_dword v[2:3], v0, off

.LBB0_419:
	s_mov_b32 s6, -1
	s_lshl_b32 s5, s5, 8
	v_mbcnt_lo_u32_b32 v112, s6, 0
	v_mbcnt_hi_u32_b32 v112, s6, v112
	s_getreg_b32 s6, hwreg(HW_REG_HW_ID, 0, 6)
	s_and_b32 s6, s6, 63
	s_lshl_b32 s6, s6, 2
	s_add_i32 s6, s6, 0
	s_add_i32 s6, s6, 0x20200
	v_mov_b32_e32 v113, s6
	ds_read_b32 v113, v113
	v_bfrev_b32_e32 v114, 0.5
	s_movk_i32 s84, 0x80
	s_lshl_b32 s58, s4, 2
	s_ashr_i32 s59, s58, 31
	s_waitcnt lgkmcnt(0)
	v_readfirstlane_b32 s6, v113
	s_nop 1
	v_lshl_add_u32 v112, s6, 6, v112
	s_nop 0
	v_readfirstlane_b32 s6, v112
	s_bfe_u32 s8, s6, 0x20006
	s_ashr_i32 s6, s6, 2
	s_andn2_b32 s6, s6, 63
	s_add_i32 s6, s6, s5
	v_and_or_b32 v166, v112, 15, s6
	s_lshl_b32 s5, s4, 8
	s_lshl_b32 s6, s8, 5
	v_bfe_u32 v113, v112, 4, 2
	s_or_b32 s5, s6, s5
	v_lshl_or_b32 v164, v113, 3, s5
	v_ashrrev_i32_e32 v165, 31, v164
	v_lshlrev_b64 v[146:147], 1, v[164:165]
	v_ashrrev_i32_e32 v167, 31, v166
	v_lshlrev_b32_e32 v112, 2, v112
	v_lshl_add_u64 v[168:169], s[68:69], 0, v[146:147]
	v_lshlrev_b64 v[148:149], 11, v[166:167]
	v_bitop3_b32 v176, v112, 64, v114 bitop3:0x6c
	v_bitop3_b32 v177, v112, s84, v114 bitop3:0x6c
	v_cmp_eq_u32_e32 vcc, 0, v113
	v_lshl_add_u64 v[112:113], v[168:169], 0, v[148:149]
	global_load_dwordx4 v[142:145], v[112:113], off
	global_load_dwordx4 v[128:131], v[112:113], off offset:256
	v_or_b32_e32 v170, 16, v166
	v_ashrrev_i32_e32 v171, 31, v170
	v_lshlrev_b64 v[172:173], 11, v[170:171]
	v_lshl_add_u64 v[112:113], v[168:169], 0, v[172:173]
	global_load_dwordx4 v[116:119], v[112:113], off
	s_nop 0
	global_load_dwordx4 v[112:115], v[112:113], off offset:256
	s_waitcnt vmcnt(0)
	v_lshlrev_b32_e32 v150, 16, v142
	v_and_b32_e32 v151, 0xffff0000, v142
	v_lshlrev_b32_e32 v142, 16, v143
	v_and_b32_e32 v143, 0xffff0000, v143
	v_lshlrev_b32_e32 v152, 16, v144
	v_and_b32_e32 v153, 0xffff0000, v144
	v_pk_add_f32 v[134:135], v[134:135], v[142:143]
	v_pk_add_f32 v[132:133], v[132:133], v[150:151]
	v_pk_add_f32 v[136:137], v[136:137], v[152:153]
	v_lshlrev_b32_e32 v144, 16, v145
	v_and_b32_e32 v145, 0xffff0000, v145
	v_cvt_pk_bf16_f32 v132, v132, v133
	v_cvt_pk_bf16_f32 v133, v134, v135
	v_cvt_pk_bf16_f32 v134, v136, v137
	v_lshl_add_u64 v[136:137], s[68:69], 0, v[148:149]
	v_pk_add_f32 v[138:139], v[138:139], v[144:145]
	v_lshl_add_u64 v[136:137], v[136:137], 0, v[146:147]
	v_cvt_pk_bf16_f32 v135, v138, v139
	global_store_dwordx4 v[136:137], v[132:135], off nt
	v_lshlrev_b32_e32 v138, 16, v132
	s_nop 0
	v_and_b32_e32 v132, 0xffff0000, v132
	v_mul_f32_e32 v132, v132, v132
	v_fmac_f32_e32 v132, v138, v138
	v_lshlrev_b32_e32 v138, 16, v133
	v_and_b32_e32 v133, 0xffff0000, v133
	v_mul_f32_e32 v133, v133, v133
	v_fmac_f32_e32 v133, v138, v138
	v_add_f32_e32 v132, v132, v133
	v_lshlrev_b32_e32 v133, 16, v134
	v_and_b32_e32 v134, 0xffff0000, v134
	v_mul_f32_e32 v134, v134, v134
	v_fmac_f32_e32 v134, v133, v133
	v_add_f32_e32 v132, v132, v134
	v_and_b32_e32 v134, 0xffff0000, v135
	v_lshlrev_b32_e32 v133, 16, v135
	v_mul_f32_e32 v134, v134, v134
	v_fmac_f32_e32 v134, v133, v133
	v_add_f32_e32 v138, v132, v134
	v_lshlrev_b32_e32 v132, 16, v128
	v_and_b32_e32 v133, 0xffff0000, v128
	v_lshlrev_b32_e32 v128, 16, v129
	v_and_b32_e32 v129, 0xffff0000, v129
	v_lshlrev_b32_e32 v134, 16, v130
	v_and_b32_e32 v135, 0xffff0000, v130
	v_lshlrev_b32_e32 v130, 16, v131
	v_and_b32_e32 v131, 0xffff0000, v131
	v_pk_add_f32 v[126:127], v[126:127], v[128:129]
	v_pk_add_f32 v[124:125], v[124:125], v[132:133]
	v_pk_add_f32 v[128:129], v[122:123], v[130:131]
	v_pk_add_f32 v[122:123], v[120:121], v[134:135]
	v_cvt_pk_bf16_f32 v120, v124, v125
	v_cvt_pk_bf16_f32 v121, v126, v127
	s_nop 0
	v_cvt_pk_bf16_f32 v122, v122, v123
	v_cvt_pk_bf16_f32 v123, v128, v129
	global_store_dwordx4 v[136:137], v[120:123], off offset:256 nt
	v_lshlrev_b32_e32 v124, 16, v120
	s_nop 0
	v_and_b32_e32 v120, 0xffff0000, v120
	v_mul_f32_e32 v120, v120, v120
	v_fmac_f32_e32 v120, v124, v124
	v_lshlrev_b32_e32 v124, 16, v121
	v_and_b32_e32 v121, 0xffff0000, v121
	v_mul_f32_e32 v121, v121, v121
	v_add_f32_e32 v120, v138, v120
	v_fmac_f32_e32 v121, v124, v124
	v_add_f32_e32 v120, v120, v121
	v_lshlrev_b32_e32 v121, 16, v122
	v_and_b32_e32 v122, 0xffff0000, v122
	v_mul_f32_e32 v122, v122, v122
	v_fmac_f32_e32 v122, v121, v121
	v_add_f32_e32 v120, v120, v122
	v_and_b32_e32 v122, 0xffff0000, v123
	v_lshlrev_b32_e32 v121, 16, v123
	v_mul_f32_e32 v122, v122, v122
	v_fmac_f32_e32 v122, v121, v121
	v_add_f32_e32 v120, v120, v122
	v_mov_b32_e32 v121, v120
	s_nop 1
	v_permlane16_swap_b32_e32 v121, v120
	s_waitcnt lgkmcnt(0)
	v_add_f32_e32 v120, v120, v121
	v_mov_b32_e32 v121, v120
	s_nop 1
	v_permlane32_swap_b32_e32 v121, v120
	s_and_saveexec_b64 s[6:7], vcc
	s_cbranch_execz .LBB0_421
	s_waitcnt lgkmcnt(0)
	v_add_f32_e32 v122, v120, v121
	v_lshlrev_b64 v[120:121], 6, v[166:167]
	v_lshl_add_u64 v[120:121], s[46:47], 0, v[120:121]
	v_lshl_add_u64 v[120:121], s[58:59], 2, v[120:121]
	s_lshl_b32 s38, s8, 2
	v_lshl_add_u64 v[120:121], v[120:121], 0, s[38:39]
	global_store_dword v[120:121], v122, off
.LBB0_421:
	s_or_b64 exec, exec, s[6:7]
	v_lshlrev_b32_e32 v120, 16, v116
	s_waitcnt lgkmcnt(0)
	v_and_b32_e32 v121, 0xffff0000, v116
	v_lshlrev_b32_e32 v116, 16, v117
	v_and_b32_e32 v117, 0xffff0000, v117
	v_lshlrev_b32_e32 v122, 16, v118
	v_and_b32_e32 v123, 0xffff0000, v118
	v_lshlrev_b32_e32 v118, 16, v119
	v_and_b32_e32 v119, 0xffff0000, v119
	v_pk_add_f32 v[108:109], v[108:109], v[120:121]
	v_pk_add_f32 v[110:111], v[110:111], v[116:117]
	v_pk_add_f32 v[116:117], v[106:107], v[118:119]
	v_pk_add_f32 v[106:107], v[104:105], v[122:123]
	v_cvt_pk_bf16_f32 v104, v108, v109
	v_lshl_add_u64 v[108:109], s[68:69], 0, v[172:173]
	v_lshl_add_u64 v[108:109], v[164:165], 1, v[108:109]
	v_cvt_pk_bf16_f32 v105, v110, v111
	v_cvt_pk_bf16_f32 v106, v106, v107
	v_cvt_pk_bf16_f32 v107, v116, v117
	global_store_dwordx4 v[108:109], v[104:107], off nt
	v_lshlrev_b32_e32 v110, 16, v104
	v_and_b32_e32 v111, 0xffff0000, v114
	v_and_b32_e32 v104, 0xffff0000, v104
	v_mul_f32_e32 v104, v104, v104
	v_fmac_f32_e32 v104, v110, v110
	v_lshlrev_b32_e32 v110, 16, v105
	v_and_b32_e32 v105, 0xffff0000, v105
	v_mul_f32_e32 v105, v105, v105
	v_fmac_f32_e32 v105, v110, v110
	v_add_f32_e32 v104, v104, v105
	v_lshlrev_b32_e32 v105, 16, v106
	v_and_b32_e32 v106, 0xffff0000, v106
	v_mul_f32_e32 v106, v106, v106
	v_fmac_f32_e32 v106, v105, v105
	v_add_f32_e32 v104, v104, v106
	v_and_b32_e32 v106, 0xffff0000, v107
	v_lshlrev_b32_e32 v105, 16, v107
	v_mul_f32_e32 v106, v106, v106
	v_fmac_f32_e32 v106, v105, v105
	v_add_f32_e32 v116, v104, v106
	v_lshlrev_b32_e32 v104, 16, v112
	v_and_b32_e32 v105, 0xffff0000, v112
	v_lshlrev_b32_e32 v110, 16, v114
	v_lshlrev_b32_e32 v106, 16, v113
	v_and_b32_e32 v107, 0xffff0000, v113
	v_lshlrev_b32_e32 v112, 16, v115
	v_and_b32_e32 v113, 0xffff0000, v115
	v_pk_add_f32 v[100:101], v[100:101], v[104:105]
	v_pk_add_f32 v[96:97], v[96:97], v[110:111]
	v_pk_add_f32 v[102:103], v[102:103], v[106:107]
	v_pk_add_f32 v[104:105], v[98:99], v[112:113]
	v_cvt_pk_bf16_f32 v98, v100, v101
	v_cvt_pk_bf16_f32 v99, v102, v103
	v_cvt_pk_bf16_f32 v100, v96, v97
	s_nop 0
	v_and_b32_e32 v97, 0xffff0000, v98
	v_lshlrev_b32_e32 v96, 16, v98
	v_mul_f32_e32 v97, v97, v97
	v_fmac_f32_e32 v97, v96, v96
	v_and_b32_e32 v102, 0xffff0000, v99
	v_add_f32_e32 v96, v116, v97
	v_lshlrev_b32_e32 v97, 16, v99
	v_mul_f32_e32 v102, v102, v102
	v_fmac_f32_e32 v102, v97, v97
	v_add_f32_e32 v96, v96, v102
	v_and_b32_e32 v102, 0xffff0000, v100
	v_lshlrev_b32_e32 v97, 16, v100
	v_mul_f32_e32 v102, v102, v102
	v_fmac_f32_e32 v102, v97, v97
	v_cvt_pk_bf16_f32 v101, v104, v105
	v_add_f32_e32 v96, v96, v102
	v_and_b32_e32 v102, 0xffff0000, v101
	v_lshlrev_b32_e32 v97, 16, v101
	v_mul_f32_e32 v102, v102, v102
	v_fmac_f32_e32 v102, v97, v97
	v_add_f32_e32 v96, v96, v102
	v_mov_b32_e32 v97, v96
	s_nop 1
	v_permlane16_swap_b32_e32 v97, v96
	global_store_dwordx4 v[108:109], v[98:101], off offset:256 nt
	s_waitcnt lgkmcnt(0)
	v_add_f32_e32 v96, v96, v97
	v_mov_b32_e32 v97, v96
	s_nop 1
	v_permlane32_swap_b32_e32 v97, v96
	s_mov_b64 s[6:7], exec
	s_and_b64 s[4:5], s[6:7], vcc
	v_mov_b32_e32 v198, v246
	v_mov_b32_e32 v199, v247
	v_mov_b32_e32 v205, v249
	v_mov_b32_e32 v196, v251
	v_mov_b32_e32 v251, 0x260
	s_mov_b64 exec, s[4:5]
	s_cbranch_execz .LBB0_423
	s_waitcnt lgkmcnt(0)
	v_add_f32_e32 v98, v96, v97
	v_lshlrev_b64 v[96:97], 6, v[170:171]
	v_lshl_add_u64 v[96:97], s[46:47], 0, v[96:97]
	v_lshl_add_u64 v[96:97], s[58:59], 2, v[96:97]
	s_lshl_b32 s38, s8, 2
	v_lshl_add_u64 v[96:97], v[96:97], 0, s[38:39]
	global_store_dword v[96:97], v98, off
.LBB0_423:
	s_or_b64 exec, exec, s[6:7]
	v_or_b32_e32 v112, 32, v166
	v_ashrrev_i32_e32 v113, 31, v112
	v_lshlrev_b64 v[118:119], 11, v[112:113]
	s_waitcnt lgkmcnt(0)
	v_lshl_add_u64 v[96:97], v[168:169], 0, v[118:119]
	global_load_dwordx4 v[114:117], v[96:97], off
	global_load_dwordx4 v[104:107], v[96:97], off offset:256
	v_or_b32_e32 v108, 48, v166
	v_ashrrev_i32_e32 v109, 31, v108
	v_lshlrev_b64 v[110:111], 11, v[108:109]
	v_lshl_add_u64 v[96:97], v[168:169], 0, v[110:111]
	global_load_dwordx4 v[100:103], v[96:97], off
	s_nop 0
	global_load_dwordx4 v[96:99], v[96:97], off offset:256
	s_waitcnt vmcnt(0)
	v_lshlrev_b32_e32 v120, 16, v114
	v_and_b32_e32 v121, 0xffff0000, v114
	v_lshlrev_b32_e32 v114, 16, v115
	v_and_b32_e32 v115, 0xffff0000, v115
	v_lshlrev_b32_e32 v122, 16, v116
	v_and_b32_e32 v123, 0xffff0000, v116
	v_pk_add_f32 v[90:91], v[90:91], v[114:115]
	v_pk_add_f32 v[88:89], v[88:89], v[120:121]
	v_pk_add_f32 v[92:93], v[92:93], v[122:123]
	v_lshlrev_b32_e32 v116, 16, v117
	v_and_b32_e32 v117, 0xffff0000, v117
	v_cvt_pk_bf16_f32 v88, v88, v89
	v_cvt_pk_bf16_f32 v89, v90, v91
	v_cvt_pk_bf16_f32 v90, v92, v93
	v_lshl_add_u64 v[92:93], s[68:69], 0, v[118:119]
	v_pk_add_f32 v[94:95], v[94:95], v[116:117]
	v_lshl_add_u64 v[92:93], v[164:165], 1, v[92:93]
	v_cvt_pk_bf16_f32 v91, v94, v95
	global_store_dwordx4 v[92:93], v[88:91], off nt
	v_lshlrev_b32_e32 v94, 16, v88
	v_and_b32_e32 v95, 0xffff0000, v106
	v_and_b32_e32 v88, 0xffff0000, v88
	v_mul_f32_e32 v88, v88, v88
	v_fmac_f32_e32 v88, v94, v94
	v_lshlrev_b32_e32 v94, 16, v89
	v_and_b32_e32 v89, 0xffff0000, v89
	v_mul_f32_e32 v89, v89, v89
	v_fmac_f32_e32 v89, v94, v94
	v_add_f32_e32 v88, v88, v89
	v_lshlrev_b32_e32 v89, 16, v90
	v_and_b32_e32 v90, 0xffff0000, v90
	v_mul_f32_e32 v90, v90, v90
	v_fmac_f32_e32 v90, v89, v89
	v_add_f32_e32 v88, v88, v90
	v_and_b32_e32 v90, 0xffff0000, v91
	v_lshlrev_b32_e32 v89, 16, v91
	v_mul_f32_e32 v90, v90, v90
	v_fmac_f32_e32 v90, v89, v89
	v_add_f32_e32 v114, v88, v90
	v_lshlrev_b32_e32 v88, 16, v104
	v_and_b32_e32 v89, 0xffff0000, v104
	v_lshlrev_b32_e32 v90, 16, v105
	v_and_b32_e32 v91, 0xffff0000, v105
	v_lshlrev_b32_e32 v94, 16, v106
	v_lshlrev_b32_e32 v104, 16, v107
	v_and_b32_e32 v105, 0xffff0000, v107
	v_pk_add_f32 v[84:85], v[84:85], v[88:89]
	v_pk_add_f32 v[88:89], v[82:83], v[104:105]
	v_pk_add_f32 v[82:83], v[80:81], v[94:95]
	v_cvt_pk_bf16_f32 v80, v84, v85
	v_pk_add_f32 v[86:87], v[86:87], v[90:91]
	v_lshlrev_b32_e32 v84, 16, v80
	v_cvt_pk_bf16_f32 v81, v86, v87
	v_cvt_pk_bf16_f32 v82, v82, v83
	v_cvt_pk_bf16_f32 v83, v88, v89
	global_store_dwordx4 v[92:93], v[80:83], off offset:256 nt
	s_nop 1
	v_and_b32_e32 v80, 0xffff0000, v80
	v_mul_f32_e32 v80, v80, v80
	v_fmac_f32_e32 v80, v84, v84
	v_lshlrev_b32_e32 v84, 16, v81
	v_and_b32_e32 v81, 0xffff0000, v81
	v_mul_f32_e32 v81, v81, v81
	v_add_f32_e32 v80, v114, v80
	v_fmac_f32_e32 v81, v84, v84
	v_add_f32_e32 v80, v80, v81
	v_lshlrev_b32_e32 v81, 16, v82
	v_and_b32_e32 v82, 0xffff0000, v82
	v_mul_f32_e32 v82, v82, v82
	v_fmac_f32_e32 v82, v81, v81
	v_add_f32_e32 v80, v80, v82
	v_and_b32_e32 v82, 0xffff0000, v83
	v_lshlrev_b32_e32 v81, 16, v83
	v_mul_f32_e32 v82, v82, v82
	v_fmac_f32_e32 v82, v81, v81
	v_add_f32_e32 v80, v80, v82
	v_mov_b32_e32 v81, v80
	s_nop 1
	v_permlane16_swap_b32_e32 v81, v80
	s_waitcnt lgkmcnt(0)
	v_add_f32_e32 v80, v80, v81
	v_mov_b32_e32 v81, v80
	s_nop 1
	v_permlane32_swap_b32_e32 v81, v80
	s_and_saveexec_b64 s[6:7], vcc
	s_cbranch_execz .LBB0_425
	s_waitcnt lgkmcnt(0)
	v_add_f32_e32 v82, v80, v81
	v_lshlrev_b64 v[80:81], 6, v[112:113]
	v_lshl_add_u64 v[80:81], s[46:47], 0, v[80:81]
	v_lshl_add_u64 v[80:81], s[58:59], 2, v[80:81]
	s_lshl_b32 s38, s8, 2
	v_lshl_add_u64 v[80:81], v[80:81], 0, s[38:39]
	global_store_dword v[80:81], v82, off
.LBB0_425:
	s_or_b64 exec, exec, s[6:7]
	v_lshlrev_b32_e32 v80, 16, v100
	s_waitcnt lgkmcnt(0)
	v_and_b32_e32 v81, 0xffff0000, v100
	v_lshlrev_b32_e32 v84, 16, v102
	v_and_b32_e32 v85, 0xffff0000, v102
	v_lshlrev_b32_e32 v86, 16, v103
	v_and_b32_e32 v87, 0xffff0000, v103
	v_pk_add_f32 v[76:77], v[76:77], v[80:81]
	v_lshlrev_b32_e32 v82, 16, v101
	v_and_b32_e32 v83, 0xffff0000, v101
	v_pk_add_f32 v[80:81], v[74:75], v[86:87]
	v_pk_add_f32 v[74:75], v[72:73], v[84:85]
	v_cvt_pk_bf16_f32 v72, v76, v77
	v_lshl_add_u64 v[76:77], s[68:69], 0, v[110:111]
	v_pk_add_f32 v[78:79], v[78:79], v[82:83]
	v_lshl_add_u64 v[76:77], v[164:165], 1, v[76:77]
	v_cvt_pk_bf16_f32 v73, v78, v79
	v_cvt_pk_bf16_f32 v74, v74, v75
	v_cvt_pk_bf16_f32 v75, v80, v81
	global_store_dwordx4 v[76:77], v[72:75], off nt
	v_lshlrev_b32_e32 v78, 16, v72
	v_and_b32_e32 v79, 0xffff0000, v98
	v_and_b32_e32 v72, 0xffff0000, v72
	v_mul_f32_e32 v72, v72, v72
	v_fmac_f32_e32 v72, v78, v78
	v_lshlrev_b32_e32 v78, 16, v73
	v_and_b32_e32 v73, 0xffff0000, v73
	v_mul_f32_e32 v73, v73, v73
	v_fmac_f32_e32 v73, v78, v78
	v_add_f32_e32 v72, v72, v73
	v_lshlrev_b32_e32 v73, 16, v74
	v_and_b32_e32 v74, 0xffff0000, v74
	v_mul_f32_e32 v74, v74, v74
	v_fmac_f32_e32 v74, v73, v73
	v_add_f32_e32 v72, v72, v74
	v_and_b32_e32 v74, 0xffff0000, v75
	v_lshlrev_b32_e32 v73, 16, v75
	v_mul_f32_e32 v74, v74, v74
	v_fmac_f32_e32 v74, v73, v73
	v_add_f32_e32 v82, v72, v74
	v_lshlrev_b32_e32 v72, 16, v96
	v_and_b32_e32 v73, 0xffff0000, v96
	v_lshlrev_b32_e32 v78, 16, v98
	v_lshlrev_b32_e32 v74, 16, v97
	v_and_b32_e32 v75, 0xffff0000, v97
	v_lshlrev_b32_e32 v80, 16, v99
	v_and_b32_e32 v81, 0xffff0000, v99
	v_pk_add_f32 v[68:69], v[68:69], v[72:73]
	v_pk_add_f32 v[64:65], v[64:65], v[78:79]
	v_pk_add_f32 v[70:71], v[70:71], v[74:75]
	v_pk_add_f32 v[72:73], v[66:67], v[80:81]
	v_cvt_pk_bf16_f32 v66, v68, v69
	v_cvt_pk_bf16_f32 v67, v70, v71
	v_cvt_pk_bf16_f32 v68, v64, v65
	s_nop 0
	v_and_b32_e32 v65, 0xffff0000, v66
	v_lshlrev_b32_e32 v64, 16, v66
	v_mul_f32_e32 v65, v65, v65
	v_fmac_f32_e32 v65, v64, v64
	v_and_b32_e32 v70, 0xffff0000, v67
	v_add_f32_e32 v64, v82, v65
	v_lshlrev_b32_e32 v65, 16, v67
	v_mul_f32_e32 v70, v70, v70
	v_fmac_f32_e32 v70, v65, v65
	v_add_f32_e32 v64, v64, v70
	v_and_b32_e32 v70, 0xffff0000, v68
	v_lshlrev_b32_e32 v65, 16, v68
	v_mul_f32_e32 v70, v70, v70
	v_fmac_f32_e32 v70, v65, v65
	v_cvt_pk_bf16_f32 v69, v72, v73
	v_add_f32_e32 v64, v64, v70
	v_and_b32_e32 v70, 0xffff0000, v69
	v_lshlrev_b32_e32 v65, 16, v69
	v_mul_f32_e32 v70, v70, v70
	v_fmac_f32_e32 v70, v65, v65
	v_add_f32_e32 v64, v64, v70
	v_mov_b32_e32 v65, v64
	s_nop 1
	v_permlane16_swap_b32_e32 v65, v64
	global_store_dwordx4 v[76:77], v[66:69], off offset:256 nt
	s_waitcnt lgkmcnt(0)
	v_add_f32_e32 v64, v64, v65
	v_mov_b32_e32 v65, v64
	s_nop 1
	v_permlane32_swap_b32_e32 v65, v64
	s_and_saveexec_b64 s[6:7], vcc
	s_cbranch_execz .LBB0_427
	s_waitcnt lgkmcnt(0)
	v_add_f32_e32 v66, v64, v65
	v_lshlrev_b64 v[64:65], 6, v[108:109]
	v_lshl_add_u64 v[64:65], s[46:47], 0, v[64:65]
	v_lshl_add_u64 v[64:65], s[58:59], 2, v[64:65]
	s_lshl_b32 s38, s8, 2
	v_lshl_add_u64 v[64:65], v[64:65], 0, s[38:39]
	global_store_dword v[64:65], v66, off
.LBB0_427:
	s_or_b64 exec, exec, s[6:7]
	v_add_u32_e32 v80, 0x80, v166
	v_ashrrev_i32_e32 v81, 31, v80
	v_lshlrev_b64 v[86:87], 11, v[80:81]
	s_waitcnt lgkmcnt(0)
	v_lshl_add_u64 v[64:65], v[168:169], 0, v[86:87]
	global_load_dwordx4 v[82:85], v[64:65], off
	global_load_dwordx4 v[72:75], v[64:65], off offset:256
	v_add_u32_e32 v76, 0x90, v166
	v_ashrrev_i32_e32 v77, 31, v76
	v_lshlrev_b64 v[78:79], 11, v[76:77]
	v_lshl_add_u64 v[64:65], v[168:169], 0, v[78:79]
	global_load_dwordx4 v[68:71], v[64:65], off
	s_nop 0
	global_load_dwordx4 v[64:67], v[64:65], off offset:256
	s_waitcnt vmcnt(0)
	v_lshlrev_b32_e32 v88, 16, v82
	v_and_b32_e32 v89, 0xffff0000, v82
	v_lshlrev_b32_e32 v82, 16, v83
	v_and_b32_e32 v83, 0xffff0000, v83
	v_lshlrev_b32_e32 v90, 16, v84
	v_and_b32_e32 v91, 0xffff0000, v84
	v_pk_add_f32 v[58:59], v[58:59], v[82:83]
	v_pk_add_f32 v[56:57], v[56:57], v[88:89]
	v_pk_add_f32 v[60:61], v[60:61], v[90:91]
	v_lshlrev_b32_e32 v84, 16, v85
	v_and_b32_e32 v85, 0xffff0000, v85
	v_cvt_pk_bf16_f32 v56, v56, v57
	v_cvt_pk_bf16_f32 v57, v58, v59
	v_cvt_pk_bf16_f32 v58, v60, v61
	v_lshl_add_u64 v[60:61], s[68:69], 0, v[86:87]
	v_pk_add_f32 v[62:63], v[62:63], v[84:85]
	v_lshl_add_u64 v[60:61], v[164:165], 1, v[60:61]
	v_cvt_pk_bf16_f32 v59, v62, v63
	global_store_dwordx4 v[60:61], v[56:59], off nt
	v_lshlrev_b32_e32 v62, 16, v56
	v_and_b32_e32 v63, 0xffff0000, v74
	v_and_b32_e32 v56, 0xffff0000, v56
	v_mul_f32_e32 v56, v56, v56
	v_fmac_f32_e32 v56, v62, v62
	v_lshlrev_b32_e32 v62, 16, v57
	v_and_b32_e32 v57, 0xffff0000, v57
	v_mul_f32_e32 v57, v57, v57
	v_fmac_f32_e32 v57, v62, v62
	v_add_f32_e32 v56, v56, v57
	v_lshlrev_b32_e32 v57, 16, v58
	v_and_b32_e32 v58, 0xffff0000, v58
	v_mul_f32_e32 v58, v58, v58
	v_fmac_f32_e32 v58, v57, v57
	v_add_f32_e32 v56, v56, v58
	v_and_b32_e32 v58, 0xffff0000, v59
	v_lshlrev_b32_e32 v57, 16, v59
	v_mul_f32_e32 v58, v58, v58
	v_fmac_f32_e32 v58, v57, v57
	v_add_f32_e32 v82, v56, v58
	v_lshlrev_b32_e32 v56, 16, v72
	v_and_b32_e32 v57, 0xffff0000, v72
	v_lshlrev_b32_e32 v58, 16, v73
	v_and_b32_e32 v59, 0xffff0000, v73
	v_lshlrev_b32_e32 v62, 16, v74
	v_lshlrev_b32_e32 v72, 16, v75
	v_and_b32_e32 v73, 0xffff0000, v75
	v_pk_add_f32 v[52:53], v[52:53], v[56:57]
	v_pk_add_f32 v[56:57], v[50:51], v[72:73]
	v_pk_add_f32 v[50:51], v[48:49], v[62:63]
	v_cvt_pk_bf16_f32 v48, v52, v53
	v_pk_add_f32 v[54:55], v[54:55], v[58:59]
	v_lshlrev_b32_e32 v52, 16, v48
	v_cvt_pk_bf16_f32 v49, v54, v55
	v_cvt_pk_bf16_f32 v50, v50, v51
	v_cvt_pk_bf16_f32 v51, v56, v57
	global_store_dwordx4 v[60:61], v[48:51], off offset:256 nt
	s_nop 1
	v_and_b32_e32 v48, 0xffff0000, v48
	v_mul_f32_e32 v48, v48, v48
	v_fmac_f32_e32 v48, v52, v52
	v_lshlrev_b32_e32 v52, 16, v49
	v_and_b32_e32 v49, 0xffff0000, v49
	v_mul_f32_e32 v49, v49, v49
	v_add_f32_e32 v48, v82, v48
	v_fmac_f32_e32 v49, v52, v52
	v_add_f32_e32 v48, v48, v49
	v_lshlrev_b32_e32 v49, 16, v50
	v_and_b32_e32 v50, 0xffff0000, v50
	v_mul_f32_e32 v50, v50, v50
	v_fmac_f32_e32 v50, v49, v49
	v_add_f32_e32 v48, v48, v50
	v_and_b32_e32 v50, 0xffff0000, v51
	v_lshlrev_b32_e32 v49, 16, v51
	v_mul_f32_e32 v50, v50, v50
	v_fmac_f32_e32 v50, v49, v49
	v_add_f32_e32 v48, v48, v50
	v_mov_b32_e32 v49, v48
	s_nop 1
	v_permlane16_swap_b32_e32 v49, v48
	s_waitcnt lgkmcnt(0)
	v_add_f32_e32 v48, v48, v49
	v_mov_b32_e32 v49, v48
	s_nop 1
	v_permlane32_swap_b32_e32 v49, v48
	s_and_saveexec_b64 s[6:7], vcc
	s_cbranch_execz .LBB0_429
	s_waitcnt lgkmcnt(0)
	v_add_f32_e32 v50, v48, v49
	v_lshlrev_b64 v[48:49], 6, v[80:81]
	v_lshl_add_u64 v[48:49], s[46:47], 0, v[48:49]
	v_lshl_add_u64 v[48:49], s[58:59], 2, v[48:49]
	s_lshl_b32 s38, s8, 2
	v_lshl_add_u64 v[48:49], v[48:49], 0, s[38:39]
	global_store_dword v[48:49], v50, off
.LBB0_429:
	s_or_b64 exec, exec, s[6:7]
	v_lshlrev_b32_e32 v48, 16, v68
	s_waitcnt lgkmcnt(0)
	v_and_b32_e32 v49, 0xffff0000, v68
	v_lshlrev_b32_e32 v52, 16, v70
	v_and_b32_e32 v53, 0xffff0000, v70
	v_lshlrev_b32_e32 v54, 16, v71
	v_and_b32_e32 v55, 0xffff0000, v71
	v_pk_add_f32 v[44:45], v[44:45], v[48:49]
	v_lshlrev_b32_e32 v50, 16, v69
	v_and_b32_e32 v51, 0xffff0000, v69
	v_pk_add_f32 v[48:49], v[42:43], v[54:55]
	v_pk_add_f32 v[42:43], v[40:41], v[52:53]
	v_cvt_pk_bf16_f32 v40, v44, v45
	v_lshl_add_u64 v[44:45], s[68:69], 0, v[78:79]
	v_pk_add_f32 v[46:47], v[46:47], v[50:51]
	v_lshl_add_u64 v[44:45], v[164:165], 1, v[44:45]
	v_cvt_pk_bf16_f32 v41, v46, v47
	v_cvt_pk_bf16_f32 v42, v42, v43
	v_cvt_pk_bf16_f32 v43, v48, v49
	global_store_dwordx4 v[44:45], v[40:43], off nt
	v_lshlrev_b32_e32 v46, 16, v40
	v_and_b32_e32 v47, 0xffff0000, v66
	v_and_b32_e32 v40, 0xffff0000, v40
	v_mul_f32_e32 v40, v40, v40
	v_fmac_f32_e32 v40, v46, v46
	v_lshlrev_b32_e32 v46, 16, v41
	v_and_b32_e32 v41, 0xffff0000, v41
	v_mul_f32_e32 v41, v41, v41
	v_fmac_f32_e32 v41, v46, v46
	v_add_f32_e32 v40, v40, v41
	v_lshlrev_b32_e32 v41, 16, v42
	v_and_b32_e32 v42, 0xffff0000, v42
	v_mul_f32_e32 v42, v42, v42
	v_fmac_f32_e32 v42, v41, v41
	v_add_f32_e32 v40, v40, v42
	v_and_b32_e32 v42, 0xffff0000, v43
	v_lshlrev_b32_e32 v41, 16, v43
	v_mul_f32_e32 v42, v42, v42
	v_fmac_f32_e32 v42, v41, v41
	v_add_f32_e32 v50, v40, v42
	v_lshlrev_b32_e32 v40, 16, v64
	v_and_b32_e32 v41, 0xffff0000, v64
	v_lshlrev_b32_e32 v46, 16, v66
	v_lshlrev_b32_e32 v42, 16, v65
	v_and_b32_e32 v43, 0xffff0000, v65
	v_lshlrev_b32_e32 v48, 16, v67
	v_and_b32_e32 v49, 0xffff0000, v67
	v_pk_add_f32 v[36:37], v[36:37], v[40:41]
	v_pk_add_f32 v[32:33], v[32:33], v[46:47]
	v_pk_add_f32 v[38:39], v[38:39], v[42:43]
	v_pk_add_f32 v[40:41], v[34:35], v[48:49]
	v_cvt_pk_bf16_f32 v34, v36, v37
	v_cvt_pk_bf16_f32 v35, v38, v39
	v_cvt_pk_bf16_f32 v36, v32, v33
	s_nop 0
	v_and_b32_e32 v33, 0xffff0000, v34
	v_lshlrev_b32_e32 v32, 16, v34
	v_mul_f32_e32 v33, v33, v33
	v_fmac_f32_e32 v33, v32, v32
	v_and_b32_e32 v38, 0xffff0000, v35
	v_add_f32_e32 v32, v50, v33
	v_lshlrev_b32_e32 v33, 16, v35
	v_mul_f32_e32 v38, v38, v38
	v_fmac_f32_e32 v38, v33, v33
	v_add_f32_e32 v32, v32, v38
	v_and_b32_e32 v38, 0xffff0000, v36
	v_lshlrev_b32_e32 v33, 16, v36
	v_mul_f32_e32 v38, v38, v38
	v_fmac_f32_e32 v38, v33, v33
	v_cvt_pk_bf16_f32 v37, v40, v41
	v_add_f32_e32 v32, v32, v38
	v_and_b32_e32 v38, 0xffff0000, v37
	v_lshlrev_b32_e32 v33, 16, v37
	v_mul_f32_e32 v38, v38, v38
	v_fmac_f32_e32 v38, v33, v33
	v_add_f32_e32 v32, v32, v38
	v_mov_b32_e32 v33, v32
	s_nop 1
	v_permlane16_swap_b32_e32 v33, v32
	global_store_dwordx4 v[44:45], v[34:37], off offset:256 nt
	s_waitcnt lgkmcnt(0)
	v_add_f32_e32 v32, v32, v33
	v_mov_b32_e32 v33, v32
	s_nop 1
	v_permlane32_swap_b32_e32 v33, v32
	s_and_saveexec_b64 s[6:7], vcc
	s_cbranch_execz .LBB0_431
	s_waitcnt lgkmcnt(0)
	v_add_f32_e32 v34, v32, v33
	v_lshlrev_b64 v[32:33], 6, v[76:77]
	v_lshl_add_u64 v[32:33], s[46:47], 0, v[32:33]
	v_lshl_add_u64 v[32:33], s[58:59], 2, v[32:33]
	s_lshl_b32 s38, s8, 2
	v_lshl_add_u64 v[32:33], v[32:33], 0, s[38:39]
	global_store_dword v[32:33], v34, off
.LBB0_431:
	s_or_b64 exec, exec, s[6:7]
	v_add_u32_e32 v48, 0xa0, v166
	v_ashrrev_i32_e32 v49, 31, v48
	v_lshlrev_b64 v[54:55], 11, v[48:49]
	s_waitcnt lgkmcnt(0)
	v_lshl_add_u64 v[32:33], v[168:169], 0, v[54:55]
	global_load_dwordx4 v[50:53], v[32:33], off
	global_load_dwordx4 v[40:43], v[32:33], off offset:256
	v_add_u32_e32 v44, 0xb0, v166
	v_ashrrev_i32_e32 v45, 31, v44
	v_lshlrev_b64 v[46:47], 11, v[44:45]
	v_lshl_add_u64 v[32:33], v[168:169], 0, v[46:47]
	global_load_dwordx4 v[36:39], v[32:33], off
	s_nop 0
	global_load_dwordx4 v[32:35], v[32:33], off offset:256
	s_waitcnt vmcnt(0)
	v_lshlrev_b32_e32 v56, 16, v50
	v_and_b32_e32 v57, 0xffff0000, v50
	v_lshlrev_b32_e32 v50, 16, v51
	v_and_b32_e32 v51, 0xffff0000, v51
	v_lshlrev_b32_e32 v58, 16, v52
	v_and_b32_e32 v59, 0xffff0000, v52
	v_pk_add_f32 v[26:27], v[26:27], v[50:51]
	v_pk_add_f32 v[24:25], v[24:25], v[56:57]
	v_pk_add_f32 v[28:29], v[28:29], v[58:59]
	v_lshlrev_b32_e32 v52, 16, v53
	v_and_b32_e32 v53, 0xffff0000, v53
	v_cvt_pk_bf16_f32 v24, v24, v25
	v_cvt_pk_bf16_f32 v25, v26, v27
	v_cvt_pk_bf16_f32 v26, v28, v29
	v_lshl_add_u64 v[28:29], s[68:69], 0, v[54:55]
	v_pk_add_f32 v[30:31], v[30:31], v[52:53]
	v_lshl_add_u64 v[28:29], v[164:165], 1, v[28:29]
	v_cvt_pk_bf16_f32 v27, v30, v31
	global_store_dwordx4 v[28:29], v[24:27], off nt
	v_lshlrev_b32_e32 v30, 16, v24
	v_and_b32_e32 v31, 0xffff0000, v42
	v_and_b32_e32 v24, 0xffff0000, v24
	v_mul_f32_e32 v24, v24, v24
	v_fmac_f32_e32 v24, v30, v30
	v_lshlrev_b32_e32 v30, 16, v25
	v_and_b32_e32 v25, 0xffff0000, v25
	v_mul_f32_e32 v25, v25, v25
	v_fmac_f32_e32 v25, v30, v30
	v_add_f32_e32 v24, v24, v25
	v_lshlrev_b32_e32 v25, 16, v26
	v_and_b32_e32 v26, 0xffff0000, v26
	v_mul_f32_e32 v26, v26, v26
	v_fmac_f32_e32 v26, v25, v25
	v_add_f32_e32 v24, v24, v26
	v_and_b32_e32 v26, 0xffff0000, v27
	v_lshlrev_b32_e32 v25, 16, v27
	v_mul_f32_e32 v26, v26, v26
	v_fmac_f32_e32 v26, v25, v25
	v_add_f32_e32 v50, v24, v26
	v_lshlrev_b32_e32 v24, 16, v40
	v_and_b32_e32 v25, 0xffff0000, v40
	v_lshlrev_b32_e32 v26, 16, v41
	v_and_b32_e32 v27, 0xffff0000, v41
	v_lshlrev_b32_e32 v30, 16, v42
	v_lshlrev_b32_e32 v40, 16, v43
	v_and_b32_e32 v41, 0xffff0000, v43
	v_pk_add_f32 v[20:21], v[20:21], v[24:25]
	v_pk_add_f32 v[24:25], v[18:19], v[40:41]
	v_pk_add_f32 v[18:19], v[16:17], v[30:31]
	v_cvt_pk_bf16_f32 v16, v20, v21
	v_pk_add_f32 v[22:23], v[22:23], v[26:27]
	v_lshlrev_b32_e32 v20, 16, v16
	v_cvt_pk_bf16_f32 v17, v22, v23
	v_cvt_pk_bf16_f32 v18, v18, v19
	v_cvt_pk_bf16_f32 v19, v24, v25
	global_store_dwordx4 v[28:29], v[16:19], off offset:256 nt
	s_nop 1
	v_and_b32_e32 v16, 0xffff0000, v16
	v_mul_f32_e32 v16, v16, v16
	v_fmac_f32_e32 v16, v20, v20
	v_lshlrev_b32_e32 v20, 16, v17
	v_and_b32_e32 v17, 0xffff0000, v17
	v_mul_f32_e32 v17, v17, v17
	v_add_f32_e32 v16, v50, v16
	v_fmac_f32_e32 v17, v20, v20
	v_add_f32_e32 v16, v16, v17
	v_lshlrev_b32_e32 v17, 16, v18
	v_and_b32_e32 v18, 0xffff0000, v18
	v_mul_f32_e32 v18, v18, v18
	v_fmac_f32_e32 v18, v17, v17
	v_add_f32_e32 v16, v16, v18
	v_and_b32_e32 v18, 0xffff0000, v19
	v_lshlrev_b32_e32 v17, 16, v19
	v_mul_f32_e32 v18, v18, v18
	v_fmac_f32_e32 v18, v17, v17
	v_add_f32_e32 v16, v16, v18
	v_mov_b32_e32 v17, v16
	s_nop 1
	v_permlane16_swap_b32_e32 v17, v16
	s_waitcnt lgkmcnt(0)
	v_add_f32_e32 v16, v16, v17
	v_mov_b32_e32 v17, v16
	s_nop 1
	v_permlane32_swap_b32_e32 v17, v16
	s_and_saveexec_b64 s[6:7], vcc
	s_cbranch_execz .LBB0_433
	s_waitcnt lgkmcnt(0)
	v_add_f32_e32 v18, v16, v17
	v_lshlrev_b64 v[16:17], 6, v[48:49]
	v_lshl_add_u64 v[16:17], s[46:47], 0, v[16:17]
	v_lshl_add_u64 v[16:17], s[58:59], 2, v[16:17]
	s_lshl_b32 s38, s8, 2
	v_lshl_add_u64 v[16:17], v[16:17], 0, s[38:39]
	global_store_dword v[16:17], v18, off
.LBB0_433:
	s_or_b64 exec, exec, s[6:7]
	v_lshlrev_b32_e32 v16, 16, v36
	s_waitcnt lgkmcnt(0)
	v_and_b32_e32 v17, 0xffff0000, v36
	v_lshlrev_b32_e32 v20, 16, v38
	v_and_b32_e32 v21, 0xffff0000, v38
	v_lshlrev_b32_e32 v22, 16, v39
	v_and_b32_e32 v23, 0xffff0000, v39
	v_pk_add_f32 v[12:13], v[12:13], v[16:17]
	v_lshlrev_b32_e32 v18, 16, v37
	v_and_b32_e32 v19, 0xffff0000, v37
	v_pk_add_f32 v[16:17], v[10:11], v[22:23]
	v_pk_add_f32 v[10:11], v[8:9], v[20:21]
	v_cvt_pk_bf16_f32 v8, v12, v13
	v_lshl_add_u64 v[12:13], s[68:69], 0, v[46:47]
	v_pk_add_f32 v[14:15], v[14:15], v[18:19]
	v_lshl_add_u64 v[12:13], v[164:165], 1, v[12:13]
	v_cvt_pk_bf16_f32 v9, v14, v15
	v_cvt_pk_bf16_f32 v10, v10, v11
	v_cvt_pk_bf16_f32 v11, v16, v17
	global_store_dwordx4 v[12:13], v[8:11], off nt
	v_lshlrev_b32_e32 v14, 16, v8
	v_and_b32_e32 v15, 0xffff0000, v34
	v_and_b32_e32 v8, 0xffff0000, v8
	v_mul_f32_e32 v8, v8, v8
	v_fmac_f32_e32 v8, v14, v14
	v_lshlrev_b32_e32 v14, 16, v9
	v_and_b32_e32 v9, 0xffff0000, v9
	v_mul_f32_e32 v9, v9, v9
	v_fmac_f32_e32 v9, v14, v14
	v_add_f32_e32 v8, v8, v9
	v_lshlrev_b32_e32 v9, 16, v10
	v_and_b32_e32 v10, 0xffff0000, v10
	v_mul_f32_e32 v10, v10, v10
	v_fmac_f32_e32 v10, v9, v9
	v_add_f32_e32 v8, v8, v10
	v_and_b32_e32 v10, 0xffff0000, v11
	v_lshlrev_b32_e32 v9, 16, v11
	v_mul_f32_e32 v10, v10, v10
	v_fmac_f32_e32 v10, v9, v9
	v_add_f32_e32 v18, v8, v10
	v_lshlrev_b32_e32 v8, 16, v32
	v_and_b32_e32 v9, 0xffff0000, v32
	v_lshlrev_b32_e32 v14, 16, v34
	v_lshlrev_b32_e32 v10, 16, v33
	v_and_b32_e32 v11, 0xffff0000, v33
	v_lshlrev_b32_e32 v16, 16, v35
	v_and_b32_e32 v17, 0xffff0000, v35
	v_pk_add_f32 v[4:5], v[4:5], v[8:9]
	v_pk_add_f32 v[0:1], v[0:1], v[14:15]
	v_pk_add_f32 v[6:7], v[6:7], v[10:11]
	v_pk_add_f32 v[8:9], v[2:3], v[16:17]
	v_cvt_pk_bf16_f32 v2, v4, v5
	v_cvt_pk_bf16_f32 v3, v6, v7
	v_cvt_pk_bf16_f32 v4, v0, v1
	s_nop 0
	v_and_b32_e32 v1, 0xffff0000, v2
	v_lshlrev_b32_e32 v0, 16, v2
	v_mul_f32_e32 v1, v1, v1
	v_fmac_f32_e32 v1, v0, v0
	v_and_b32_e32 v6, 0xffff0000, v3
	v_add_f32_e32 v0, v18, v1
	v_lshlrev_b32_e32 v1, 16, v3
	v_mul_f32_e32 v6, v6, v6
	v_fmac_f32_e32 v6, v1, v1
	v_add_f32_e32 v0, v0, v6
	v_and_b32_e32 v6, 0xffff0000, v4
	v_lshlrev_b32_e32 v1, 16, v4
	v_mul_f32_e32 v6, v6, v6
	v_fmac_f32_e32 v6, v1, v1
	v_cvt_pk_bf16_f32 v5, v8, v9
	v_add_f32_e32 v0, v0, v6
	v_and_b32_e32 v6, 0xffff0000, v5
	v_lshlrev_b32_e32 v1, 16, v5
	v_mul_f32_e32 v6, v6, v6
	v_fmac_f32_e32 v6, v1, v1
	v_add_f32_e32 v0, v0, v6
	v_mov_b32_e32 v1, v0
	s_nop 1
	v_permlane16_swap_b32_e32 v1, v0
	global_store_dwordx4 v[12:13], v[2:5], off offset:256 nt
	s_waitcnt lgkmcnt(0)
	v_add_f32_e32 v0, v0, v1
	v_mov_b32_e32 v1, v0
	s_nop 1
	v_permlane32_swap_b32_e32 v1, v0
	s_and_saveexec_b64 s[6:7], vcc
	s_cbranch_execz .LBB0_435
	s_waitcnt lgkmcnt(0)
	v_add_f32_e32 v2, v0, v1
	v_lshlrev_b64 v[0:1], 6, v[44:45]
	v_lshl_add_u64 v[0:1], s[46:47], 0, v[0:1]
	v_lshl_add_u64 v[0:1], s[58:59], 2, v[0:1]
	s_lshl_b32 s38, s8, 2
	v_lshl_add_u64 v[0:1], v[0:1], 0, s[38:39]
	global_store_dword v[0:1], v2, off

.LBB0_525:
	s_or_b64 exec, exec, s[8:9]
	v_and_b32_e32 v3, 0xff, v0
	v_readlane_b32 s2, v255, 13
	v_cmp_lt_i32_e32 vcc, -1, v4
	s_nop 0
	v_lshl_add_u32 v1, v3, 2, s2
	v_lshl_add_u32 v1, v2, 10, v1
	s_and_saveexec_b64 s[6:7], vcc
	s_cbranch_execz .LBB0_527
	v_lshl_or_b32 v140, v4, 8, v3
	v_lshlrev_b64 v[4:5], 6, v[140:141]
	v_lshl_add_u64 v[16:17], s[48:49], 0, v[4:5]
	global_load_dwordx4 v[4:7], v[16:17], off
	global_load_dwordx4 v[8:11], v[16:17], off offset:32
	global_load_dwordx4 v[12:15], v[16:17], off offset:16
	s_nop 0
	global_load_dwordx4 v[16:19], v[16:17], off offset:48
	s_waitcnt vmcnt(0) lgkmcnt(0)
	v_mov_b32_e32 v20, v4
	v_mov_b32_e32 v21, v8
	v_mov_b32_e32 v8, v5
	v_mov_b32_e32 v4, v6
	v_mov_b32_e32 v5, v10
	v_mov_b32_e32 v10, v7
	v_mov_b32_e32 v6, v12
	v_mov_b32_e32 v7, v16
	v_mov_b32_e32 v16, v13
	v_mov_b32_e32 v12, v14
	v_mov_b32_e32 v13, v18
	v_mov_b32_e32 v18, v15
	v_pk_add_f32 v[8:9], v[20:21], v[8:9]
	v_pk_add_f32 v[4:5], v[4:5], v[10:11]
	v_pk_add_f32 v[6:7], v[6:7], v[16:17]
	v_pk_add_f32 v[10:11], v[12:13], v[18:19]
	v_pk_add_f32 v[4:5], v[8:9], v[4:5]
	v_pk_add_f32 v[6:7], v[6:7], v[10:11]
	s_nop 0
	v_pk_add_f32 v[4:5], v[4:5], v[6:7]
	s_nop 0
	v_add_f32_e32 v4, v4, v5
	v_fmamk_f32 v4, v4, 0x3a800000, v250
	v_rsq_f32_e32 v4, v4
	ds_write_b32 v1, v4

.LBB0_538:
	v_lshl_or_b32 v140, v4, 8, v3
	v_lshlrev_b64 v[2:3], 6, v[140:141]
	v_lshl_add_u64 v[14:15], s[48:49], 0, v[2:3]
	global_load_dwordx4 v[2:5], v[14:15], off
	global_load_dwordx4 v[6:9], v[14:15], off offset:32
	global_load_dwordx4 v[10:13], v[14:15], off offset:16
	s_nop 0
	global_load_dwordx4 v[14:17], v[14:15], off offset:48
	s_waitcnt vmcnt(0) lgkmcnt(0)
	v_mov_b32_e32 v18, v2
	v_mov_b32_e32 v19, v6
	v_mov_b32_e32 v6, v3
	v_mov_b32_e32 v2, v4
	v_mov_b32_e32 v3, v8
	v_mov_b32_e32 v8, v5
	v_mov_b32_e32 v4, v10
	v_mov_b32_e32 v5, v14
	v_mov_b32_e32 v14, v11
	v_mov_b32_e32 v10, v12
	v_mov_b32_e32 v11, v16
	v_mov_b32_e32 v16, v13
	v_pk_add_f32 v[6:7], v[18:19], v[6:7]
	v_pk_add_f32 v[2:3], v[2:3], v[8:9]
	v_pk_add_f32 v[4:5], v[4:5], v[14:15]
	v_pk_add_f32 v[8:9], v[10:11], v[16:17]
	v_pk_add_f32 v[2:3], v[6:7], v[2:3]
	v_pk_add_f32 v[4:5], v[4:5], v[8:9]
	s_nop 0
	v_pk_add_f32 v[2:3], v[2:3], v[4:5]
	s_nop 0
	v_add_f32_e32 v0, v2, v3
	v_fmamk_f32 v0, v0, 0x3a800000, v250
	v_rsq_f32_e32 v0, v0
	ds_write_b32 v1, v0 offset:2048

.LBB0_555:
	s_mov_b32 s4, -1
	s_getreg_b32 s5, hwreg(HW_REG_HW_ID, 0, 6)
	s_and_b32 s5, s5, 63
	s_lshl_b32 s5, s5, 2
	s_add_i32 s5, s5, 0
	s_add_i32 s5, s5, 0x20200
	v_mov_b32_e32 v140, s5
	ds_read_b32 v140, v140
	v_mbcnt_lo_u32_b32 v142, s4, 0
	v_mbcnt_hi_u32_b32 v142, s4, v142
	v_bfrev_b32_e32 v143, 0.5
	s_mov_b64 s[6:7], -1
	s_waitcnt lgkmcnt(0)
	v_readfirstlane_b32 s4, v140
	s_nop 1
	v_lshl_add_u32 v140, s4, 6, v142
	s_nop 0
	v_readfirstlane_b32 s4, v140
	s_ashr_i32 s5, s4, 2
	s_andn2_b32 s5, s5, 63
	v_bfe_u32 v162, v140, 4, 2
	v_and_or_b32 v169, v140, 15, s5
	s_cmp_gt_u32 s28, 3
	v_lshl_add_u32 v158, s94, 8, v169
	v_lshlrev_b32_e32 v142, 2, v162
	v_lshlrev_b32_e32 v140, 2, v140
	s_cselect_b64 s[56:57], -1, 0
	v_bitop3_b32 v168, v140, 64, v143 bitop3:0x6c
	v_bitop3_b32 v167, v140, s84, v143 bitop3:0x6c
	s_and_b64 vcc, exec, s[56:57]
	v_ashrrev_i32_e32 v159, 31, v158
	v_lshlrev_b32_e32 v140, 2, v142
	s_cbranch_vccz .LBB0_557
	v_lshlrev_b64 v[142:143], 6, v[158:159]
	v_lshl_add_u64 v[142:143], s[48:49], 0, v[142:143]
	v_lshl_add_u64 v[142:143], v[142:143], 0, v[140:141]
	global_load_dwordx4 v[170:173], v[142:143], off
	s_mov_b64 s[6:7], 0
	s_waitcnt vmcnt(0) lgkmcnt(0)
	v_mov_b32_e32 v142, v171
	v_mov_b32_e32 v143, v172
	v_mov_b32_e32 v171, v173
	v_pk_add_f32 v[142:143], v[142:143], v[170:171]
	s_nop 0
	v_add_f32_e32 v142, v142, v143
	v_mov_b32_e32 v143, v142
	s_nop 1
	v_permlane16_swap_b32_e32 v143, v142
	s_waitcnt lgkmcnt(0)
	v_add_f32_e32 v142, v142, v143
	v_mov_b32_e32 v143, v142
	s_nop 1
	v_permlane32_swap_b32_e32 v143, v142
	s_waitcnt lgkmcnt(0)
	v_add_f32_e32 v142, v142, v143
	v_fmamk_f32 v142, v142, 0x3a800000, v250
	v_rsq_f32_e32 v164, v142

.LBB0_561:
	s_or_b64 exec, exec, s[6:7]
	v_or_b32_e32 v112, 16, v158
	s_mov_b64 s[6:7], -1
	s_and_b64 vcc, exec, s[56:57]
	s_waitcnt lgkmcnt(0)
	v_ashrrev_i32_e32 v113, 31, v112
	s_cbranch_vccz .LBB0_563
	v_lshlrev_b64 v[114:115], 6, v[112:113]
	v_lshl_add_u64 v[114:115], s[48:49], 0, v[114:115]
	v_lshl_add_u64 v[114:115], v[114:115], 0, v[140:141]
	global_load_dwordx4 v[114:117], v[114:115], off
	s_mov_b64 s[6:7], 0
	s_waitcnt vmcnt(0) lgkmcnt(0)
	v_mov_b32_e32 v118, v115
	v_mov_b32_e32 v119, v116
	v_mov_b32_e32 v115, v117
	v_pk_add_f32 v[114:115], v[118:119], v[114:115]
	s_nop 0
	v_add_f32_e32 v114, v114, v115
	v_mov_b32_e32 v115, v114
	s_nop 1
	v_permlane16_swap_b32_e32 v115, v114
	s_waitcnt lgkmcnt(0)
	v_add_f32_e32 v114, v114, v115
	v_mov_b32_e32 v115, v114
	s_nop 1
	v_permlane32_swap_b32_e32 v115, v114
	s_waitcnt lgkmcnt(0)
	v_add_f32_e32 v114, v114, v115
	v_fmamk_f32 v114, v114, 0x3a800000, v250
	v_rsq_f32_e32 v116, v114

.LBB0_567:
	s_or_b64 exec, exec, s[6:7]
	v_or_b32_e32 v96, 32, v158
	s_mov_b64 s[6:7], -1
	s_and_b64 vcc, exec, s[56:57]
	s_waitcnt lgkmcnt(0)
	v_ashrrev_i32_e32 v97, 31, v96
	s_cbranch_vccz .LBB0_569
	v_lshlrev_b64 v[98:99], 6, v[96:97]
	v_lshl_add_u64 v[98:99], s[48:49], 0, v[98:99]
	v_lshl_add_u64 v[98:99], v[98:99], 0, v[140:141]
	global_load_dwordx4 v[98:101], v[98:99], off
	s_mov_b64 s[6:7], 0
	s_waitcnt vmcnt(0) lgkmcnt(0)
	v_mov_b32_e32 v102, v99
	v_mov_b32_e32 v103, v100
	v_mov_b32_e32 v99, v101
	v_pk_add_f32 v[98:99], v[102:103], v[98:99]
	s_nop 0
	v_add_f32_e32 v98, v98, v99
	v_mov_b32_e32 v99, v98
	s_nop 1
	v_permlane16_swap_b32_e32 v99, v98
	s_waitcnt lgkmcnt(0)
	v_add_f32_e32 v98, v98, v99
	v_mov_b32_e32 v99, v98
	s_nop 1
	v_permlane32_swap_b32_e32 v99, v98
	s_waitcnt lgkmcnt(0)
	v_add_f32_e32 v98, v98, v99
	v_fmamk_f32 v98, v98, 0x3a800000, v250
	v_rsq_f32_e32 v100, v98

.LBB0_573:
	s_or_b64 exec, exec, s[6:7]
	v_or_b32_e32 v80, 48, v158
	s_mov_b64 s[6:7], -1
	s_and_b64 vcc, exec, s[56:57]
	s_waitcnt lgkmcnt(0)
	v_ashrrev_i32_e32 v81, 31, v80
	s_cbranch_vccz .LBB0_575
	v_lshlrev_b64 v[82:83], 6, v[80:81]
	v_lshl_add_u64 v[82:83], s[48:49], 0, v[82:83]
	v_lshl_add_u64 v[82:83], v[82:83], 0, v[140:141]
	global_load_dwordx4 v[82:85], v[82:83], off
	s_mov_b64 s[6:7], 0
	s_waitcnt vmcnt(0) lgkmcnt(0)
	v_mov_b32_e32 v86, v83
	v_mov_b32_e32 v87, v84
	v_mov_b32_e32 v83, v85
	v_pk_add_f32 v[82:83], v[86:87], v[82:83]
	s_nop 0
	v_add_f32_e32 v82, v82, v83
	v_mov_b32_e32 v83, v82
	s_nop 1
	v_permlane16_swap_b32_e32 v83, v82
	s_waitcnt lgkmcnt(0)
	v_add_f32_e32 v82, v82, v83
	v_mov_b32_e32 v83, v82
	s_nop 1
	v_permlane32_swap_b32_e32 v83, v82
	s_waitcnt lgkmcnt(0)
	v_add_f32_e32 v82, v82, v83
	v_fmamk_f32 v82, v82, 0x3a800000, v250
	v_rsq_f32_e32 v84, v82

.LBB0_579:
	s_or_b64 exec, exec, s[6:7]
	v_add_u32_e32 v64, 0x80, v158
	s_mov_b64 s[6:7], -1
	s_and_b64 vcc, exec, s[56:57]
	s_waitcnt lgkmcnt(0)
	v_ashrrev_i32_e32 v65, 31, v64
	s_cbranch_vccz .LBB0_581
	v_lshlrev_b64 v[66:67], 6, v[64:65]
	v_lshl_add_u64 v[66:67], s[48:49], 0, v[66:67]
	v_lshl_add_u64 v[66:67], v[66:67], 0, v[140:141]
	global_load_dwordx4 v[66:69], v[66:67], off
	s_mov_b64 s[6:7], 0
	s_waitcnt vmcnt(0) lgkmcnt(0)
	v_mov_b32_e32 v70, v67
	v_mov_b32_e32 v71, v68
	v_mov_b32_e32 v67, v69
	v_pk_add_f32 v[66:67], v[70:71], v[66:67]
	s_nop 0
	v_add_f32_e32 v66, v66, v67
	v_mov_b32_e32 v67, v66
	s_nop 1
	v_permlane16_swap_b32_e32 v67, v66
	s_waitcnt lgkmcnt(0)
	v_add_f32_e32 v66, v66, v67
	v_mov_b32_e32 v67, v66
	s_nop 1
	v_permlane32_swap_b32_e32 v67, v66
	s_waitcnt lgkmcnt(0)
	v_add_f32_e32 v66, v66, v67
	v_fmamk_f32 v66, v66, 0x3a800000, v250
	v_rsq_f32_e32 v68, v66

.LBB0_585:
	s_or_b64 exec, exec, s[6:7]
	v_add_u32_e32 v48, 0x90, v158
	s_mov_b64 s[6:7], -1
	s_and_b64 vcc, exec, s[56:57]
	s_waitcnt lgkmcnt(0)
	v_ashrrev_i32_e32 v49, 31, v48
	s_cbranch_vccz .LBB0_587
	v_lshlrev_b64 v[50:51], 6, v[48:49]
	v_lshl_add_u64 v[50:51], s[48:49], 0, v[50:51]
	v_lshl_add_u64 v[50:51], v[50:51], 0, v[140:141]
	global_load_dwordx4 v[50:53], v[50:51], off
	s_mov_b64 s[6:7], 0
	s_waitcnt vmcnt(0) lgkmcnt(0)
	v_mov_b32_e32 v54, v51
	v_mov_b32_e32 v55, v52
	v_mov_b32_e32 v51, v53
	v_pk_add_f32 v[50:51], v[54:55], v[50:51]
	s_nop 0
	v_add_f32_e32 v50, v50, v51
	v_mov_b32_e32 v51, v50
	s_nop 1
	v_permlane16_swap_b32_e32 v51, v50
	s_waitcnt lgkmcnt(0)
	v_add_f32_e32 v50, v50, v51
	v_mov_b32_e32 v51, v50
	s_nop 1
	v_permlane32_swap_b32_e32 v51, v50
	s_waitcnt lgkmcnt(0)
	v_add_f32_e32 v50, v50, v51
	v_fmamk_f32 v50, v50, 0x3a800000, v250
	v_rsq_f32_e32 v52, v50

.LBB0_591:
	s_or_b64 exec, exec, s[6:7]
	v_add_u32_e32 v32, 0xa0, v158
	s_mov_b64 s[6:7], -1
	s_and_b64 vcc, exec, s[56:57]
	s_waitcnt lgkmcnt(0)
	v_ashrrev_i32_e32 v33, 31, v32
	s_cbranch_vccz .LBB0_593
	v_lshlrev_b64 v[34:35], 6, v[32:33]
	v_lshl_add_u64 v[34:35], s[48:49], 0, v[34:35]
	v_lshl_add_u64 v[34:35], v[34:35], 0, v[140:141]
	global_load_dwordx4 v[34:37], v[34:35], off
	s_mov_b64 s[6:7], 0
	s_waitcnt vmcnt(0) lgkmcnt(0)
	v_mov_b32_e32 v38, v35
	v_mov_b32_e32 v39, v36
	v_mov_b32_e32 v35, v37
	v_pk_add_f32 v[34:35], v[38:39], v[34:35]
	s_nop 0
	v_add_f32_e32 v34, v34, v35
	v_mov_b32_e32 v35, v34
	s_nop 1
	v_permlane16_swap_b32_e32 v35, v34
	s_waitcnt lgkmcnt(0)
	v_add_f32_e32 v34, v34, v35
	v_mov_b32_e32 v35, v34
	s_nop 1
	v_permlane32_swap_b32_e32 v35, v34
	s_waitcnt lgkmcnt(0)
	v_add_f32_e32 v34, v34, v35
	v_fmamk_f32 v34, v34, 0x3a800000, v250
	v_rsq_f32_e32 v36, v34

.LBB0_597:
	s_or_b64 exec, exec, s[6:7]
	v_add_u32_e32 v16, 0xb0, v158
	s_mov_b64 s[6:7], -1
	s_and_b64 vcc, exec, s[56:57]
	s_waitcnt lgkmcnt(0)
	v_ashrrev_i32_e32 v17, 31, v16
	s_cbranch_vccz .LBB0_599
	v_lshlrev_b64 v[18:19], 6, v[16:17]
	v_lshl_add_u64 v[18:19], s[48:49], 0, v[18:19]
	v_lshl_add_u64 v[18:19], v[18:19], 0, v[140:141]
	global_load_dwordx4 v[18:21], v[18:19], off
	s_mov_b64 s[6:7], 0
	s_waitcnt vmcnt(0) lgkmcnt(0)
	v_mov_b32_e32 v22, v19
	v_mov_b32_e32 v23, v20
	v_mov_b32_e32 v19, v21
	v_pk_add_f32 v[18:19], v[22:23], v[18:19]
	s_nop 0
	v_add_f32_e32 v18, v18, v19
	v_mov_b32_e32 v19, v18
	s_nop 1
	v_permlane16_swap_b32_e32 v19, v18
	s_waitcnt lgkmcnt(0)
	v_add_f32_e32 v18, v18, v19
	v_mov_b32_e32 v19, v18
	s_nop 1
	v_permlane32_swap_b32_e32 v19, v18
	s_waitcnt lgkmcnt(0)
	v_add_f32_e32 v18, v18, v19
	v_fmamk_f32 v18, v18, 0x3a800000, v250
	v_rsq_f32_e32 v20, v18

.LBB0_613:
	s_lshl_b32 s6, s26, 6
	s_and_b32 s27, s26, 63
	s_cmp_eq_u32 s27, 0
	s_cselect_b64 s[12:13], -1, 0
	s_cmp_lg_u32 s27, 0
	s_cselect_b64 s[8:9], -1, 0
	s_waitcnt vmcnt(0)
	s_barrier
	s_and_saveexec_b64 s[10:11], s[42:43]
	s_cbranch_execz .LBB0_617
	s_and_b64 s[4:5], s[12:13], s[44:45]
	s_xor_b64 s[4:5], s[4:5], -1
	v_mov_b32_e32 v4, 0
	s_and_saveexec_b64 s[12:13], s[4:5]
	s_cbranch_execz .LBB0_616
	v_add_u32_e32 v4, s6, v72
	v_ashrrev_i32_e32 v5, 31, v4
	v_lshlrev_b64 v[4:5], 6, v[4:5]
	v_lshl_add_u64 v[16:17], s[48:49], 0, v[4:5]
	global_load_dwordx4 v[4:7], v[16:17], off
	global_load_dwordx4 v[8:11], v[16:17], off offset:32
	global_load_dwordx4 v[12:15], v[16:17], off offset:16
	s_nop 0
	global_load_dwordx4 v[16:19], v[16:17], off offset:48
	s_waitcnt vmcnt(0) lgkmcnt(0)
	v_mov_b32_e32 v20, v4
	v_mov_b32_e32 v21, v8
	v_mov_b32_e32 v8, v5
	v_mov_b32_e32 v4, v6
	v_mov_b32_e32 v5, v10
	v_mov_b32_e32 v10, v7
	v_mov_b32_e32 v6, v12
	v_mov_b32_e32 v7, v16
	v_mov_b32_e32 v16, v13
	v_mov_b32_e32 v12, v14
	v_mov_b32_e32 v13, v18
	v_mov_b32_e32 v18, v15
	v_pk_add_f32 v[8:9], v[20:21], v[8:9]
	v_pk_add_f32 v[4:5], v[4:5], v[10:11]
	v_pk_add_f32 v[6:7], v[6:7], v[16:17]
	v_pk_add_f32 v[10:11], v[12:13], v[18:19]
	v_pk_add_f32 v[4:5], v[8:9], v[4:5]
	v_pk_add_f32 v[6:7], v[6:7], v[10:11]
	s_nop 0
	v_pk_add_f32 v[4:5], v[4:5], v[6:7]
	s_nop 0
	v_add_f32_e32 v4, v4, v5
	v_fmamk_f32 v4, v4, 0x3a800000, v250
	v_mul_f32_e32 v5, 0x4f800000, v4
	v_cmp_gt_f32_e32 vcc, s94, v4
	s_nop 1
	v_cndmask_b32_e32 v4, v4, v5, vcc
	v_sqrt_f32_e32 v5, v4
	s_nop 0
	v_add_u32_e32 v6, -1, v5
	v_add_u32_e32 v7, 1, v5
	v_fma_f32 v8, -v6, v5, v4
	v_fma_f32 v9, -v7, v5, v4
	v_cmp_ge_f32_e64 s[46:47], 0, v8
	s_nop 1
	v_cndmask_b32_e64 v5, v5, v6, s[46:47]
	v_cmp_lt_f32_e64 s[46:47], 0, v9
	s_nop 1
	v_cndmask_b32_e64 v5, v5, v7, s[46:47]
	v_mul_f32_e32 v6, 0x37800000, v5
	v_cndmask_b32_e32 v5, v5, v6, vcc
	v_cmp_class_f32_e32 vcc, v4, v251
	s_nop 1
	v_cndmask_b32_e32 v4, v5, v4, vcc
	v_div_scale_f32 v5, s[4:5], v4, v4, 1.0
	v_rcp_f32_e32 v6, v5
	v_div_scale_f32 v7, vcc, 1.0, v4, 1.0
	v_fma_f32 v8, -v5, v6, 1.0
	v_fmac_f32_e32 v6, v8, v6
	v_mul_f32_e32 v8, v7, v6
	v_fma_f32 v9, -v5, v8, v7
	v_fmac_f32_e32 v8, v9, v6
	v_fma_f32 v5, -v5, v8, v7
	v_div_fmas_f32 v5, v5, v6, v8
	v_div_fixup_f32 v4, v5, v4, 1.0

.LBB0_641:
	s_lshl_b32 s8, s28, 6
	s_and_b32 s29, s28, 63
	s_cmp_eq_u32 s29, 0
	s_cselect_b64 s[14:15], -1, 0
	s_cmp_lg_u32 s29, 0
	s_cselect_b64 s[10:11], -1, 0
	s_waitcnt vmcnt(0)
	s_barrier
	s_and_saveexec_b64 s[12:13], s[40:41]
	s_cbranch_execz .LBB0_645
	s_and_b64 s[4:5], s[14:15], s[42:43]
	s_xor_b64 s[4:5], s[4:5], -1
	v_mov_b32_e32 v0, 0
	s_and_saveexec_b64 s[14:15], s[4:5]
	s_cbranch_execz .LBB0_644
	v_add_u32_e32 v0, s8, v72
	v_ashrrev_i32_e32 v1, 31, v0
	v_lshlrev_b64 v[0:1], 6, v[0:1]
	v_lshl_add_u64 v[16:17], s[48:49], 0, v[0:1]
	global_load_dwordx4 v[0:3], v[16:17], off
	global_load_dwordx4 v[4:7], v[16:17], off offset:32
	global_load_dwordx4 v[12:15], v[16:17], off offset:16
	s_nop 0
	global_load_dwordx4 v[16:19], v[16:17], off offset:48
	s_waitcnt vmcnt(0) lgkmcnt(0)
	v_mov_b32_e32 v20, v0
	v_mov_b32_e32 v21, v4
	v_mov_b32_e32 v4, v1
	v_mov_b32_e32 v0, v2
	v_mov_b32_e32 v1, v6
	v_mov_b32_e32 v6, v3
	v_mov_b32_e32 v2, v12
	v_mov_b32_e32 v3, v16
	v_mov_b32_e32 v16, v13
	v_mov_b32_e32 v12, v14
	v_mov_b32_e32 v13, v18
	v_mov_b32_e32 v18, v15
	v_pk_add_f32 v[4:5], v[20:21], v[4:5]
	v_pk_add_f32 v[0:1], v[0:1], v[6:7]
	v_pk_add_f32 v[2:3], v[2:3], v[16:17]
	v_pk_add_f32 v[6:7], v[12:13], v[18:19]
	v_pk_add_f32 v[0:1], v[4:5], v[0:1]
	v_pk_add_f32 v[2:3], v[2:3], v[6:7]
	s_nop 0
	v_pk_add_f32 v[0:1], v[0:1], v[2:3]
	s_nop 0
	v_add_f32_e32 v0, v0, v1
	v_fmamk_f32 v0, v0, 0x3a800000, v250
	v_mul_f32_e32 v1, 0x4f800000, v0
	v_cmp_gt_f32_e32 vcc, s94, v0
	s_nop 1
	v_cndmask_b32_e32 v0, v0, v1, vcc
	v_sqrt_f32_e32 v1, v0
	s_nop 0
	v_add_u32_e32 v2, -1, v1
	v_add_u32_e32 v3, 1, v1
	v_fma_f32 v4, -v2, v1, v0
	v_fma_f32 v5, -v3, v1, v0
	v_cmp_ge_f32_e64 s[44:45], 0, v4
	s_nop 1
	v_cndmask_b32_e64 v1, v1, v2, s[44:45]
	v_cmp_lt_f32_e64 s[44:45], 0, v5
	s_nop 1
	v_cndmask_b32_e64 v1, v1, v3, s[44:45]
	v_mul_f32_e32 v2, 0x37800000, v1
	v_cndmask_b32_e32 v1, v1, v2, vcc
	v_cmp_class_f32_e32 vcc, v0, v251
	s_nop 1
	v_cndmask_b32_e32 v0, v1, v0, vcc
	v_div_scale_f32 v1, s[4:5], v0, v0, 1.0
	v_rcp_f32_e32 v2, v1
	v_div_scale_f32 v3, vcc, 1.0, v0, 1.0
	v_fma_f32 v4, -v1, v2, 1.0
	v_fmac_f32_e32 v2, v4, v2
	v_mul_f32_e32 v4, v3, v2
	v_fma_f32 v5, -v1, v4, v3
	v_fmac_f32_e32 v4, v5, v2
	v_fma_f32 v1, -v1, v4, v3
	v_div_fmas_f32 v1, v1, v2, v4
	v_div_fixup_f32 v0, v1, v0, 1.0
